# batched loads in rwkv invn loop, lora bias preload, pipelined ada matvec loads, fft input loads unrolled
# speedup vs baseline: 1.0394x; 1.0394x over previous
; template <int KT>
; __device__ __forceinline__ void scan_block(const Ctx& C, const PV& P, int layer, int sq, int h, int d, int row0, unsigned char* smem) {
;     ...
;     auto prefetch = [&](int c0) {
; #pragma unroll
;         for (int j = 0; j < 2; ++j) {
;             const int i = (tid >> 6) + 8 * j, tstep = c0 + i, t = d == 0 ? tstep : S - 1 - tstep, lt = lt0 + t;
;             const int tm = t > 0 ? lt - 1 : lt, tp = t < S - 1 ? lt + 1 : lt;
;             pr_[j][0] = raw[(size_t)tm * 1920 + c]; pr_[j][1] = raw[(size_t)lt * 1920 + c]; pr_[j][2] = raw[(size_t)tp * 1920 + c];
;             pk_[j][0] = raw[(size_t)tm * 1920 + 512 + c]; pk_[j][1] = raw[(size_t)lt * 1920 + 512 + c]; pk_[j][2] = raw[(size_t)tp * 1920 + 512 + c];
;             pa_[j] = aact[(size_t)lt * 512 + c]; pw_[j] = wdec[(size_t)lt * 512 + c]; pn_[j] = invn[(size_t)lt * 8 + h];
;         }
; #pragma unroll
;         for (int j = 0; j < NV; ++j) {
;             const int i = (ROWS == 32) ? (tid >> 5) : ((tid >> 6) + 8 * j), tstep = c0 + i, t = d == 0 ? tstep : S - 1 - tstep, lt = lt0 + t;
;             const int tm = t > 0 ? lt - 1 : lt, tp = t < S - 1 ? lt + 1 : lt;
;             pv_[j][0] = raw[(size_t)tm * 1920 + vcol]; pv_[j][1] = raw[(size_t)lt * 1920 + vcol]; pv_[j][2] = raw[(size_t)tp * 1920 + vcol];
;         }
;     };
.LBB0_2130:
	s_barrier
	s_mov_b64 s[12:13], -1
	s_and_b64 vcc, exec, s[2:3]
	v_ashrrev_i32_e32 v145, 31, v144
	s_cbranch_vccnz .LBB0_543
	s_branch .LBB0_554
.LBB0_533:
	s_cmpk_lg_i32 s5, 0xff0
	s_cselect_b64 s[20:21], -1, 0
	s_cmpk_eq_i32 s5, 0xff0
	v_subrev_u32_e32 v101, 24, v71
	v_add_u32_e32 v99, s5, v65
	v_add_u32_e32 v100, -16, v71
	s_cbranch_scc1 .LBB0_535
	v_add_u32_e32 v24, s5, v65
	v_add_u32_e32 v8, 16, v24
	v_add_u32_e32 v9, -16, v71
	v_cndmask_b32_e64 v9, v9, v8, s[40:41]
	v_add_u32_e32 v8, s4, v9
	v_cmp_lt_i32_e32 vcc, 0, v9
	v_mov_b32_e32 v25, s4
	v_mov_b64_e32 v[10:11], s[14:15]
	v_subbrev_co_u32_e32 v12, vcc, 0, v8, vcc
	v_cmp_gt_i32_e32 vcc, s78, v9
	v_mad_i64_i32 v[12:13], s[6:7], v12, s77, v[10:11]
	s_nop 0
	v_addc_co_u32_e32 v20, vcc, v9, v25, vcc
	v_mad_i64_i32 v[16:17], s[6:7], v8, s77, v[10:11]
	v_mad_i64_i32 v[20:21], s[6:7], v20, s77, v[10:11]
	v_lshl_add_u64 v[14:15], v[12:13], 0, v[132:133]
	v_ashrrev_i32_e32 v9, 31, v8
	v_lshl_add_u64 v[18:19], v[16:17], 0, v[132:133]
	v_lshl_add_u64 v[22:23], v[20:21], 0, v[132:133]
	global_load_ushort v66, v[14:15], off
	global_load_ushort v70, v[18:19], off
	global_load_ushort v67, v[22:23], off
	global_load_ushort v68, v[14:15], off offset:1024
	global_load_ushort v72, v[18:19], off offset:1024
	global_load_ushort v69, v[22:23], off offset:1024
	v_lshlrev_b64 v[14:15], 10, v[8:9]
	v_lshlrev_b64 v[8:9], 5, v[8:9]
	v_lshl_add_u64 v[18:19], v[40:41], 0, v[14:15]
	v_lshl_add_u64 v[14:15], v[42:43], 0, v[14:15]
	v_lshl_add_u64 v[8:9], s[12:13], 0, v[8:9]
	global_load_ushort v73, v[18:19], off
	global_load_ushort v74, v[14:15], off
	global_load_dword v75, v[8:9], off
	v_add_u32_e32 v8, 24, v24
	v_cndmask_b32_e64 v9, v101, v8, s[40:41]
	v_add_u32_e32 v8, s4, v9
	v_cmp_lt_i32_e32 vcc, 0, v9
	v_mad_i64_i32 v[22:23], s[6:7], v8, s77, v[10:11]
	s_nop 0
	v_subbrev_co_u32_e32 v14, vcc, 0, v8, vcc
	v_cmp_gt_i32_e32 vcc, s78, v9
	v_mad_i64_i32 v[14:15], s[6:7], v14, s77, v[10:11]
	s_nop 0
	v_addc_co_u32_e32 v26, vcc, v9, v25, vcc
	v_mad_i64_i32 v[10:11], s[6:7], v26, s77, v[10:11]
	v_lshl_add_u64 v[18:19], v[14:15], 0, v[132:133]
	v_ashrrev_i32_e32 v9, 31, v8
	v_lshl_add_u64 v[24:25], v[22:23], 0, v[132:133]
	v_lshl_add_u64 v[26:27], v[10:11], 0, v[132:133]
	global_load_ushort v76, v[18:19], off
	global_load_ushort v83, v[24:25], off
	global_load_ushort v77, v[26:27], off
	global_load_ushort v78, v[18:19], off offset:1024
	global_load_ushort v84, v[24:25], off offset:1024
	global_load_ushort v79, v[26:27], off offset:1024
	v_lshlrev_b64 v[18:19], 10, v[8:9]
	v_lshlrev_b64 v[8:9], 5, v[8:9]
	v_lshl_add_u64 v[24:25], v[40:41], 0, v[18:19]
	v_lshl_add_u64 v[18:19], v[42:43], 0, v[18:19]
	v_lshl_add_u64 v[8:9], s[12:13], 0, v[8:9]
	s_waitcnt vmcnt(17)
	v_mov_b32_e32 v47, v133
	global_load_ushort v87, v[18:19], off
	global_load_dword v88, v[8:9], off
	v_lshl_add_u64 v[8:9], v[12:13], 0, v[46:47]
	global_load_ushort v89, v[24:25], off
	global_load_ushort v94, v[8:9], off
	v_lshl_add_u64 v[8:9], v[16:17], 0, v[46:47]
	global_load_ushort v96, v[8:9], off
	v_lshl_add_u64 v[8:9], v[20:21], 0, v[46:47]
	global_load_ushort v95, v[8:9], off
	v_lshl_add_u64 v[8:9], v[14:15], 0, v[46:47]
	global_load_ushort v97, v[8:9], off
	v_lshl_add_u64 v[8:9], v[22:23], 0, v[46:47]
	global_load_ushort v98, v[8:9], off
	v_lshl_add_u64 v[8:9], v[10:11], 0, v[46:47]
	global_load_ushort v47, v[8:9], off

; __device__ __forceinline__ void fft_items(const Ctx& C, const PV& P, unsigned char* smem) {
;     ...
;         __syncthreads();
;         for (int s = tid; s < S; s += NT) { const f16x2 v = z[s]; sm[__brev((unsigned)s) >> (32 - lg)] = make_float2((float)v[0], (float)v[1]); }
;         __syncthreads();
.LBB0_604:
	v_lshl_add_u64 v[36:37], v[2:3], 0, s[30:31]
	v_lshl_add_u64 v[38:39], v[36:37], 0, s[30:31]
	v_lshl_add_u64 v[40:41], v[38:39], 0, s[30:31]
	v_lshl_add_u64 v[80:81], v[40:41], 0, s[30:31]
	v_lshl_add_u64 v[82:83], v[80:81], 0, s[30:31]
	v_lshl_add_u64 v[84:85], v[82:83], 0, s[30:31]
	v_lshl_add_u64 v[86:87], v[84:85], 0, s[30:31]
	global_load_dword v42, v[2:3], off
	global_load_dword v43, v[36:37], off
	global_load_dword v44, v[38:39], off
	global_load_dword v45, v[40:41], off
	global_load_dword v46, v[80:81], off
	global_load_dword v47, v[82:83], off
	global_load_dword v48, v[84:85], off
	global_load_dword v49, v[86:87], off
	v_bfrev_b32_e32 v56, v6
	v_lshrrev_b32_e32 v56, s13, v56
	v_lshl_add_u32 v56, v56, 3, 0
	v_add_u32_e32 v57, 0x200, v6
	v_bfrev_b32_e32 v57, v57
	v_lshrrev_b32_e32 v57, s13, v57
	v_lshl_add_u32 v57, v57, 3, 0
	v_add_u32_e32 v58, 0x400, v6
	v_bfrev_b32_e32 v58, v58
	v_lshrrev_b32_e32 v58, s13, v58
	v_lshl_add_u32 v58, v58, 3, 0
	v_add_u32_e32 v59, 0x600, v6
	v_bfrev_b32_e32 v59, v59
	v_lshrrev_b32_e32 v59, s13, v59
	v_lshl_add_u32 v59, v59, 3, 0
	v_add_u32_e32 v60, 0x800, v6
	v_bfrev_b32_e32 v60, v60
	v_lshrrev_b32_e32 v60, s13, v60
	v_lshl_add_u32 v60, v60, 3, 0
	v_add_u32_e32 v61, 0xa00, v6
	v_bfrev_b32_e32 v61, v61
	v_lshrrev_b32_e32 v61, s13, v61
	v_lshl_add_u32 v61, v61, 3, 0
	v_add_u32_e32 v62, 0xc00, v6
	v_bfrev_b32_e32 v62, v62
	v_lshrrev_b32_e32 v62, s13, v62
	v_lshl_add_u32 v62, v62, 3, 0
	v_add_u32_e32 v63, 0xe00, v6
	v_bfrev_b32_e32 v63, v63
	v_lshrrev_b32_e32 v63, s13, v63
	v_lshl_add_u32 v63, v63, 3, 0
	s_waitcnt vmcnt(7)
	v_cvt_f32_f16_sdwa v65, v42 dst_sel:DWORD dst_unused:UNUSED_PAD src0_sel:WORD_1
	v_cvt_f32_f16_e32 v64, v42
	ds_write_b64 v56, v[64:65]
	s_waitcnt vmcnt(6)
	v_cvt_f32_f16_sdwa v67, v43 dst_sel:DWORD dst_unused:UNUSED_PAD src0_sel:WORD_1
	v_cvt_f32_f16_e32 v66, v43
	ds_write_b64 v57, v[66:67]
	s_waitcnt vmcnt(5)
	v_cvt_f32_f16_sdwa v69, v44 dst_sel:DWORD dst_unused:UNUSED_PAD src0_sel:WORD_1
	v_cvt_f32_f16_e32 v68, v44
	ds_write_b64 v58, v[68:69]
	s_waitcnt vmcnt(4)
	v_cvt_f32_f16_sdwa v71, v45 dst_sel:DWORD dst_unused:UNUSED_PAD src0_sel:WORD_1
	v_cvt_f32_f16_e32 v70, v45
	ds_write_b64 v59, v[70:71]
	s_waitcnt vmcnt(3)
	v_cvt_f32_f16_sdwa v73, v46 dst_sel:DWORD dst_unused:UNUSED_PAD src0_sel:WORD_1
	v_cvt_f32_f16_e32 v72, v46
	ds_write_b64 v60, v[72:73]
	s_waitcnt vmcnt(2)
	v_cvt_f32_f16_sdwa v75, v47 dst_sel:DWORD dst_unused:UNUSED_PAD src0_sel:WORD_1
	v_cvt_f32_f16_e32 v74, v47
	ds_write_b64 v61, v[74:75]
	s_waitcnt vmcnt(1)
	v_cvt_f32_f16_sdwa v77, v48 dst_sel:DWORD dst_unused:UNUSED_PAD src0_sel:WORD_1
	v_cvt_f32_f16_e32 v76, v48
	ds_write_b64 v62, v[76:77]
	s_waitcnt vmcnt(0)
	v_cvt_f32_f16_sdwa v79, v49 dst_sel:DWORD dst_unused:UNUSED_PAD src0_sel:WORD_1
	v_cvt_f32_f16_e32 v78, v49
	ds_write_b64 v63, v[78:79]
	v_add_u32_e32 v6, 0x1000, v6
	v_cmp_le_i32_e64 s[40:41], s7, v6
	v_lshl_add_u64 v[2:3], v[86:87], 0, s[30:31]
	s_or_b64 s[34:35], s[40:41], s[34:35]
	s_andn2_b64 exec, exec, s[34:35]
	s_cbranch_execnz .LBB0_604

; __device__ __forceinline__ float sigmoidf_(float x) { return __builtin_amdgcn_rcpf(1.0f + __expf(-x)); }
; __device__ __forceinline__ void lora_phase(const Ctx& C, const PV& P, int layer, unsigned char* smem) {
;     ...
;         const bf16_t* Bt; int K, acol; const float* bias = nullptr; f16* dst;
;         if (which < 2) { Bt = W + OW_W2T + (size_t)which * 512 * 64; K = 64; acol = which * 64; bias = P.inp(14) + (size_t)(layer * 2 + which) * 512; dst = wa + (size_t)which * SZ512; }
;         else if (which < 4) { const int d = which - 2; Bt = W + OW_A2T + (size_t)d * 512 * 64; K = 64; acol = 128 + d * 64; bias = P.inp(16) + (size_t)(layer * 2 + d) * 512; dst = wa + (size_t)which * SZ512; }
;         else { Bt = W + OW_G2T; K = 128; acol = 256; dst = gbuf; }
;         f32x4 acc[4][4];
;         gemm_core<4, true>(C, acc, lin + (size_t)tm * 128 * 384 + acol, 384, Bt + (size_t)tn * 128 * K, K, K, smem);
; #pragma unroll
;         for (int i = 0; i < 4; ++i) {
;             const int lt = tm * 128 + wm * 64 + i * 16 + fr;
; #pragma unroll
;             for (int jn = 0; jn < 4; ++jn) {
;                 const int n = tn * 128 + wn * 64 + jn * 16 + fq * 4;
;                 typedef f16 f16x4 __attribute__((ext_vector_type(4)));
;                 f16x4 h;
; #pragma unroll
;                 for (int r = 0; r < 4; ++r) {
;                     float v = acc[i][jn][r];
;                     if (which < 2) {
;                         const float z = bias[n + r] + v;
;                         v = __expf(-0.6065306597126334f * sigmoidf_(z));
;                     } else if (which < 4) { v = sigmoidf_(bias[n + r] + v); }
;                     h[r] = (f16)v;
;                 }
;                 *(f16x4*)(dst + (size_t)lt * 512 + n) = h;
.LBB0_643:
	s_or_b64 exec, exec, s[2:3]
	s_movk_i32 s2, 0x1400
	v_cmp_gt_u32_e32 vcc, s2, v128
	s_movk_i32 s2, 0x13ff
	s_waitcnt vmcnt(7)
	v_or_b32_e32 v64, v121, v129
	v_cmp_lt_u32_e64 s[42:43], s2, v128
	s_and_saveexec_b64 s[20:21], vcc
	v_lshlrev_b32_e32 v132, 2, v64
	v_lshl_add_u64 v[162:163], v[104:105], 0, v[132:133]
	global_load_dwordx4 v[164:167], v[162:163], off
	global_load_dwordx4 v[168:171], v[162:163], off offset:64
	global_load_dwordx4 v[172:175], v[162:163], off offset:128
	global_load_dwordx4 v[176:179], v[162:163], off offset:192
	s_waitcnt vmcnt(0)
	s_or_b64 exec, exec, s[20:21]
	s_and_saveexec_b64 s[2:3], s[40:41]
	s_xor_b64 s[2:3], exec, s[2:3]
	s_cbranch_execz .LBB0_647
	v_mov_b32_e32 v65, v60
	s_and_saveexec_b64 s[20:21], vcc
	s_cbranch_execz .LBB0_646
	v_lshlrev_b32_e32 v132, 2, v64
	v_lshl_add_u64 v[66:67], v[104:105], 0, v[132:133]
	v_mov_b32_e32 v65, v164
	v_add_f32_e32 v65, v60, v65
	v_mul_f32_e32 v65, 0xbfb8aa3b, v65
	v_exp_f32_e32 v65, v65
	s_nop 0
	v_add_f32_e32 v65, 1.0, v65
	v_rcp_f32_e32 v65, v65

; __device__ __forceinline__ float sigmoidf_(float x) { return __builtin_amdgcn_rcpf(1.0f + __expf(-x)); }
; __device__ __forceinline__ void lora_phase(const Ctx& C, const PV& P, int layer, unsigned char* smem) {
;     ...
;                 for (int r = 0; r < 4; ++r) {
;                     float v = acc[i][jn][r];
;                     if (which < 2) {
;                         const float z = bias[n + r] + v;
;                         v = __expf(-0.6065306597126334f * sigmoidf_(z));
;                     } else if (which < 4) { v = sigmoidf_(bias[n + r] + v); }
;                     h[r] = (f16)v;
;                 }
;                 *(f16x4*)(dst + (size_t)lt * 512 + n) = h;
.LBB0_648:
	v_lshl_add_u64 v[66:67], v[104:105], 0, v[132:133]
	v_mov_b32_e32 v65, v164
	v_add_f32_e32 v60, v60, v65
	v_mul_f32_e32 v60, 0xbfb8aa3b, v60
	v_exp_f32_e32 v60, v60
	s_nop 0
	v_add_f32_e32 v60, 1.0, v60
	v_rcp_f32_e32 v60, v60
	s_nop 0
	v_mul_f32_e32 v60, 0xbf1b4598, v60
	v_mul_f32_e32 v60, 0x3fb8aa3b, v60
	v_exp_f32_e32 v65, v60
.LBB0_649:
	s_or_b64 exec, exec, s[2:3]
	s_and_saveexec_b64 s[2:3], s[40:41]
	s_xor_b64 s[2:3], exec, s[2:3]
	s_cbranch_execz .LBB0_653
	v_mov_b32_e32 v66, v61
	s_and_saveexec_b64 s[20:21], vcc
	s_cbranch_execz .LBB0_652
	v_lshl_add_u64 v[66:67], v[104:105], 0, v[132:133]
	v_mov_b32_e32 v60, v165
	v_add_f32_e32 v60, v61, v60
	v_mul_f32_e32 v60, 0xbfb8aa3b, v60
	v_exp_f32_e32 v60, v60
	s_nop 0
	v_add_f32_e32 v60, 1.0, v60
	v_rcp_f32_e32 v66, v60

; __device__ __forceinline__ float sigmoidf_(float x) { return __builtin_amdgcn_rcpf(1.0f + __expf(-x)); }
; __device__ __forceinline__ void lora_phase(const Ctx& C, const PV& P, int layer, unsigned char* smem) {
;     ...
;                 for (int r = 0; r < 4; ++r) {
;                     float v = acc[i][jn][r];
;                     if (which < 2) {
;                         const float z = bias[n + r] + v;
;                         v = __expf(-0.6065306597126334f * sigmoidf_(z));
;                     } else if (which < 4) { v = sigmoidf_(bias[n + r] + v); }
;                     h[r] = (f16)v;
;                 }
;                 *(f16x4*)(dst + (size_t)lt * 512 + n) = h;
.LBB0_654:
	v_lshl_add_u64 v[66:67], v[104:105], 0, v[132:133]
	v_mov_b32_e32 v60, v165
	v_add_f32_e32 v60, v61, v60
	v_mul_f32_e32 v60, 0xbfb8aa3b, v60
	v_exp_f32_e32 v60, v60
	s_nop 0
	v_add_f32_e32 v60, 1.0, v60
	v_rcp_f32_e32 v60, v60
	s_nop 0
	v_mul_f32_e32 v60, 0xbf1b4598, v60
	v_mul_f32_e32 v60, 0x3fb8aa3b, v60
	v_exp_f32_e32 v66, v60
.LBB0_655:
	s_or_b64 exec, exec, s[2:3]
	s_and_saveexec_b64 s[2:3], s[40:41]
	s_xor_b64 s[2:3], exec, s[2:3]
	s_cbranch_execz .LBB0_659
	s_and_saveexec_b64 s[6:7], s[42:43]
	s_xor_b64 s[20:21], exec, s[6:7]
	s_or_saveexec_b64 s[20:21], s[20:21]
	v_mov_b32_e32 v67, v62
	s_xor_b64 exec, exec, s[20:21]
	s_cbranch_execz .LBB0_658
	v_lshlrev_b32_e32 v132, 2, v64
	v_lshl_add_u64 v[60:61], v[104:105], 0, v[132:133]
	v_mov_b32_e32 v60, v166
	v_add_f32_e32 v60, v62, v60
	v_mul_f32_e32 v60, 0xbfb8aa3b, v60
	v_exp_f32_e32 v60, v60
	s_nop 0
	v_add_f32_e32 v60, 1.0, v60
	v_rcp_f32_e32 v67, v60

; __device__ __forceinline__ float sigmoidf_(float x) { return __builtin_amdgcn_rcpf(1.0f + __expf(-x)); }
; __device__ __forceinline__ void lora_phase(const Ctx& C, const PV& P, int layer, unsigned char* smem) {
;     ...
;                 for (int r = 0; r < 4; ++r) {
;                     float v = acc[i][jn][r];
;                     if (which < 2) {
;                         const float z = bias[n + r] + v;
;                         v = __expf(-0.6065306597126334f * sigmoidf_(z));
;                     } else if (which < 4) { v = sigmoidf_(bias[n + r] + v); }
;                     h[r] = (f16)v;
;                 }
;                 *(f16x4*)(dst + (size_t)lt * 512 + n) = h;
.LBB0_660:
	v_lshlrev_b32_e32 v132, 2, v64
	v_lshl_add_u64 v[60:61], v[104:105], 0, v[132:133]
	v_mov_b32_e32 v60, v166
	v_add_f32_e32 v60, v62, v60
	v_mul_f32_e32 v60, 0xbfb8aa3b, v60
	v_exp_f32_e32 v60, v60
	s_nop 0
	v_add_f32_e32 v60, 1.0, v60
	v_rcp_f32_e32 v60, v60
	s_nop 0
	v_mul_f32_e32 v60, 0xbf1b4598, v60
	v_mul_f32_e32 v60, 0x3fb8aa3b, v60
	v_exp_f32_e32 v67, v60
.LBB0_661:
	s_or_b64 exec, exec, s[2:3]
	s_and_saveexec_b64 s[2:3], s[40:41]
	s_xor_b64 s[2:3], exec, s[2:3]
	s_cbranch_execz .LBB0_665
	v_mov_b32_e32 v61, v63
	s_and_saveexec_b64 s[20:21], vcc
	s_cbranch_execz .LBB0_664
	v_lshlrev_b32_e32 v132, 2, v64
	v_lshl_add_u64 v[60:61], v[104:105], 0, v[132:133]
	v_mov_b32_e32 v60, v167
	v_add_f32_e32 v60, v63, v60
	v_mul_f32_e32 v60, 0xbfb8aa3b, v60
	v_exp_f32_e32 v60, v60
	s_nop 0
	v_add_f32_e32 v60, 1.0, v60
	v_rcp_f32_e32 v61, v60

; __device__ __forceinline__ float sigmoidf_(float x) { return __builtin_amdgcn_rcpf(1.0f + __expf(-x)); }
; __device__ __forceinline__ void lora_phase(const Ctx& C, const PV& P, int layer, unsigned char* smem) {
;     ...
;                 for (int r = 0; r < 4; ++r) {
;                     float v = acc[i][jn][r];
;                     if (which < 2) {
;                         const float z = bias[n + r] + v;
;                         v = __expf(-0.6065306597126334f * sigmoidf_(z));
;                     } else if (which < 4) { v = sigmoidf_(bias[n + r] + v); }
;                     h[r] = (f16)v;
;                 }
;                 *(f16x4*)(dst + (size_t)lt * 512 + n) = h;
.LBB0_666:
	v_mov_b32_e32 v61, v133
	s_waitcnt vmcnt(6)
	v_lshl_add_u64 v[68:69], v[104:105], 0, v[60:61]
	v_mov_b32_e32 v61, v167
	v_add_f32_e32 v61, v63, v61
	v_mul_f32_e32 v61, 0xbfb8aa3b, v61
	v_exp_f32_e32 v61, v61
	s_nop 0
	v_add_f32_e32 v61, 1.0, v61
	v_rcp_f32_e32 v61, v61
	s_nop 0
	v_mul_f32_e32 v61, 0xbf1b4598, v61
	v_mul_f32_e32 v61, 0x3fb8aa3b, v61
	v_exp_f32_e32 v61, v61
.LBB0_667:
	s_or_b64 exec, exec, s[2:3]
	v_lshl_or_b32 v62, v127, 7, v120
	v_ashrrev_i32_e32 v63, 31, v62
	s_waitcnt vmcnt(6)
	v_lshlrev_b64 v[68:69], 10, v[62:63]
	v_lshl_add_u64 v[68:69], v[106:107], 0, v[68:69]
	v_lshlrev_b32_e32 v132, 1, v64
	v_cvt_pk_f16_f32 v67, v67, v61
	v_cvt_pk_f16_f32 v66, v65, v66
	v_lshl_add_u64 v[64:65], v[68:69], 0, v[132:133]
	global_store_dwordx2 v[64:65], v[66:67], off
	s_and_saveexec_b64 s[2:3], s[40:41]
	s_xor_b64 s[2:3], exec, s[2:3]
	s_cbranch_execz .LBB0_671
	v_mov_b32_e32 v63, v56
	s_and_saveexec_b64 s[20:21], vcc
	s_cbranch_execz .LBB0_670
	v_mov_b32_e32 v61, v133
	v_lshl_add_u64 v[66:67], v[104:105], 0, v[60:61]
	v_mov_b32_e32 v61, v168
	v_add_f32_e32 v61, v56, v61
	v_mul_f32_e32 v61, 0xbfb8aa3b, v61
	v_exp_f32_e32 v61, v61
	s_nop 0
	v_add_f32_e32 v61, 1.0, v61
	v_rcp_f32_e32 v63, v61

; __device__ __forceinline__ float sigmoidf_(float x) { return __builtin_amdgcn_rcpf(1.0f + __expf(-x)); }
; __device__ __forceinline__ void lora_phase(const Ctx& C, const PV& P, int layer, unsigned char* smem) {
;     ...
;                 for (int r = 0; r < 4; ++r) {
;                     float v = acc[i][jn][r];
;                     if (which < 2) {
;                         const float z = bias[n + r] + v;
;                         v = __expf(-0.6065306597126334f * sigmoidf_(z));
;                     } else if (which < 4) { v = sigmoidf_(bias[n + r] + v); }
;                     h[r] = (f16)v;
;                 }
;                 *(f16x4*)(dst + (size_t)lt * 512 + n) = h;
.LBB0_672:
	v_mov_b32_e32 v61, v133
	v_lshl_add_u64 v[66:67], v[104:105], 0, v[60:61]
	v_mov_b32_e32 v61, v168
	v_add_f32_e32 v56, v56, v61
	v_mul_f32_e32 v56, 0xbfb8aa3b, v56
	v_exp_f32_e32 v56, v56
	s_nop 0
	v_add_f32_e32 v56, 1.0, v56
	v_rcp_f32_e32 v56, v56
	s_nop 0
	v_mul_f32_e32 v56, 0xbf1b4598, v56
	v_mul_f32_e32 v56, 0x3fb8aa3b, v56
	v_exp_f32_e32 v63, v56
.LBB0_673:
	s_or_b64 exec, exec, s[2:3]
	s_and_saveexec_b64 s[2:3], s[40:41]
	s_xor_b64 s[2:3], exec, s[2:3]
	s_cbranch_execz .LBB0_677
	v_mov_b32_e32 v56, v57
	s_and_saveexec_b64 s[20:21], vcc
	s_cbranch_execz .LBB0_676
	v_mov_b32_e32 v61, v133
	v_lshl_add_u64 v[66:67], v[104:105], 0, v[60:61]
	v_mov_b32_e32 v56, v169
	v_add_f32_e32 v56, v57, v56
	v_mul_f32_e32 v56, 0xbfb8aa3b, v56
	v_exp_f32_e32 v56, v56
	s_nop 0
	v_add_f32_e32 v56, 1.0, v56
	v_rcp_f32_e32 v56, v56

; __device__ __forceinline__ float sigmoidf_(float x) { return __builtin_amdgcn_rcpf(1.0f + __expf(-x)); }
; __device__ __forceinline__ void lora_phase(const Ctx& C, const PV& P, int layer, unsigned char* smem) {
;     ...
;                 for (int r = 0; r < 4; ++r) {
;                     float v = acc[i][jn][r];
;                     if (which < 2) {
;                         const float z = bias[n + r] + v;
;                         v = __expf(-0.6065306597126334f * sigmoidf_(z));
;                     } else if (which < 4) { v = sigmoidf_(bias[n + r] + v); }
;                     h[r] = (f16)v;
;                 }
;                 *(f16x4*)(dst + (size_t)lt * 512 + n) = h;
.LBB0_678:
	v_mov_b32_e32 v61, v133
	v_lshl_add_u64 v[66:67], v[104:105], 0, v[60:61]
	v_mov_b32_e32 v56, v169
	v_add_f32_e32 v56, v57, v56
	v_mul_f32_e32 v56, 0xbfb8aa3b, v56
	v_exp_f32_e32 v56, v56
	s_nop 0
	v_add_f32_e32 v56, 1.0, v56
	v_rcp_f32_e32 v56, v56
	s_nop 0
	v_mul_f32_e32 v56, 0xbf1b4598, v56
	v_mul_f32_e32 v56, 0x3fb8aa3b, v56
	v_exp_f32_e32 v56, v56
.LBB0_679:
	s_or_b64 exec, exec, s[2:3]
	s_and_saveexec_b64 s[2:3], s[40:41]
	s_xor_b64 s[2:3], exec, s[2:3]
	s_cbranch_execz .LBB0_683
	v_mov_b32_e32 v57, v58
	s_and_saveexec_b64 s[20:21], vcc
	s_cbranch_execz .LBB0_682
	v_mov_b32_e32 v61, v133
	v_lshl_add_u64 v[66:67], v[104:105], 0, v[60:61]
	v_mov_b32_e32 v57, v170
	v_add_f32_e32 v57, v58, v57
	v_mul_f32_e32 v57, 0xbfb8aa3b, v57
	v_exp_f32_e32 v57, v57
	s_nop 0
	v_add_f32_e32 v57, 1.0, v57
	v_rcp_f32_e32 v57, v57

; __device__ __forceinline__ float sigmoidf_(float x) { return __builtin_amdgcn_rcpf(1.0f + __expf(-x)); }
; __device__ __forceinline__ void lora_phase(const Ctx& C, const PV& P, int layer, unsigned char* smem) {
;     ...
;                 for (int r = 0; r < 4; ++r) {
;                     float v = acc[i][jn][r];
;                     if (which < 2) {
;                         const float z = bias[n + r] + v;
;                         v = __expf(-0.6065306597126334f * sigmoidf_(z));
;                     } else if (which < 4) { v = sigmoidf_(bias[n + r] + v); }
;                     h[r] = (f16)v;
;                 }
;                 *(f16x4*)(dst + (size_t)lt * 512 + n) = h;
.LBB0_684:
	v_mov_b32_e32 v61, v133
	v_lshl_add_u64 v[66:67], v[104:105], 0, v[60:61]
	v_mov_b32_e32 v57, v170
	v_add_f32_e32 v57, v58, v57
	v_mul_f32_e32 v57, 0xbfb8aa3b, v57
	v_exp_f32_e32 v57, v57
	s_nop 0
	v_add_f32_e32 v57, 1.0, v57
	v_rcp_f32_e32 v57, v57
	s_nop 0
	v_mul_f32_e32 v57, 0xbf1b4598, v57
	v_mul_f32_e32 v57, 0x3fb8aa3b, v57
	v_exp_f32_e32 v57, v57
.LBB0_685:
	s_or_b64 exec, exec, s[2:3]
	s_and_saveexec_b64 s[2:3], s[40:41]
	s_xor_b64 s[2:3], exec, s[2:3]
	s_cbranch_execz .LBB0_689
	v_mov_b32_e32 v58, v59
	s_and_saveexec_b64 s[20:21], vcc
	s_cbranch_execz .LBB0_688
	v_mov_b32_e32 v61, v133
	v_lshl_add_u64 v[66:67], v[104:105], 0, v[60:61]
	v_mov_b32_e32 v58, v171
	v_add_f32_e32 v58, v59, v58
	v_mul_f32_e32 v58, 0xbfb8aa3b, v58
	v_exp_f32_e32 v58, v58
	s_nop 0
	v_add_f32_e32 v58, 1.0, v58
	v_rcp_f32_e32 v58, v58

; __device__ __forceinline__ float sigmoidf_(float x) { return __builtin_amdgcn_rcpf(1.0f + __expf(-x)); }
; __device__ __forceinline__ void lora_phase(const Ctx& C, const PV& P, int layer, unsigned char* smem) {
;     ...
;                 for (int r = 0; r < 4; ++r) {
;                     float v = acc[i][jn][r];
;                     if (which < 2) {
;                         const float z = bias[n + r] + v;
;                         v = __expf(-0.6065306597126334f * sigmoidf_(z));
;                     } else if (which < 4) { v = sigmoidf_(bias[n + r] + v); }
;                     h[r] = (f16)v;
;                 }
;                 *(f16x4*)(dst + (size_t)lt * 512 + n) = h;
.LBB0_690:
	v_mov_b32_e32 v61, v133
	v_lshl_add_u64 v[66:67], v[104:105], 0, v[60:61]
	v_mov_b32_e32 v58, v171
	v_add_f32_e32 v58, v59, v58
	v_mul_f32_e32 v58, 0xbfb8aa3b, v58
	v_exp_f32_e32 v58, v58
	s_nop 0
	v_add_f32_e32 v58, 1.0, v58
	v_rcp_f32_e32 v58, v58
	s_nop 0
	v_mul_f32_e32 v58, 0xbf1b4598, v58
	v_mul_f32_e32 v58, 0x3fb8aa3b, v58
	v_exp_f32_e32 v58, v58
.LBB0_691:
	s_or_b64 exec, exec, s[2:3]
	v_cvt_pk_f16_f32 v57, v57, v58
	v_cvt_pk_f16_f32 v56, v63, v56
	global_store_dwordx2 v[64:65], v[56:57], off offset:32
	s_and_saveexec_b64 s[2:3], s[40:41]
	s_xor_b64 s[2:3], exec, s[2:3]
	s_cbranch_execz .LBB0_695
	v_mov_b32_e32 v56, v52
	s_and_saveexec_b64 s[20:21], vcc
	s_cbranch_execz .LBB0_694
	v_mov_b32_e32 v61, v133
	v_lshl_add_u64 v[56:57], v[104:105], 0, v[60:61]
	v_mov_b32_e32 v56, v172
	v_add_f32_e32 v56, v52, v56
	v_mul_f32_e32 v56, 0xbfb8aa3b, v56
	v_exp_f32_e32 v56, v56
	s_nop 0
	v_add_f32_e32 v56, 1.0, v56
	v_rcp_f32_e32 v56, v56

; __device__ __forceinline__ float sigmoidf_(float x) { return __builtin_amdgcn_rcpf(1.0f + __expf(-x)); }
; __device__ __forceinline__ void lora_phase(const Ctx& C, const PV& P, int layer, unsigned char* smem) {
;     ...
;                 for (int r = 0; r < 4; ++r) {
;                     float v = acc[i][jn][r];
;                     if (which < 2) {
;                         const float z = bias[n + r] + v;
;                         v = __expf(-0.6065306597126334f * sigmoidf_(z));
;                     } else if (which < 4) { v = sigmoidf_(bias[n + r] + v); }
;                     h[r] = (f16)v;
;                 }
;                 *(f16x4*)(dst + (size_t)lt * 512 + n) = h;
.LBB0_696:
	v_mov_b32_e32 v61, v133
	v_lshl_add_u64 v[56:57], v[104:105], 0, v[60:61]
	v_mov_b32_e32 v56, v172
	v_add_f32_e32 v52, v52, v56
	v_mul_f32_e32 v52, 0xbfb8aa3b, v52
	v_exp_f32_e32 v52, v52
	s_nop 0
	v_add_f32_e32 v52, 1.0, v52
	v_rcp_f32_e32 v52, v52
	s_nop 0
	v_mul_f32_e32 v52, 0xbf1b4598, v52
	v_mul_f32_e32 v52, 0x3fb8aa3b, v52
	v_exp_f32_e32 v56, v52
.LBB0_697:
	s_or_b64 exec, exec, s[2:3]
	s_and_saveexec_b64 s[2:3], s[40:41]
	s_xor_b64 s[2:3], exec, s[2:3]
	s_cbranch_execz .LBB0_701
	v_mov_b32_e32 v52, v53
	s_and_saveexec_b64 s[20:21], vcc
	s_cbranch_execz .LBB0_700
	v_mov_b32_e32 v61, v133
	v_lshl_add_u64 v[58:59], v[104:105], 0, v[60:61]
	v_mov_b32_e32 v52, v173
	v_add_f32_e32 v52, v53, v52
	v_mul_f32_e32 v52, 0xbfb8aa3b, v52
	v_exp_f32_e32 v52, v52
	s_nop 0
	v_add_f32_e32 v52, 1.0, v52
	v_rcp_f32_e32 v52, v52

; __device__ __forceinline__ float sigmoidf_(float x) { return __builtin_amdgcn_rcpf(1.0f + __expf(-x)); }
; __device__ __forceinline__ void lora_phase(const Ctx& C, const PV& P, int layer, unsigned char* smem) {
;     ...
;                 for (int r = 0; r < 4; ++r) {
;                     float v = acc[i][jn][r];
;                     if (which < 2) {
;                         const float z = bias[n + r] + v;
;                         v = __expf(-0.6065306597126334f * sigmoidf_(z));
;                     } else if (which < 4) { v = sigmoidf_(bias[n + r] + v); }
;                     h[r] = (f16)v;
;                 }
;                 *(f16x4*)(dst + (size_t)lt * 512 + n) = h;
.LBB0_702:
	v_mov_b32_e32 v61, v133
	v_lshl_add_u64 v[58:59], v[104:105], 0, v[60:61]
	v_mov_b32_e32 v52, v173
	v_add_f32_e32 v52, v53, v52
	v_mul_f32_e32 v52, 0xbfb8aa3b, v52
	v_exp_f32_e32 v52, v52
	s_nop 0
	v_add_f32_e32 v52, 1.0, v52
	v_rcp_f32_e32 v52, v52
	s_nop 0
	v_mul_f32_e32 v52, 0xbf1b4598, v52
	v_mul_f32_e32 v52, 0x3fb8aa3b, v52
	v_exp_f32_e32 v52, v52
.LBB0_703:
	s_or_b64 exec, exec, s[2:3]
	s_and_saveexec_b64 s[2:3], s[40:41]
	s_xor_b64 s[2:3], exec, s[2:3]
	s_cbranch_execz .LBB0_707
	v_mov_b32_e32 v53, v54
	s_and_saveexec_b64 s[20:21], vcc
	s_cbranch_execz .LBB0_706
	v_mov_b32_e32 v61, v133
	v_lshl_add_u64 v[58:59], v[104:105], 0, v[60:61]
	v_mov_b32_e32 v53, v174
	v_add_f32_e32 v53, v54, v53
	v_mul_f32_e32 v53, 0xbfb8aa3b, v53
	v_exp_f32_e32 v53, v53
	s_nop 0
	v_add_f32_e32 v53, 1.0, v53
	v_rcp_f32_e32 v53, v53

; __device__ __forceinline__ float sigmoidf_(float x) { return __builtin_amdgcn_rcpf(1.0f + __expf(-x)); }
; __device__ __forceinline__ void lora_phase(const Ctx& C, const PV& P, int layer, unsigned char* smem) {
;     ...
;                 for (int r = 0; r < 4; ++r) {
;                     float v = acc[i][jn][r];
;                     if (which < 2) {
;                         const float z = bias[n + r] + v;
;                         v = __expf(-0.6065306597126334f * sigmoidf_(z));
;                     } else if (which < 4) { v = sigmoidf_(bias[n + r] + v); }
;                     h[r] = (f16)v;
;                 }
;                 *(f16x4*)(dst + (size_t)lt * 512 + n) = h;
.LBB0_708:
	v_mov_b32_e32 v61, v133
	v_lshl_add_u64 v[58:59], v[104:105], 0, v[60:61]
	v_mov_b32_e32 v53, v174
	v_add_f32_e32 v53, v54, v53
	v_mul_f32_e32 v53, 0xbfb8aa3b, v53
	v_exp_f32_e32 v53, v53
	s_nop 0
	v_add_f32_e32 v53, 1.0, v53
	v_rcp_f32_e32 v53, v53
	s_nop 0
	v_mul_f32_e32 v53, 0xbf1b4598, v53
	v_mul_f32_e32 v53, 0x3fb8aa3b, v53
	v_exp_f32_e32 v53, v53
.LBB0_709:
	s_or_b64 exec, exec, s[2:3]
	s_and_saveexec_b64 s[2:3], s[40:41]
	s_xor_b64 s[2:3], exec, s[2:3]
	s_cbranch_execz .LBB0_713
	v_mov_b32_e32 v54, v55
	s_and_saveexec_b64 s[20:21], vcc
	s_cbranch_execz .LBB0_712
	v_mov_b32_e32 v61, v133
	v_lshl_add_u64 v[58:59], v[104:105], 0, v[60:61]
	v_mov_b32_e32 v54, v175
	v_add_f32_e32 v54, v55, v54
	v_mul_f32_e32 v54, 0xbfb8aa3b, v54
	v_exp_f32_e32 v54, v54
	s_nop 0
	v_add_f32_e32 v54, 1.0, v54
	v_rcp_f32_e32 v54, v54

; __device__ __forceinline__ float sigmoidf_(float x) { return __builtin_amdgcn_rcpf(1.0f + __expf(-x)); }
; __device__ __forceinline__ void lora_phase(const Ctx& C, const PV& P, int layer, unsigned char* smem) {
;     ...
;                 for (int r = 0; r < 4; ++r) {
;                     float v = acc[i][jn][r];
;                     if (which < 2) {
;                         const float z = bias[n + r] + v;
;                         v = __expf(-0.6065306597126334f * sigmoidf_(z));
;                     } else if (which < 4) { v = sigmoidf_(bias[n + r] + v); }
;                     h[r] = (f16)v;
;                 }
;                 *(f16x4*)(dst + (size_t)lt * 512 + n) = h;
.LBB0_714:
	v_mov_b32_e32 v61, v133
	v_lshl_add_u64 v[58:59], v[104:105], 0, v[60:61]
	v_mov_b32_e32 v54, v175
	v_add_f32_e32 v54, v55, v54
	v_mul_f32_e32 v54, 0xbfb8aa3b, v54
	v_exp_f32_e32 v54, v54
	s_nop 0
	v_add_f32_e32 v54, 1.0, v54
	v_rcp_f32_e32 v54, v54
	s_nop 0
	v_mul_f32_e32 v54, 0xbf1b4598, v54
	v_mul_f32_e32 v54, 0x3fb8aa3b, v54
	v_exp_f32_e32 v54, v54
.LBB0_715:
	s_or_b64 exec, exec, s[2:3]
	v_cvt_pk_f16_f32 v53, v53, v54
	v_cvt_pk_f16_f32 v52, v56, v52
	global_store_dwordx2 v[64:65], v[52:53], off offset:64
	s_and_saveexec_b64 s[2:3], s[40:41]
	s_xor_b64 s[2:3], exec, s[2:3]
	s_cbranch_execz .LBB0_719
	v_mov_b32_e32 v52, v48
	s_and_saveexec_b64 s[20:21], vcc
	s_cbranch_execz .LBB0_718
	v_mov_b32_e32 v61, v133
	v_lshl_add_u64 v[52:53], v[104:105], 0, v[60:61]
	v_mov_b32_e32 v52, v176
	v_add_f32_e32 v52, v48, v52
	v_mul_f32_e32 v52, 0xbfb8aa3b, v52
	v_exp_f32_e32 v52, v52
	s_nop 0
	v_add_f32_e32 v52, 1.0, v52
	v_rcp_f32_e32 v52, v52

; __device__ __forceinline__ float sigmoidf_(float x) { return __builtin_amdgcn_rcpf(1.0f + __expf(-x)); }
; __device__ __forceinline__ void lora_phase(const Ctx& C, const PV& P, int layer, unsigned char* smem) {
;     ...
;                 for (int r = 0; r < 4; ++r) {
;                     float v = acc[i][jn][r];
;                     if (which < 2) {
;                         const float z = bias[n + r] + v;
;                         v = __expf(-0.6065306597126334f * sigmoidf_(z));
;                     } else if (which < 4) { v = sigmoidf_(bias[n + r] + v); }
;                     h[r] = (f16)v;
;                 }
;                 *(f16x4*)(dst + (size_t)lt * 512 + n) = h;
.LBB0_720:
	v_mov_b32_e32 v61, v133
	v_lshl_add_u64 v[52:53], v[104:105], 0, v[60:61]
	v_mov_b32_e32 v52, v176
	v_add_f32_e32 v48, v48, v52
	v_mul_f32_e32 v48, 0xbfb8aa3b, v48
	v_exp_f32_e32 v48, v48
	s_nop 0
	v_add_f32_e32 v48, 1.0, v48
	v_rcp_f32_e32 v48, v48
	s_nop 0
	v_mul_f32_e32 v48, 0xbf1b4598, v48
	v_mul_f32_e32 v48, 0x3fb8aa3b, v48
	v_exp_f32_e32 v52, v48
.LBB0_721:
	s_or_b64 exec, exec, s[2:3]
	s_and_saveexec_b64 s[2:3], s[40:41]
	s_xor_b64 s[2:3], exec, s[2:3]
	s_cbranch_execz .LBB0_725
	v_mov_b32_e32 v48, v49
	s_and_saveexec_b64 s[20:21], vcc
	s_cbranch_execz .LBB0_724
	v_mov_b32_e32 v61, v133
	v_lshl_add_u64 v[54:55], v[104:105], 0, v[60:61]
	v_mov_b32_e32 v48, v177
	v_add_f32_e32 v48, v49, v48
	v_mul_f32_e32 v48, 0xbfb8aa3b, v48
	v_exp_f32_e32 v48, v48
	s_nop 0
	v_add_f32_e32 v48, 1.0, v48
	v_rcp_f32_e32 v48, v48

; __device__ __forceinline__ float sigmoidf_(float x) { return __builtin_amdgcn_rcpf(1.0f + __expf(-x)); }
; __device__ __forceinline__ void lora_phase(const Ctx& C, const PV& P, int layer, unsigned char* smem) {
;     ...
;                 for (int r = 0; r < 4; ++r) {
;                     float v = acc[i][jn][r];
;                     if (which < 2) {
;                         const float z = bias[n + r] + v;
;                         v = __expf(-0.6065306597126334f * sigmoidf_(z));
;                     } else if (which < 4) { v = sigmoidf_(bias[n + r] + v); }
;                     h[r] = (f16)v;
;                 }
;                 *(f16x4*)(dst + (size_t)lt * 512 + n) = h;
.LBB0_726:
	v_mov_b32_e32 v61, v133
	v_lshl_add_u64 v[54:55], v[104:105], 0, v[60:61]
	v_mov_b32_e32 v48, v177
	v_add_f32_e32 v48, v49, v48
	v_mul_f32_e32 v48, 0xbfb8aa3b, v48
	v_exp_f32_e32 v48, v48
	s_nop 0
	v_add_f32_e32 v48, 1.0, v48
	v_rcp_f32_e32 v48, v48
	s_nop 0
	v_mul_f32_e32 v48, 0xbf1b4598, v48
	v_mul_f32_e32 v48, 0x3fb8aa3b, v48
	v_exp_f32_e32 v48, v48
.LBB0_727:
	s_or_b64 exec, exec, s[2:3]
	s_and_saveexec_b64 s[2:3], s[40:41]
	s_xor_b64 s[2:3], exec, s[2:3]
	s_cbranch_execz .LBB0_731
	v_mov_b32_e32 v49, v50
	s_and_saveexec_b64 s[20:21], vcc
	s_cbranch_execz .LBB0_730
	v_mov_b32_e32 v61, v133
	v_lshl_add_u64 v[54:55], v[104:105], 0, v[60:61]
	v_mov_b32_e32 v49, v178
	v_add_f32_e32 v49, v50, v49
	v_mul_f32_e32 v49, 0xbfb8aa3b, v49
	v_exp_f32_e32 v49, v49
	s_nop 0
	v_add_f32_e32 v49, 1.0, v49
	v_rcp_f32_e32 v49, v49

; __device__ __forceinline__ float sigmoidf_(float x) { return __builtin_amdgcn_rcpf(1.0f + __expf(-x)); }
; __device__ __forceinline__ void lora_phase(const Ctx& C, const PV& P, int layer, unsigned char* smem) {
;     ...
;                 for (int r = 0; r < 4; ++r) {
;                     float v = acc[i][jn][r];
;                     if (which < 2) {
;                         const float z = bias[n + r] + v;
;                         v = __expf(-0.6065306597126334f * sigmoidf_(z));
;                     } else if (which < 4) { v = sigmoidf_(bias[n + r] + v); }
;                     h[r] = (f16)v;
;                 }
;                 *(f16x4*)(dst + (size_t)lt * 512 + n) = h;
.LBB0_732:
	v_mov_b32_e32 v61, v133
	v_lshl_add_u64 v[54:55], v[104:105], 0, v[60:61]
	v_mov_b32_e32 v49, v178
	v_add_f32_e32 v49, v50, v49
	v_mul_f32_e32 v49, 0xbfb8aa3b, v49
	v_exp_f32_e32 v49, v49
	s_nop 0
	v_add_f32_e32 v49, 1.0, v49
	v_rcp_f32_e32 v49, v49
	s_nop 0
	v_mul_f32_e32 v49, 0xbf1b4598, v49
	v_mul_f32_e32 v49, 0x3fb8aa3b, v49
	v_exp_f32_e32 v49, v49
.LBB0_733:
	s_or_b64 exec, exec, s[2:3]
	s_and_saveexec_b64 s[2:3], s[40:41]
	s_xor_b64 s[2:3], exec, s[2:3]
	s_cbranch_execz .LBB0_737
	v_mov_b32_e32 v50, v51
	s_and_saveexec_b64 s[20:21], vcc
	s_cbranch_execz .LBB0_736
	v_mov_b32_e32 v61, v133
	v_lshl_add_u64 v[54:55], v[104:105], 0, v[60:61]
	v_mov_b32_e32 v50, v179
	v_add_f32_e32 v50, v51, v50
	v_mul_f32_e32 v50, 0xbfb8aa3b, v50
	v_exp_f32_e32 v50, v50
	s_nop 0
	v_add_f32_e32 v50, 1.0, v50
	v_rcp_f32_e32 v50, v50

; __device__ __forceinline__ float sigmoidf_(float x) { return __builtin_amdgcn_rcpf(1.0f + __expf(-x)); }
; __device__ __forceinline__ void lora_phase(const Ctx& C, const PV& P, int layer, unsigned char* smem) {
;     ...
;                 for (int r = 0; r < 4; ++r) {
;                     float v = acc[i][jn][r];
;                     if (which < 2) {
;                         const float z = bias[n + r] + v;
;                         v = __expf(-0.6065306597126334f * sigmoidf_(z));
;                     } else if (which < 4) { v = sigmoidf_(bias[n + r] + v); }
;                     h[r] = (f16)v;
;                 }
;                 *(f16x4*)(dst + (size_t)lt * 512 + n) = h;
.LBB0_738:
	v_mov_b32_e32 v61, v133
	v_lshl_add_u64 v[54:55], v[104:105], 0, v[60:61]
	v_mov_b32_e32 v50, v179
	v_add_f32_e32 v50, v51, v50
	v_mul_f32_e32 v50, 0xbfb8aa3b, v50
	v_exp_f32_e32 v50, v50
	s_nop 0
	v_add_f32_e32 v50, 1.0, v50
	v_rcp_f32_e32 v50, v50
	s_nop 0
	v_mul_f32_e32 v50, 0xbf1b4598, v50
	v_mul_f32_e32 v50, 0x3fb8aa3b, v50
	v_exp_f32_e32 v50, v50
.LBB0_739:
	s_or_b64 exec, exec, s[2:3]
	v_cvt_pk_f16_f32 v49, v49, v50
	v_cvt_pk_f16_f32 v48, v52, v48
	global_store_dwordx2 v[64:65], v[48:49], off offset:96
	s_and_saveexec_b64 s[2:3], s[40:41]
	s_xor_b64 s[2:3], exec, s[2:3]
	s_cbranch_execz .LBB0_743
	v_mov_b32_e32 v48, v44
	s_and_saveexec_b64 s[20:21], vcc
	s_cbranch_execz .LBB0_742
	v_mov_b32_e32 v61, v133
	v_lshl_add_u64 v[48:49], v[104:105], 0, v[60:61]
	v_mov_b32_e32 v48, v164
	v_add_f32_e32 v48, v44, v48
	v_mul_f32_e32 v48, 0xbfb8aa3b, v48
	v_exp_f32_e32 v48, v48
	s_nop 0
	v_add_f32_e32 v48, 1.0, v48
	v_rcp_f32_e32 v48, v48

; __device__ __forceinline__ float sigmoidf_(float x) { return __builtin_amdgcn_rcpf(1.0f + __expf(-x)); }
; __device__ __forceinline__ void lora_phase(const Ctx& C, const PV& P, int layer, unsigned char* smem) {
;     ...
;                 for (int r = 0; r < 4; ++r) {
;                     float v = acc[i][jn][r];
;                     if (which < 2) {
;                         const float z = bias[n + r] + v;
;                         v = __expf(-0.6065306597126334f * sigmoidf_(z));
;                     } else if (which < 4) { v = sigmoidf_(bias[n + r] + v); }
;                     h[r] = (f16)v;
;                 }
;                 *(f16x4*)(dst + (size_t)lt * 512 + n) = h;
.LBB0_744:
	v_mov_b32_e32 v61, v133
	v_lshl_add_u64 v[48:49], v[104:105], 0, v[60:61]
	v_mov_b32_e32 v48, v164
	v_add_f32_e32 v44, v44, v48
	v_mul_f32_e32 v44, 0xbfb8aa3b, v44
	v_exp_f32_e32 v44, v44
	s_nop 0
	v_add_f32_e32 v44, 1.0, v44
	v_rcp_f32_e32 v44, v44
	s_nop 0
	v_mul_f32_e32 v44, 0xbf1b4598, v44
	v_mul_f32_e32 v44, 0x3fb8aa3b, v44
	v_exp_f32_e32 v48, v44
.LBB0_745:
	s_or_b64 exec, exec, s[2:3]
	s_and_saveexec_b64 s[2:3], s[40:41]
	s_xor_b64 s[2:3], exec, s[2:3]
	s_cbranch_execz .LBB0_749
	v_mov_b32_e32 v44, v45
	s_and_saveexec_b64 s[20:21], vcc
	s_cbranch_execz .LBB0_748
	v_mov_b32_e32 v61, v133
	v_lshl_add_u64 v[50:51], v[104:105], 0, v[60:61]
	v_mov_b32_e32 v44, v165
	v_add_f32_e32 v44, v45, v44
	v_mul_f32_e32 v44, 0xbfb8aa3b, v44
	v_exp_f32_e32 v44, v44
	s_nop 0
	v_add_f32_e32 v44, 1.0, v44
	v_rcp_f32_e32 v44, v44

; __device__ __forceinline__ float sigmoidf_(float x) { return __builtin_amdgcn_rcpf(1.0f + __expf(-x)); }
; __device__ __forceinline__ void lora_phase(const Ctx& C, const PV& P, int layer, unsigned char* smem) {
;     ...
;                 for (int r = 0; r < 4; ++r) {
;                     float v = acc[i][jn][r];
;                     if (which < 2) {
;                         const float z = bias[n + r] + v;
;                         v = __expf(-0.6065306597126334f * sigmoidf_(z));
;                     } else if (which < 4) { v = sigmoidf_(bias[n + r] + v); }
;                     h[r] = (f16)v;
;                 }
;                 *(f16x4*)(dst + (size_t)lt * 512 + n) = h;
.LBB0_750:
	v_mov_b32_e32 v61, v133
	v_lshl_add_u64 v[50:51], v[104:105], 0, v[60:61]
	v_mov_b32_e32 v44, v165
	v_add_f32_e32 v44, v45, v44
	v_mul_f32_e32 v44, 0xbfb8aa3b, v44
	v_exp_f32_e32 v44, v44
	s_nop 0
	v_add_f32_e32 v44, 1.0, v44
	v_rcp_f32_e32 v44, v44
	s_nop 0
	v_mul_f32_e32 v44, 0xbf1b4598, v44
	v_mul_f32_e32 v44, 0x3fb8aa3b, v44
	v_exp_f32_e32 v44, v44
.LBB0_751:
	s_or_b64 exec, exec, s[2:3]
	s_and_saveexec_b64 s[2:3], s[40:41]
	s_xor_b64 s[2:3], exec, s[2:3]
	s_cbranch_execz .LBB0_755
	v_mov_b32_e32 v45, v46
	s_and_saveexec_b64 s[20:21], vcc
	s_cbranch_execz .LBB0_754
	v_mov_b32_e32 v61, v133
	v_lshl_add_u64 v[50:51], v[104:105], 0, v[60:61]
	v_mov_b32_e32 v45, v166
	v_add_f32_e32 v45, v46, v45
	v_mul_f32_e32 v45, 0xbfb8aa3b, v45
	v_exp_f32_e32 v45, v45
	s_nop 0
	v_add_f32_e32 v45, 1.0, v45
	v_rcp_f32_e32 v45, v45

; __device__ __forceinline__ float sigmoidf_(float x) { return __builtin_amdgcn_rcpf(1.0f + __expf(-x)); }
; __device__ __forceinline__ void lora_phase(const Ctx& C, const PV& P, int layer, unsigned char* smem) {
;     ...
;                 for (int r = 0; r < 4; ++r) {
;                     float v = acc[i][jn][r];
;                     if (which < 2) {
;                         const float z = bias[n + r] + v;
;                         v = __expf(-0.6065306597126334f * sigmoidf_(z));
;                     } else if (which < 4) { v = sigmoidf_(bias[n + r] + v); }
;                     h[r] = (f16)v;
;                 }
;                 *(f16x4*)(dst + (size_t)lt * 512 + n) = h;
.LBB0_756:
	v_mov_b32_e32 v61, v133
	v_lshl_add_u64 v[50:51], v[104:105], 0, v[60:61]
	v_mov_b32_e32 v45, v166
	v_add_f32_e32 v45, v46, v45
	v_mul_f32_e32 v45, 0xbfb8aa3b, v45
	v_exp_f32_e32 v45, v45
	s_nop 0
	v_add_f32_e32 v45, 1.0, v45
	v_rcp_f32_e32 v45, v45
	s_nop 0
	v_mul_f32_e32 v45, 0xbf1b4598, v45
	v_mul_f32_e32 v45, 0x3fb8aa3b, v45
	v_exp_f32_e32 v45, v45
.LBB0_757:
	s_or_b64 exec, exec, s[2:3]
	s_and_saveexec_b64 s[2:3], s[40:41]
	s_xor_b64 s[2:3], exec, s[2:3]
	s_cbranch_execz .LBB0_761
	v_mov_b32_e32 v46, v47
	s_and_saveexec_b64 s[20:21], vcc
	s_cbranch_execz .LBB0_760
	v_mov_b32_e32 v61, v133
	v_lshl_add_u64 v[50:51], v[104:105], 0, v[60:61]
	v_mov_b32_e32 v46, v167
	v_add_f32_e32 v46, v47, v46
	v_mul_f32_e32 v46, 0xbfb8aa3b, v46
	v_exp_f32_e32 v46, v46
	s_nop 0
	v_add_f32_e32 v46, 1.0, v46
	v_rcp_f32_e32 v46, v46

; __device__ __forceinline__ float sigmoidf_(float x) { return __builtin_amdgcn_rcpf(1.0f + __expf(-x)); }
; __device__ __forceinline__ void lora_phase(const Ctx& C, const PV& P, int layer, unsigned char* smem) {
;     ...
;                 for (int r = 0; r < 4; ++r) {
;                     float v = acc[i][jn][r];
;                     if (which < 2) {
;                         const float z = bias[n + r] + v;
;                         v = __expf(-0.6065306597126334f * sigmoidf_(z));
;                     } else if (which < 4) { v = sigmoidf_(bias[n + r] + v); }
;                     h[r] = (f16)v;
;                 }
;                 *(f16x4*)(dst + (size_t)lt * 512 + n) = h;
.LBB0_762:
	v_mov_b32_e32 v61, v133
	v_lshl_add_u64 v[50:51], v[104:105], 0, v[60:61]
	v_mov_b32_e32 v46, v167
	v_add_f32_e32 v46, v47, v46
	v_mul_f32_e32 v46, 0xbfb8aa3b, v46
	v_exp_f32_e32 v46, v46
	s_nop 0
	v_add_f32_e32 v46, 1.0, v46
	v_rcp_f32_e32 v46, v46
	s_nop 0
	v_mul_f32_e32 v46, 0xbf1b4598, v46
	v_mul_f32_e32 v46, 0x3fb8aa3b, v46
	v_exp_f32_e32 v46, v46
.LBB0_763:
	s_or_b64 exec, exec, s[2:3]
	v_or_b32_e32 v50, 16, v62
	v_ashrrev_i32_e32 v51, 31, v50
	v_lshlrev_b64 v[50:51], 10, v[50:51]
	v_lshl_add_u64 v[50:51], v[106:107], 0, v[50:51]
	v_cvt_pk_f16_f32 v47, v45, v46
	v_cvt_pk_f16_f32 v46, v48, v44
	v_lshl_add_u64 v[44:45], v[50:51], 0, v[132:133]
	global_store_dwordx2 v[44:45], v[46:47], off
	s_and_saveexec_b64 s[2:3], s[40:41]
	s_xor_b64 s[2:3], exec, s[2:3]
	s_cbranch_execz .LBB0_767
	v_mov_b32_e32 v46, v40
	s_and_saveexec_b64 s[20:21], vcc
	s_cbranch_execz .LBB0_766
	v_mov_b32_e32 v61, v133
	v_lshl_add_u64 v[46:47], v[104:105], 0, v[60:61]
	v_mov_b32_e32 v46, v168
	v_add_f32_e32 v46, v40, v46
	v_mul_f32_e32 v46, 0xbfb8aa3b, v46
	v_exp_f32_e32 v46, v46
	s_nop 0
	v_add_f32_e32 v46, 1.0, v46
	v_rcp_f32_e32 v46, v46

; __device__ __forceinline__ float sigmoidf_(float x) { return __builtin_amdgcn_rcpf(1.0f + __expf(-x)); }
; __device__ __forceinline__ void lora_phase(const Ctx& C, const PV& P, int layer, unsigned char* smem) {
;     ...
;                 for (int r = 0; r < 4; ++r) {
;                     float v = acc[i][jn][r];
;                     if (which < 2) {
;                         const float z = bias[n + r] + v;
;                         v = __expf(-0.6065306597126334f * sigmoidf_(z));
;                     } else if (which < 4) { v = sigmoidf_(bias[n + r] + v); }
;                     h[r] = (f16)v;
;                 }
;                 *(f16x4*)(dst + (size_t)lt * 512 + n) = h;
.LBB0_768:
	v_mov_b32_e32 v61, v133
	v_lshl_add_u64 v[46:47], v[104:105], 0, v[60:61]
	v_mov_b32_e32 v46, v168
	v_add_f32_e32 v40, v40, v46
	v_mul_f32_e32 v40, 0xbfb8aa3b, v40
	v_exp_f32_e32 v40, v40
	s_nop 0
	v_add_f32_e32 v40, 1.0, v40
	v_rcp_f32_e32 v40, v40
	s_nop 0
	v_mul_f32_e32 v40, 0xbf1b4598, v40
	v_mul_f32_e32 v40, 0x3fb8aa3b, v40
	v_exp_f32_e32 v46, v40
.LBB0_769:
	s_or_b64 exec, exec, s[2:3]
	s_and_saveexec_b64 s[2:3], s[40:41]
	s_xor_b64 s[2:3], exec, s[2:3]
	s_cbranch_execz .LBB0_773
	v_mov_b32_e32 v40, v41
	s_and_saveexec_b64 s[20:21], vcc
	s_cbranch_execz .LBB0_772
	v_mov_b32_e32 v61, v133
	v_lshl_add_u64 v[48:49], v[104:105], 0, v[60:61]
	v_mov_b32_e32 v40, v169
	v_add_f32_e32 v40, v41, v40
	v_mul_f32_e32 v40, 0xbfb8aa3b, v40
	v_exp_f32_e32 v40, v40
	s_nop 0
	v_add_f32_e32 v40, 1.0, v40
	v_rcp_f32_e32 v40, v40

; __device__ __forceinline__ float sigmoidf_(float x) { return __builtin_amdgcn_rcpf(1.0f + __expf(-x)); }
; __device__ __forceinline__ void lora_phase(const Ctx& C, const PV& P, int layer, unsigned char* smem) {
;     ...
;                 for (int r = 0; r < 4; ++r) {
;                     float v = acc[i][jn][r];
;                     if (which < 2) {
;                         const float z = bias[n + r] + v;
;                         v = __expf(-0.6065306597126334f * sigmoidf_(z));
;                     } else if (which < 4) { v = sigmoidf_(bias[n + r] + v); }
;                     h[r] = (f16)v;
;                 }
;                 *(f16x4*)(dst + (size_t)lt * 512 + n) = h;
.LBB0_774:
	v_mov_b32_e32 v61, v133
	v_lshl_add_u64 v[48:49], v[104:105], 0, v[60:61]
	v_mov_b32_e32 v40, v169
	v_add_f32_e32 v40, v41, v40
	v_mul_f32_e32 v40, 0xbfb8aa3b, v40
	v_exp_f32_e32 v40, v40
	s_nop 0
	v_add_f32_e32 v40, 1.0, v40
	v_rcp_f32_e32 v40, v40
	s_nop 0
	v_mul_f32_e32 v40, 0xbf1b4598, v40
	v_mul_f32_e32 v40, 0x3fb8aa3b, v40
	v_exp_f32_e32 v40, v40
.LBB0_775:
	s_or_b64 exec, exec, s[2:3]
	s_and_saveexec_b64 s[2:3], s[40:41]
	s_xor_b64 s[2:3], exec, s[2:3]
	s_cbranch_execz .LBB0_779
	v_mov_b32_e32 v41, v42
	s_and_saveexec_b64 s[20:21], vcc
	s_cbranch_execz .LBB0_778
	v_mov_b32_e32 v61, v133
	v_lshl_add_u64 v[48:49], v[104:105], 0, v[60:61]
	v_mov_b32_e32 v41, v170
	v_add_f32_e32 v41, v42, v41
	v_mul_f32_e32 v41, 0xbfb8aa3b, v41
	v_exp_f32_e32 v41, v41
	s_nop 0
	v_add_f32_e32 v41, 1.0, v41
	v_rcp_f32_e32 v41, v41

; __device__ __forceinline__ float sigmoidf_(float x) { return __builtin_amdgcn_rcpf(1.0f + __expf(-x)); }
; __device__ __forceinline__ void lora_phase(const Ctx& C, const PV& P, int layer, unsigned char* smem) {
;     ...
;                 for (int r = 0; r < 4; ++r) {
;                     float v = acc[i][jn][r];
;                     if (which < 2) {
;                         const float z = bias[n + r] + v;
;                         v = __expf(-0.6065306597126334f * sigmoidf_(z));
;                     } else if (which < 4) { v = sigmoidf_(bias[n + r] + v); }
;                     h[r] = (f16)v;
;                 }
;                 *(f16x4*)(dst + (size_t)lt * 512 + n) = h;
.LBB0_780:
	v_mov_b32_e32 v61, v133
	v_lshl_add_u64 v[48:49], v[104:105], 0, v[60:61]
	v_mov_b32_e32 v41, v170
	v_add_f32_e32 v41, v42, v41
	v_mul_f32_e32 v41, 0xbfb8aa3b, v41
	v_exp_f32_e32 v41, v41
	s_nop 0
	v_add_f32_e32 v41, 1.0, v41
	v_rcp_f32_e32 v41, v41
	s_nop 0
	v_mul_f32_e32 v41, 0xbf1b4598, v41
	v_mul_f32_e32 v41, 0x3fb8aa3b, v41
	v_exp_f32_e32 v41, v41
.LBB0_781:
	s_or_b64 exec, exec, s[2:3]
	s_and_saveexec_b64 s[2:3], s[40:41]
	s_xor_b64 s[2:3], exec, s[2:3]
	s_cbranch_execz .LBB0_785
	v_mov_b32_e32 v42, v43
	s_and_saveexec_b64 s[20:21], vcc
	s_cbranch_execz .LBB0_784
	v_mov_b32_e32 v61, v133
	v_lshl_add_u64 v[48:49], v[104:105], 0, v[60:61]
	v_mov_b32_e32 v42, v171
	v_add_f32_e32 v42, v43, v42
	v_mul_f32_e32 v42, 0xbfb8aa3b, v42
	v_exp_f32_e32 v42, v42
	s_nop 0
	v_add_f32_e32 v42, 1.0, v42
	v_rcp_f32_e32 v42, v42

; __device__ __forceinline__ float sigmoidf_(float x) { return __builtin_amdgcn_rcpf(1.0f + __expf(-x)); }
; __device__ __forceinline__ void lora_phase(const Ctx& C, const PV& P, int layer, unsigned char* smem) {
;     ...
;                 for (int r = 0; r < 4; ++r) {
;                     float v = acc[i][jn][r];
;                     if (which < 2) {
;                         const float z = bias[n + r] + v;
;                         v = __expf(-0.6065306597126334f * sigmoidf_(z));
;                     } else if (which < 4) { v = sigmoidf_(bias[n + r] + v); }
;                     h[r] = (f16)v;
;                 }
;                 *(f16x4*)(dst + (size_t)lt * 512 + n) = h;
.LBB0_786:
	v_mov_b32_e32 v61, v133
	v_lshl_add_u64 v[48:49], v[104:105], 0, v[60:61]
	v_mov_b32_e32 v42, v171
	v_add_f32_e32 v42, v43, v42
	v_mul_f32_e32 v42, 0xbfb8aa3b, v42
	v_exp_f32_e32 v42, v42
	s_nop 0
	v_add_f32_e32 v42, 1.0, v42
	v_rcp_f32_e32 v42, v42
	s_nop 0
	v_mul_f32_e32 v42, 0xbf1b4598, v42
	v_mul_f32_e32 v42, 0x3fb8aa3b, v42
	v_exp_f32_e32 v42, v42
.LBB0_787:
	s_or_b64 exec, exec, s[2:3]
	v_cvt_pk_f16_f32 v41, v41, v42
	v_cvt_pk_f16_f32 v40, v46, v40
	global_store_dwordx2 v[44:45], v[40:41], off offset:32
	s_and_saveexec_b64 s[2:3], s[40:41]
	s_xor_b64 s[2:3], exec, s[2:3]
	s_cbranch_execz .LBB0_791
	v_mov_b32_e32 v40, v36
	s_and_saveexec_b64 s[20:21], vcc
	s_cbranch_execz .LBB0_790
	v_mov_b32_e32 v61, v133
	v_lshl_add_u64 v[40:41], v[104:105], 0, v[60:61]
	v_mov_b32_e32 v40, v172
	v_add_f32_e32 v40, v36, v40
	v_mul_f32_e32 v40, 0xbfb8aa3b, v40
	v_exp_f32_e32 v40, v40
	s_nop 0
	v_add_f32_e32 v40, 1.0, v40
	v_rcp_f32_e32 v40, v40

; __device__ __forceinline__ float sigmoidf_(float x) { return __builtin_amdgcn_rcpf(1.0f + __expf(-x)); }
; __device__ __forceinline__ void lora_phase(const Ctx& C, const PV& P, int layer, unsigned char* smem) {
;     ...
;                 for (int r = 0; r < 4; ++r) {
;                     float v = acc[i][jn][r];
;                     if (which < 2) {
;                         const float z = bias[n + r] + v;
;                         v = __expf(-0.6065306597126334f * sigmoidf_(z));
;                     } else if (which < 4) { v = sigmoidf_(bias[n + r] + v); }
;                     h[r] = (f16)v;
;                 }
;                 *(f16x4*)(dst + (size_t)lt * 512 + n) = h;
.LBB0_792:
	v_mov_b32_e32 v61, v133
	v_lshl_add_u64 v[40:41], v[104:105], 0, v[60:61]
	v_mov_b32_e32 v40, v172
	v_add_f32_e32 v36, v36, v40
	v_mul_f32_e32 v36, 0xbfb8aa3b, v36
	v_exp_f32_e32 v36, v36
	s_nop 0
	v_add_f32_e32 v36, 1.0, v36
	v_rcp_f32_e32 v36, v36
	s_nop 0
	v_mul_f32_e32 v36, 0xbf1b4598, v36
	v_mul_f32_e32 v36, 0x3fb8aa3b, v36
	v_exp_f32_e32 v40, v36
.LBB0_793:
	s_or_b64 exec, exec, s[2:3]
	s_and_saveexec_b64 s[2:3], s[40:41]
	s_xor_b64 s[2:3], exec, s[2:3]
	s_cbranch_execz .LBB0_797
	v_mov_b32_e32 v36, v37
	s_and_saveexec_b64 s[20:21], vcc
	s_cbranch_execz .LBB0_796
	v_mov_b32_e32 v61, v133
	v_lshl_add_u64 v[42:43], v[104:105], 0, v[60:61]
	v_mov_b32_e32 v36, v173
	v_add_f32_e32 v36, v37, v36
	v_mul_f32_e32 v36, 0xbfb8aa3b, v36
	v_exp_f32_e32 v36, v36
	s_nop 0
	v_add_f32_e32 v36, 1.0, v36
	v_rcp_f32_e32 v36, v36

; __device__ __forceinline__ float sigmoidf_(float x) { return __builtin_amdgcn_rcpf(1.0f + __expf(-x)); }
; __device__ __forceinline__ void lora_phase(const Ctx& C, const PV& P, int layer, unsigned char* smem) {
;     ...
;                 for (int r = 0; r < 4; ++r) {
;                     float v = acc[i][jn][r];
;                     if (which < 2) {
;                         const float z = bias[n + r] + v;
;                         v = __expf(-0.6065306597126334f * sigmoidf_(z));
;                     } else if (which < 4) { v = sigmoidf_(bias[n + r] + v); }
;                     h[r] = (f16)v;
;                 }
;                 *(f16x4*)(dst + (size_t)lt * 512 + n) = h;
.LBB0_798:
	v_mov_b32_e32 v61, v133
	v_lshl_add_u64 v[42:43], v[104:105], 0, v[60:61]
	v_mov_b32_e32 v36, v173
	v_add_f32_e32 v36, v37, v36
	v_mul_f32_e32 v36, 0xbfb8aa3b, v36
	v_exp_f32_e32 v36, v36
	s_nop 0
	v_add_f32_e32 v36, 1.0, v36
	v_rcp_f32_e32 v36, v36
	s_nop 0
	v_mul_f32_e32 v36, 0xbf1b4598, v36
	v_mul_f32_e32 v36, 0x3fb8aa3b, v36
	v_exp_f32_e32 v36, v36
.LBB0_799:
	s_or_b64 exec, exec, s[2:3]
	s_and_saveexec_b64 s[2:3], s[40:41]
	s_xor_b64 s[2:3], exec, s[2:3]
	s_cbranch_execz .LBB0_803
	v_mov_b32_e32 v37, v38
	s_and_saveexec_b64 s[20:21], vcc
	s_cbranch_execz .LBB0_802
	v_mov_b32_e32 v61, v133
	v_lshl_add_u64 v[42:43], v[104:105], 0, v[60:61]
	v_mov_b32_e32 v37, v174
	v_add_f32_e32 v37, v38, v37
	v_mul_f32_e32 v37, 0xbfb8aa3b, v37
	v_exp_f32_e32 v37, v37
	s_nop 0
	v_add_f32_e32 v37, 1.0, v37
	v_rcp_f32_e32 v37, v37

; __device__ __forceinline__ float sigmoidf_(float x) { return __builtin_amdgcn_rcpf(1.0f + __expf(-x)); }
; __device__ __forceinline__ void lora_phase(const Ctx& C, const PV& P, int layer, unsigned char* smem) {
;     ...
;                 for (int r = 0; r < 4; ++r) {
;                     float v = acc[i][jn][r];
;                     if (which < 2) {
;                         const float z = bias[n + r] + v;
;                         v = __expf(-0.6065306597126334f * sigmoidf_(z));
;                     } else if (which < 4) { v = sigmoidf_(bias[n + r] + v); }
;                     h[r] = (f16)v;
;                 }
;                 *(f16x4*)(dst + (size_t)lt * 512 + n) = h;
.LBB0_804:
	v_mov_b32_e32 v61, v133
	v_lshl_add_u64 v[42:43], v[104:105], 0, v[60:61]
	v_mov_b32_e32 v37, v174
	v_add_f32_e32 v37, v38, v37
	v_mul_f32_e32 v37, 0xbfb8aa3b, v37
	v_exp_f32_e32 v37, v37
	s_nop 0
	v_add_f32_e32 v37, 1.0, v37
	v_rcp_f32_e32 v37, v37
	s_nop 0
	v_mul_f32_e32 v37, 0xbf1b4598, v37
	v_mul_f32_e32 v37, 0x3fb8aa3b, v37
	v_exp_f32_e32 v37, v37
.LBB0_805:
	s_or_b64 exec, exec, s[2:3]
	s_and_saveexec_b64 s[2:3], s[40:41]
	s_xor_b64 s[2:3], exec, s[2:3]
	s_cbranch_execz .LBB0_809
	v_mov_b32_e32 v38, v39
	s_and_saveexec_b64 s[20:21], vcc
	s_cbranch_execz .LBB0_808
	v_mov_b32_e32 v61, v133
	v_lshl_add_u64 v[42:43], v[104:105], 0, v[60:61]
	v_mov_b32_e32 v38, v175
	v_add_f32_e32 v38, v39, v38
	v_mul_f32_e32 v38, 0xbfb8aa3b, v38
	v_exp_f32_e32 v38, v38
	s_nop 0
	v_add_f32_e32 v38, 1.0, v38
	v_rcp_f32_e32 v38, v38

; __device__ __forceinline__ float sigmoidf_(float x) { return __builtin_amdgcn_rcpf(1.0f + __expf(-x)); }
; __device__ __forceinline__ void lora_phase(const Ctx& C, const PV& P, int layer, unsigned char* smem) {
;     ...
;                 for (int r = 0; r < 4; ++r) {
;                     float v = acc[i][jn][r];
;                     if (which < 2) {
;                         const float z = bias[n + r] + v;
;                         v = __expf(-0.6065306597126334f * sigmoidf_(z));
;                     } else if (which < 4) { v = sigmoidf_(bias[n + r] + v); }
;                     h[r] = (f16)v;
;                 }
;                 *(f16x4*)(dst + (size_t)lt * 512 + n) = h;
.LBB0_810:
	v_mov_b32_e32 v61, v133
	v_lshl_add_u64 v[42:43], v[104:105], 0, v[60:61]
	v_mov_b32_e32 v38, v175
	v_add_f32_e32 v38, v39, v38
	v_mul_f32_e32 v38, 0xbfb8aa3b, v38
	v_exp_f32_e32 v38, v38
	s_nop 0
	v_add_f32_e32 v38, 1.0, v38
	v_rcp_f32_e32 v38, v38
	s_nop 0
	v_mul_f32_e32 v38, 0xbf1b4598, v38
	v_mul_f32_e32 v38, 0x3fb8aa3b, v38
	v_exp_f32_e32 v38, v38
.LBB0_811:
	s_or_b64 exec, exec, s[2:3]
	v_cvt_pk_f16_f32 v37, v37, v38
	v_cvt_pk_f16_f32 v36, v40, v36
	global_store_dwordx2 v[44:45], v[36:37], off offset:64
	s_and_saveexec_b64 s[2:3], s[40:41]
	s_xor_b64 s[2:3], exec, s[2:3]
	s_cbranch_execz .LBB0_815
	v_mov_b32_e32 v36, v32
	s_and_saveexec_b64 s[20:21], vcc
	s_cbranch_execz .LBB0_814
	v_mov_b32_e32 v61, v133
	v_lshl_add_u64 v[36:37], v[104:105], 0, v[60:61]
	v_mov_b32_e32 v36, v176
	v_add_f32_e32 v36, v32, v36
	v_mul_f32_e32 v36, 0xbfb8aa3b, v36
	v_exp_f32_e32 v36, v36
	s_nop 0
	v_add_f32_e32 v36, 1.0, v36
	v_rcp_f32_e32 v36, v36

; __device__ __forceinline__ float sigmoidf_(float x) { return __builtin_amdgcn_rcpf(1.0f + __expf(-x)); }
; __device__ __forceinline__ void lora_phase(const Ctx& C, const PV& P, int layer, unsigned char* smem) {
;     ...
;                 for (int r = 0; r < 4; ++r) {
;                     float v = acc[i][jn][r];
;                     if (which < 2) {
;                         const float z = bias[n + r] + v;
;                         v = __expf(-0.6065306597126334f * sigmoidf_(z));
;                     } else if (which < 4) { v = sigmoidf_(bias[n + r] + v); }
;                     h[r] = (f16)v;
;                 }
;                 *(f16x4*)(dst + (size_t)lt * 512 + n) = h;
.LBB0_816:
	v_mov_b32_e32 v61, v133
	v_lshl_add_u64 v[36:37], v[104:105], 0, v[60:61]
	v_mov_b32_e32 v36, v176
	v_add_f32_e32 v32, v32, v36
	v_mul_f32_e32 v32, 0xbfb8aa3b, v32
	v_exp_f32_e32 v32, v32
	s_nop 0
	v_add_f32_e32 v32, 1.0, v32
	v_rcp_f32_e32 v32, v32
	s_nop 0
	v_mul_f32_e32 v32, 0xbf1b4598, v32
	v_mul_f32_e32 v32, 0x3fb8aa3b, v32
	v_exp_f32_e32 v36, v32
.LBB0_817:
	s_or_b64 exec, exec, s[2:3]
	s_and_saveexec_b64 s[2:3], s[40:41]
	s_xor_b64 s[2:3], exec, s[2:3]
	s_cbranch_execz .LBB0_821
	v_mov_b32_e32 v32, v33
	s_and_saveexec_b64 s[20:21], vcc
	s_cbranch_execz .LBB0_820
	v_mov_b32_e32 v61, v133
	v_lshl_add_u64 v[38:39], v[104:105], 0, v[60:61]
	v_mov_b32_e32 v32, v177
	v_add_f32_e32 v32, v33, v32
	v_mul_f32_e32 v32, 0xbfb8aa3b, v32
	v_exp_f32_e32 v32, v32
	s_nop 0
	v_add_f32_e32 v32, 1.0, v32
	v_rcp_f32_e32 v32, v32

; __device__ __forceinline__ float sigmoidf_(float x) { return __builtin_amdgcn_rcpf(1.0f + __expf(-x)); }
; __device__ __forceinline__ void lora_phase(const Ctx& C, const PV& P, int layer, unsigned char* smem) {
;     ...
;                 for (int r = 0; r < 4; ++r) {
;                     float v = acc[i][jn][r];
;                     if (which < 2) {
;                         const float z = bias[n + r] + v;
;                         v = __expf(-0.6065306597126334f * sigmoidf_(z));
;                     } else if (which < 4) { v = sigmoidf_(bias[n + r] + v); }
;                     h[r] = (f16)v;
;                 }
;                 *(f16x4*)(dst + (size_t)lt * 512 + n) = h;
.LBB0_822:
	v_mov_b32_e32 v61, v133
	v_lshl_add_u64 v[38:39], v[104:105], 0, v[60:61]
	v_mov_b32_e32 v32, v177
	v_add_f32_e32 v32, v33, v32
	v_mul_f32_e32 v32, 0xbfb8aa3b, v32
	v_exp_f32_e32 v32, v32
	s_nop 0
	v_add_f32_e32 v32, 1.0, v32
	v_rcp_f32_e32 v32, v32
	s_nop 0
	v_mul_f32_e32 v32, 0xbf1b4598, v32
	v_mul_f32_e32 v32, 0x3fb8aa3b, v32
	v_exp_f32_e32 v32, v32
.LBB0_823:
	s_or_b64 exec, exec, s[2:3]
	s_and_saveexec_b64 s[2:3], s[40:41]
	s_xor_b64 s[2:3], exec, s[2:3]
	s_cbranch_execz .LBB0_827
	v_mov_b32_e32 v33, v34
	s_and_saveexec_b64 s[20:21], vcc
	s_cbranch_execz .LBB0_826
	v_mov_b32_e32 v61, v133
	v_lshl_add_u64 v[38:39], v[104:105], 0, v[60:61]
	v_mov_b32_e32 v33, v178
	v_add_f32_e32 v33, v34, v33
	v_mul_f32_e32 v33, 0xbfb8aa3b, v33
	v_exp_f32_e32 v33, v33
	s_nop 0
	v_add_f32_e32 v33, 1.0, v33
	v_rcp_f32_e32 v33, v33

; __device__ __forceinline__ float sigmoidf_(float x) { return __builtin_amdgcn_rcpf(1.0f + __expf(-x)); }
; __device__ __forceinline__ void lora_phase(const Ctx& C, const PV& P, int layer, unsigned char* smem) {
;     ...
;                 for (int r = 0; r < 4; ++r) {
;                     float v = acc[i][jn][r];
;                     if (which < 2) {
;                         const float z = bias[n + r] + v;
;                         v = __expf(-0.6065306597126334f * sigmoidf_(z));
;                     } else if (which < 4) { v = sigmoidf_(bias[n + r] + v); }
;                     h[r] = (f16)v;
;                 }
;                 *(f16x4*)(dst + (size_t)lt * 512 + n) = h;
.LBB0_828:
	v_mov_b32_e32 v61, v133
	v_lshl_add_u64 v[38:39], v[104:105], 0, v[60:61]
	v_mov_b32_e32 v33, v178
	v_add_f32_e32 v33, v34, v33
	v_mul_f32_e32 v33, 0xbfb8aa3b, v33
	v_exp_f32_e32 v33, v33
	s_nop 0
	v_add_f32_e32 v33, 1.0, v33
	v_rcp_f32_e32 v33, v33
	s_nop 0
	v_mul_f32_e32 v33, 0xbf1b4598, v33
	v_mul_f32_e32 v33, 0x3fb8aa3b, v33
	v_exp_f32_e32 v33, v33
.LBB0_829:
	s_or_b64 exec, exec, s[2:3]
	s_and_saveexec_b64 s[2:3], s[40:41]
	s_xor_b64 s[2:3], exec, s[2:3]
	s_cbranch_execz .LBB0_833
	v_mov_b32_e32 v34, v35
	s_and_saveexec_b64 s[20:21], vcc
	s_cbranch_execz .LBB0_832
	v_mov_b32_e32 v61, v133
	v_lshl_add_u64 v[38:39], v[104:105], 0, v[60:61]
	v_mov_b32_e32 v34, v179
	v_add_f32_e32 v34, v35, v34
	v_mul_f32_e32 v34, 0xbfb8aa3b, v34
	v_exp_f32_e32 v34, v34
	s_nop 0
	v_add_f32_e32 v34, 1.0, v34
	v_rcp_f32_e32 v34, v34

; __device__ __forceinline__ float sigmoidf_(float x) { return __builtin_amdgcn_rcpf(1.0f + __expf(-x)); }
; __device__ __forceinline__ void lora_phase(const Ctx& C, const PV& P, int layer, unsigned char* smem) {
;     ...
;                 for (int r = 0; r < 4; ++r) {
;                     float v = acc[i][jn][r];
;                     if (which < 2) {
;                         const float z = bias[n + r] + v;
;                         v = __expf(-0.6065306597126334f * sigmoidf_(z));
;                     } else if (which < 4) { v = sigmoidf_(bias[n + r] + v); }
;                     h[r] = (f16)v;
;                 }
;                 *(f16x4*)(dst + (size_t)lt * 512 + n) = h;
.LBB0_834:
	v_mov_b32_e32 v61, v133
	v_lshl_add_u64 v[38:39], v[104:105], 0, v[60:61]
	v_mov_b32_e32 v34, v179
	v_add_f32_e32 v34, v35, v34
	v_mul_f32_e32 v34, 0xbfb8aa3b, v34
	v_exp_f32_e32 v34, v34
	s_nop 0
	v_add_f32_e32 v34, 1.0, v34
	v_rcp_f32_e32 v34, v34
	s_nop 0
	v_mul_f32_e32 v34, 0xbf1b4598, v34
	v_mul_f32_e32 v34, 0x3fb8aa3b, v34
	v_exp_f32_e32 v34, v34
.LBB0_835:
	s_or_b64 exec, exec, s[2:3]
	v_cvt_pk_f16_f32 v33, v33, v34
	v_cvt_pk_f16_f32 v32, v36, v32
	global_store_dwordx2 v[44:45], v[32:33], off offset:96
	s_and_saveexec_b64 s[2:3], s[40:41]
	s_xor_b64 s[2:3], exec, s[2:3]
	s_cbranch_execz .LBB0_839
	v_mov_b32_e32 v32, v28
	s_and_saveexec_b64 s[20:21], vcc
	s_cbranch_execz .LBB0_838
	v_mov_b32_e32 v61, v133
	v_lshl_add_u64 v[32:33], v[104:105], 0, v[60:61]
	v_mov_b32_e32 v32, v164
	v_add_f32_e32 v32, v28, v32
	v_mul_f32_e32 v32, 0xbfb8aa3b, v32
	v_exp_f32_e32 v32, v32
	s_nop 0
	v_add_f32_e32 v32, 1.0, v32
	v_rcp_f32_e32 v32, v32

; __device__ __forceinline__ float sigmoidf_(float x) { return __builtin_amdgcn_rcpf(1.0f + __expf(-x)); }
; __device__ __forceinline__ void lora_phase(const Ctx& C, const PV& P, int layer, unsigned char* smem) {
;     ...
;                 for (int r = 0; r < 4; ++r) {
;                     float v = acc[i][jn][r];
;                     if (which < 2) {
;                         const float z = bias[n + r] + v;
;                         v = __expf(-0.6065306597126334f * sigmoidf_(z));
;                     } else if (which < 4) { v = sigmoidf_(bias[n + r] + v); }
;                     h[r] = (f16)v;
;                 }
;                 *(f16x4*)(dst + (size_t)lt * 512 + n) = h;
.LBB0_840:
	v_mov_b32_e32 v61, v133
	v_lshl_add_u64 v[32:33], v[104:105], 0, v[60:61]
	v_mov_b32_e32 v32, v164
	v_add_f32_e32 v28, v28, v32
	v_mul_f32_e32 v28, 0xbfb8aa3b, v28
	v_exp_f32_e32 v28, v28
	s_nop 0
	v_add_f32_e32 v28, 1.0, v28
	v_rcp_f32_e32 v28, v28
	s_nop 0
	v_mul_f32_e32 v28, 0xbf1b4598, v28
	v_mul_f32_e32 v28, 0x3fb8aa3b, v28
	v_exp_f32_e32 v32, v28
.LBB0_841:
	s_or_b64 exec, exec, s[2:3]
	s_and_saveexec_b64 s[2:3], s[40:41]
	s_xor_b64 s[2:3], exec, s[2:3]
	s_cbranch_execz .LBB0_845
	v_mov_b32_e32 v28, v29
	s_and_saveexec_b64 s[20:21], vcc
	s_cbranch_execz .LBB0_844
	v_mov_b32_e32 v61, v133
	v_lshl_add_u64 v[34:35], v[104:105], 0, v[60:61]
	v_mov_b32_e32 v28, v165
	v_add_f32_e32 v28, v29, v28
	v_mul_f32_e32 v28, 0xbfb8aa3b, v28
	v_exp_f32_e32 v28, v28
	s_nop 0
	v_add_f32_e32 v28, 1.0, v28
	v_rcp_f32_e32 v28, v28

; __device__ __forceinline__ float sigmoidf_(float x) { return __builtin_amdgcn_rcpf(1.0f + __expf(-x)); }
; __device__ __forceinline__ void lora_phase(const Ctx& C, const PV& P, int layer, unsigned char* smem) {
;     ...
;                 for (int r = 0; r < 4; ++r) {
;                     float v = acc[i][jn][r];
;                     if (which < 2) {
;                         const float z = bias[n + r] + v;
;                         v = __expf(-0.6065306597126334f * sigmoidf_(z));
;                     } else if (which < 4) { v = sigmoidf_(bias[n + r] + v); }
;                     h[r] = (f16)v;
;                 }
;                 *(f16x4*)(dst + (size_t)lt * 512 + n) = h;
.LBB0_846:
	v_mov_b32_e32 v61, v133
	v_lshl_add_u64 v[34:35], v[104:105], 0, v[60:61]
	v_mov_b32_e32 v28, v165
	v_add_f32_e32 v28, v29, v28
	v_mul_f32_e32 v28, 0xbfb8aa3b, v28
	v_exp_f32_e32 v28, v28
	s_nop 0
	v_add_f32_e32 v28, 1.0, v28
	v_rcp_f32_e32 v28, v28
	s_nop 0
	v_mul_f32_e32 v28, 0xbf1b4598, v28
	v_mul_f32_e32 v28, 0x3fb8aa3b, v28
	v_exp_f32_e32 v28, v28
.LBB0_847:
	s_or_b64 exec, exec, s[2:3]
	s_and_saveexec_b64 s[2:3], s[40:41]
	s_xor_b64 s[2:3], exec, s[2:3]
	s_cbranch_execz .LBB0_851
	v_mov_b32_e32 v29, v30
	s_and_saveexec_b64 s[20:21], vcc
	s_cbranch_execz .LBB0_850
	v_mov_b32_e32 v61, v133
	v_lshl_add_u64 v[34:35], v[104:105], 0, v[60:61]
	v_mov_b32_e32 v29, v166
	v_add_f32_e32 v29, v30, v29
	v_mul_f32_e32 v29, 0xbfb8aa3b, v29
	v_exp_f32_e32 v29, v29
	s_nop 0
	v_add_f32_e32 v29, 1.0, v29
	v_rcp_f32_e32 v29, v29

; __device__ __forceinline__ float sigmoidf_(float x) { return __builtin_amdgcn_rcpf(1.0f + __expf(-x)); }
; __device__ __forceinline__ void lora_phase(const Ctx& C, const PV& P, int layer, unsigned char* smem) {
;     ...
;                 for (int r = 0; r < 4; ++r) {
;                     float v = acc[i][jn][r];
;                     if (which < 2) {
;                         const float z = bias[n + r] + v;
;                         v = __expf(-0.6065306597126334f * sigmoidf_(z));
;                     } else if (which < 4) { v = sigmoidf_(bias[n + r] + v); }
;                     h[r] = (f16)v;
;                 }
;                 *(f16x4*)(dst + (size_t)lt * 512 + n) = h;
.LBB0_852:
	v_mov_b32_e32 v61, v133
	v_lshl_add_u64 v[34:35], v[104:105], 0, v[60:61]
	v_mov_b32_e32 v29, v166
	v_add_f32_e32 v29, v30, v29
	v_mul_f32_e32 v29, 0xbfb8aa3b, v29
	v_exp_f32_e32 v29, v29
	s_nop 0
	v_add_f32_e32 v29, 1.0, v29
	v_rcp_f32_e32 v29, v29
	s_nop 0
	v_mul_f32_e32 v29, 0xbf1b4598, v29
	v_mul_f32_e32 v29, 0x3fb8aa3b, v29
	v_exp_f32_e32 v29, v29
.LBB0_853:
	s_or_b64 exec, exec, s[2:3]
	s_and_saveexec_b64 s[2:3], s[40:41]
	s_xor_b64 s[2:3], exec, s[2:3]
	s_cbranch_execz .LBB0_857
	v_mov_b32_e32 v30, v31
	s_and_saveexec_b64 s[20:21], vcc
	s_cbranch_execz .LBB0_856
	v_mov_b32_e32 v61, v133
	v_lshl_add_u64 v[34:35], v[104:105], 0, v[60:61]
	v_mov_b32_e32 v30, v167
	v_add_f32_e32 v30, v31, v30
	v_mul_f32_e32 v30, 0xbfb8aa3b, v30
	v_exp_f32_e32 v30, v30
	s_nop 0
	v_add_f32_e32 v30, 1.0, v30
	v_rcp_f32_e32 v30, v30

; __device__ __forceinline__ float sigmoidf_(float x) { return __builtin_amdgcn_rcpf(1.0f + __expf(-x)); }
; __device__ __forceinline__ void lora_phase(const Ctx& C, const PV& P, int layer, unsigned char* smem) {
;     ...
;                 for (int r = 0; r < 4; ++r) {
;                     float v = acc[i][jn][r];
;                     if (which < 2) {
;                         const float z = bias[n + r] + v;
;                         v = __expf(-0.6065306597126334f * sigmoidf_(z));
;                     } else if (which < 4) { v = sigmoidf_(bias[n + r] + v); }
;                     h[r] = (f16)v;
;                 }
;                 *(f16x4*)(dst + (size_t)lt * 512 + n) = h;
.LBB0_858:
	v_mov_b32_e32 v61, v133
	v_lshl_add_u64 v[34:35], v[104:105], 0, v[60:61]
	v_mov_b32_e32 v30, v167
	v_add_f32_e32 v30, v31, v30
	v_mul_f32_e32 v30, 0xbfb8aa3b, v30
	v_exp_f32_e32 v30, v30
	s_nop 0
	v_add_f32_e32 v30, 1.0, v30
	v_rcp_f32_e32 v30, v30
	s_nop 0
	v_mul_f32_e32 v30, 0xbf1b4598, v30
	v_mul_f32_e32 v30, 0x3fb8aa3b, v30
	v_exp_f32_e32 v30, v30
.LBB0_859:
	s_or_b64 exec, exec, s[2:3]
	v_or_b32_e32 v34, 32, v62
	v_ashrrev_i32_e32 v35, 31, v34
	v_lshlrev_b64 v[34:35], 10, v[34:35]
	v_lshl_add_u64 v[34:35], v[106:107], 0, v[34:35]
	v_cvt_pk_f16_f32 v31, v29, v30
	v_cvt_pk_f16_f32 v30, v32, v28
	v_lshl_add_u64 v[28:29], v[34:35], 0, v[132:133]
	global_store_dwordx2 v[28:29], v[30:31], off
	s_and_saveexec_b64 s[2:3], s[40:41]
	s_xor_b64 s[2:3], exec, s[2:3]
	s_cbranch_execz .LBB0_863
	v_mov_b32_e32 v30, v24
	s_and_saveexec_b64 s[20:21], vcc
	s_cbranch_execz .LBB0_862
	v_mov_b32_e32 v61, v133
	v_lshl_add_u64 v[30:31], v[104:105], 0, v[60:61]
	v_mov_b32_e32 v30, v168
	v_add_f32_e32 v30, v24, v30
	v_mul_f32_e32 v30, 0xbfb8aa3b, v30
	v_exp_f32_e32 v30, v30
	s_nop 0
	v_add_f32_e32 v30, 1.0, v30
	v_rcp_f32_e32 v30, v30

; __device__ __forceinline__ float sigmoidf_(float x) { return __builtin_amdgcn_rcpf(1.0f + __expf(-x)); }
; __device__ __forceinline__ void lora_phase(const Ctx& C, const PV& P, int layer, unsigned char* smem) {
;     ...
;                 for (int r = 0; r < 4; ++r) {
;                     float v = acc[i][jn][r];
;                     if (which < 2) {
;                         const float z = bias[n + r] + v;
;                         v = __expf(-0.6065306597126334f * sigmoidf_(z));
;                     } else if (which < 4) { v = sigmoidf_(bias[n + r] + v); }
;                     h[r] = (f16)v;
;                 }
;                 *(f16x4*)(dst + (size_t)lt * 512 + n) = h;
.LBB0_864:
	v_mov_b32_e32 v61, v133
	v_lshl_add_u64 v[30:31], v[104:105], 0, v[60:61]
	v_mov_b32_e32 v30, v168
	v_add_f32_e32 v24, v24, v30
	v_mul_f32_e32 v24, 0xbfb8aa3b, v24
	v_exp_f32_e32 v24, v24
	s_nop 0
	v_add_f32_e32 v24, 1.0, v24
	v_rcp_f32_e32 v24, v24
	s_nop 0
	v_mul_f32_e32 v24, 0xbf1b4598, v24
	v_mul_f32_e32 v24, 0x3fb8aa3b, v24
	v_exp_f32_e32 v30, v24
.LBB0_865:
	s_or_b64 exec, exec, s[2:3]
	s_and_saveexec_b64 s[2:3], s[40:41]
	s_xor_b64 s[2:3], exec, s[2:3]
	s_cbranch_execz .LBB0_869
	v_mov_b32_e32 v24, v25
	s_and_saveexec_b64 s[20:21], vcc
	s_cbranch_execz .LBB0_868
	v_mov_b32_e32 v61, v133
	v_lshl_add_u64 v[32:33], v[104:105], 0, v[60:61]
	v_mov_b32_e32 v24, v169
	v_add_f32_e32 v24, v25, v24
	v_mul_f32_e32 v24, 0xbfb8aa3b, v24
	v_exp_f32_e32 v24, v24
	s_nop 0
	v_add_f32_e32 v24, 1.0, v24
	v_rcp_f32_e32 v24, v24

; __device__ __forceinline__ float sigmoidf_(float x) { return __builtin_amdgcn_rcpf(1.0f + __expf(-x)); }
; __device__ __forceinline__ void lora_phase(const Ctx& C, const PV& P, int layer, unsigned char* smem) {
;     ...
;                 for (int r = 0; r < 4; ++r) {
;                     float v = acc[i][jn][r];
;                     if (which < 2) {
;                         const float z = bias[n + r] + v;
;                         v = __expf(-0.6065306597126334f * sigmoidf_(z));
;                     } else if (which < 4) { v = sigmoidf_(bias[n + r] + v); }
;                     h[r] = (f16)v;
;                 }
;                 *(f16x4*)(dst + (size_t)lt * 512 + n) = h;
.LBB0_870:
	v_mov_b32_e32 v61, v133
	v_lshl_add_u64 v[32:33], v[104:105], 0, v[60:61]
	v_mov_b32_e32 v24, v169
	v_add_f32_e32 v24, v25, v24
	v_mul_f32_e32 v24, 0xbfb8aa3b, v24
	v_exp_f32_e32 v24, v24
	s_nop 0
	v_add_f32_e32 v24, 1.0, v24
	v_rcp_f32_e32 v24, v24
	s_nop 0
	v_mul_f32_e32 v24, 0xbf1b4598, v24
	v_mul_f32_e32 v24, 0x3fb8aa3b, v24
	v_exp_f32_e32 v24, v24
.LBB0_871:
	s_or_b64 exec, exec, s[2:3]
	s_and_saveexec_b64 s[2:3], s[40:41]
	s_xor_b64 s[2:3], exec, s[2:3]
	s_cbranch_execz .LBB0_875
	v_mov_b32_e32 v25, v26
	s_and_saveexec_b64 s[20:21], vcc
	s_cbranch_execz .LBB0_874
	v_mov_b32_e32 v61, v133
	v_lshl_add_u64 v[32:33], v[104:105], 0, v[60:61]
	v_mov_b32_e32 v25, v170
	v_add_f32_e32 v25, v26, v25
	v_mul_f32_e32 v25, 0xbfb8aa3b, v25
	v_exp_f32_e32 v25, v25
	s_nop 0
	v_add_f32_e32 v25, 1.0, v25
	v_rcp_f32_e32 v25, v25

; __device__ __forceinline__ float sigmoidf_(float x) { return __builtin_amdgcn_rcpf(1.0f + __expf(-x)); }
; __device__ __forceinline__ void lora_phase(const Ctx& C, const PV& P, int layer, unsigned char* smem) {
;     ...
;                 for (int r = 0; r < 4; ++r) {
;                     float v = acc[i][jn][r];
;                     if (which < 2) {
;                         const float z = bias[n + r] + v;
;                         v = __expf(-0.6065306597126334f * sigmoidf_(z));
;                     } else if (which < 4) { v = sigmoidf_(bias[n + r] + v); }
;                     h[r] = (f16)v;
;                 }
;                 *(f16x4*)(dst + (size_t)lt * 512 + n) = h;
.LBB0_876:
	v_mov_b32_e32 v61, v133
	v_lshl_add_u64 v[32:33], v[104:105], 0, v[60:61]
	v_mov_b32_e32 v25, v170
	v_add_f32_e32 v25, v26, v25
	v_mul_f32_e32 v25, 0xbfb8aa3b, v25
	v_exp_f32_e32 v25, v25
	s_nop 0
	v_add_f32_e32 v25, 1.0, v25
	v_rcp_f32_e32 v25, v25
	s_nop 0
	v_mul_f32_e32 v25, 0xbf1b4598, v25
	v_mul_f32_e32 v25, 0x3fb8aa3b, v25
	v_exp_f32_e32 v25, v25
.LBB0_877:
	s_or_b64 exec, exec, s[2:3]
	s_and_saveexec_b64 s[2:3], s[40:41]
	s_xor_b64 s[2:3], exec, s[2:3]
	s_cbranch_execz .LBB0_881
	v_mov_b32_e32 v26, v27
	s_and_saveexec_b64 s[20:21], vcc
	s_cbranch_execz .LBB0_880
	v_mov_b32_e32 v61, v133
	v_lshl_add_u64 v[32:33], v[104:105], 0, v[60:61]
	v_mov_b32_e32 v26, v171
	v_add_f32_e32 v26, v27, v26
	v_mul_f32_e32 v26, 0xbfb8aa3b, v26
	v_exp_f32_e32 v26, v26
	s_nop 0
	v_add_f32_e32 v26, 1.0, v26
	v_rcp_f32_e32 v26, v26

; __device__ __forceinline__ float sigmoidf_(float x) { return __builtin_amdgcn_rcpf(1.0f + __expf(-x)); }
; __device__ __forceinline__ void lora_phase(const Ctx& C, const PV& P, int layer, unsigned char* smem) {
;     ...
;                 for (int r = 0; r < 4; ++r) {
;                     float v = acc[i][jn][r];
;                     if (which < 2) {
;                         const float z = bias[n + r] + v;
;                         v = __expf(-0.6065306597126334f * sigmoidf_(z));
;                     } else if (which < 4) { v = sigmoidf_(bias[n + r] + v); }
;                     h[r] = (f16)v;
;                 }
;                 *(f16x4*)(dst + (size_t)lt * 512 + n) = h;
.LBB0_882:
	v_mov_b32_e32 v61, v133
	v_lshl_add_u64 v[32:33], v[104:105], 0, v[60:61]
	v_mov_b32_e32 v26, v171
	v_add_f32_e32 v26, v27, v26
	v_mul_f32_e32 v26, 0xbfb8aa3b, v26
	v_exp_f32_e32 v26, v26
	s_nop 0
	v_add_f32_e32 v26, 1.0, v26
	v_rcp_f32_e32 v26, v26
	s_nop 0
	v_mul_f32_e32 v26, 0xbf1b4598, v26
	v_mul_f32_e32 v26, 0x3fb8aa3b, v26
	v_exp_f32_e32 v26, v26
.LBB0_883:
	s_or_b64 exec, exec, s[2:3]
	v_cvt_pk_f16_f32 v25, v25, v26
	v_cvt_pk_f16_f32 v24, v30, v24
	global_store_dwordx2 v[28:29], v[24:25], off offset:32
	s_and_saveexec_b64 s[2:3], s[40:41]
	s_xor_b64 s[2:3], exec, s[2:3]
	s_cbranch_execz .LBB0_887
	v_mov_b32_e32 v24, v20
	s_and_saveexec_b64 s[20:21], vcc
	s_cbranch_execz .LBB0_886
	v_mov_b32_e32 v61, v133
	v_lshl_add_u64 v[24:25], v[104:105], 0, v[60:61]
	v_mov_b32_e32 v24, v172
	v_add_f32_e32 v24, v20, v24
	v_mul_f32_e32 v24, 0xbfb8aa3b, v24
	v_exp_f32_e32 v24, v24
	s_nop 0
	v_add_f32_e32 v24, 1.0, v24
	v_rcp_f32_e32 v24, v24

; __device__ __forceinline__ float sigmoidf_(float x) { return __builtin_amdgcn_rcpf(1.0f + __expf(-x)); }
; __device__ __forceinline__ void lora_phase(const Ctx& C, const PV& P, int layer, unsigned char* smem) {
;     ...
;                 for (int r = 0; r < 4; ++r) {
;                     float v = acc[i][jn][r];
;                     if (which < 2) {
;                         const float z = bias[n + r] + v;
;                         v = __expf(-0.6065306597126334f * sigmoidf_(z));
;                     } else if (which < 4) { v = sigmoidf_(bias[n + r] + v); }
;                     h[r] = (f16)v;
;                 }
;                 *(f16x4*)(dst + (size_t)lt * 512 + n) = h;
.LBB0_888:
	v_mov_b32_e32 v61, v133
	v_lshl_add_u64 v[24:25], v[104:105], 0, v[60:61]
	v_mov_b32_e32 v24, v172
	v_add_f32_e32 v20, v20, v24
	v_mul_f32_e32 v20, 0xbfb8aa3b, v20
	v_exp_f32_e32 v20, v20
	s_nop 0
	v_add_f32_e32 v20, 1.0, v20
	v_rcp_f32_e32 v20, v20
	s_nop 0
	v_mul_f32_e32 v20, 0xbf1b4598, v20
	v_mul_f32_e32 v20, 0x3fb8aa3b, v20
	v_exp_f32_e32 v24, v20
.LBB0_889:
	s_or_b64 exec, exec, s[2:3]
	s_and_saveexec_b64 s[2:3], s[40:41]
	s_xor_b64 s[2:3], exec, s[2:3]
	s_cbranch_execz .LBB0_893
	v_mov_b32_e32 v20, v21
	s_and_saveexec_b64 s[20:21], vcc
	s_cbranch_execz .LBB0_892
	v_mov_b32_e32 v61, v133
	v_lshl_add_u64 v[26:27], v[104:105], 0, v[60:61]
	v_mov_b32_e32 v20, v173
	v_add_f32_e32 v20, v21, v20
	v_mul_f32_e32 v20, 0xbfb8aa3b, v20
	v_exp_f32_e32 v20, v20
	s_nop 0
	v_add_f32_e32 v20, 1.0, v20
	v_rcp_f32_e32 v20, v20

; __device__ __forceinline__ float sigmoidf_(float x) { return __builtin_amdgcn_rcpf(1.0f + __expf(-x)); }
; __device__ __forceinline__ void lora_phase(const Ctx& C, const PV& P, int layer, unsigned char* smem) {
;     ...
;                 for (int r = 0; r < 4; ++r) {
;                     float v = acc[i][jn][r];
;                     if (which < 2) {
;                         const float z = bias[n + r] + v;
;                         v = __expf(-0.6065306597126334f * sigmoidf_(z));
;                     } else if (which < 4) { v = sigmoidf_(bias[n + r] + v); }
;                     h[r] = (f16)v;
;                 }
;                 *(f16x4*)(dst + (size_t)lt * 512 + n) = h;
.LBB0_894:
	v_mov_b32_e32 v61, v133
	v_lshl_add_u64 v[26:27], v[104:105], 0, v[60:61]
	v_mov_b32_e32 v20, v173
	v_add_f32_e32 v20, v21, v20
	v_mul_f32_e32 v20, 0xbfb8aa3b, v20
	v_exp_f32_e32 v20, v20
	s_nop 0
	v_add_f32_e32 v20, 1.0, v20
	v_rcp_f32_e32 v20, v20
	s_nop 0
	v_mul_f32_e32 v20, 0xbf1b4598, v20
	v_mul_f32_e32 v20, 0x3fb8aa3b, v20
	v_exp_f32_e32 v20, v20
.LBB0_895:
	s_or_b64 exec, exec, s[2:3]
	s_and_saveexec_b64 s[2:3], s[40:41]
	s_xor_b64 s[2:3], exec, s[2:3]
	s_cbranch_execz .LBB0_899
	v_mov_b32_e32 v21, v22
	s_and_saveexec_b64 s[20:21], vcc
	s_cbranch_execz .LBB0_898
	v_mov_b32_e32 v61, v133
	v_lshl_add_u64 v[26:27], v[104:105], 0, v[60:61]
	v_mov_b32_e32 v21, v174
	v_add_f32_e32 v21, v22, v21
	v_mul_f32_e32 v21, 0xbfb8aa3b, v21
	v_exp_f32_e32 v21, v21
	s_nop 0
	v_add_f32_e32 v21, 1.0, v21
	v_rcp_f32_e32 v21, v21

; __device__ __forceinline__ float sigmoidf_(float x) { return __builtin_amdgcn_rcpf(1.0f + __expf(-x)); }
; __device__ __forceinline__ void lora_phase(const Ctx& C, const PV& P, int layer, unsigned char* smem) {
;     ...
;                 for (int r = 0; r < 4; ++r) {
;                     float v = acc[i][jn][r];
;                     if (which < 2) {
;                         const float z = bias[n + r] + v;
;                         v = __expf(-0.6065306597126334f * sigmoidf_(z));
;                     } else if (which < 4) { v = sigmoidf_(bias[n + r] + v); }
;                     h[r] = (f16)v;
;                 }
;                 *(f16x4*)(dst + (size_t)lt * 512 + n) = h;
.LBB0_900:
	v_mov_b32_e32 v61, v133
	v_lshl_add_u64 v[26:27], v[104:105], 0, v[60:61]
	v_mov_b32_e32 v21, v174
	v_add_f32_e32 v21, v22, v21
	v_mul_f32_e32 v21, 0xbfb8aa3b, v21
	v_exp_f32_e32 v21, v21
	s_nop 0
	v_add_f32_e32 v21, 1.0, v21
	v_rcp_f32_e32 v21, v21
	s_nop 0
	v_mul_f32_e32 v21, 0xbf1b4598, v21
	v_mul_f32_e32 v21, 0x3fb8aa3b, v21
	v_exp_f32_e32 v21, v21
.LBB0_901:
	s_or_b64 exec, exec, s[2:3]
	s_and_saveexec_b64 s[2:3], s[40:41]
	s_xor_b64 s[2:3], exec, s[2:3]
	s_cbranch_execz .LBB0_905
	v_mov_b32_e32 v22, v23
	s_and_saveexec_b64 s[20:21], vcc
	s_cbranch_execz .LBB0_904
	v_mov_b32_e32 v61, v133
	v_lshl_add_u64 v[26:27], v[104:105], 0, v[60:61]
	v_mov_b32_e32 v22, v175
	v_add_f32_e32 v22, v23, v22
	v_mul_f32_e32 v22, 0xbfb8aa3b, v22
	v_exp_f32_e32 v22, v22
	s_nop 0
	v_add_f32_e32 v22, 1.0, v22
	v_rcp_f32_e32 v22, v22

; __device__ __forceinline__ float sigmoidf_(float x) { return __builtin_amdgcn_rcpf(1.0f + __expf(-x)); }
; __device__ __forceinline__ void lora_phase(const Ctx& C, const PV& P, int layer, unsigned char* smem) {
;     ...
;                 for (int r = 0; r < 4; ++r) {
;                     float v = acc[i][jn][r];
;                     if (which < 2) {
;                         const float z = bias[n + r] + v;
;                         v = __expf(-0.6065306597126334f * sigmoidf_(z));
;                     } else if (which < 4) { v = sigmoidf_(bias[n + r] + v); }
;                     h[r] = (f16)v;
;                 }
;                 *(f16x4*)(dst + (size_t)lt * 512 + n) = h;
.LBB0_906:
	v_mov_b32_e32 v61, v133
	v_lshl_add_u64 v[26:27], v[104:105], 0, v[60:61]
	v_mov_b32_e32 v22, v175
	v_add_f32_e32 v22, v23, v22
	v_mul_f32_e32 v22, 0xbfb8aa3b, v22
	v_exp_f32_e32 v22, v22
	s_nop 0
	v_add_f32_e32 v22, 1.0, v22
	v_rcp_f32_e32 v22, v22
	s_nop 0
	v_mul_f32_e32 v22, 0xbf1b4598, v22
	v_mul_f32_e32 v22, 0x3fb8aa3b, v22
	v_exp_f32_e32 v22, v22
.LBB0_907:
	s_or_b64 exec, exec, s[2:3]
	v_cvt_pk_f16_f32 v21, v21, v22
	v_cvt_pk_f16_f32 v20, v24, v20
	global_store_dwordx2 v[28:29], v[20:21], off offset:64
	s_and_saveexec_b64 s[2:3], s[40:41]
	s_xor_b64 s[2:3], exec, s[2:3]
	s_cbranch_execz .LBB0_911
	v_mov_b32_e32 v20, v16
	s_and_saveexec_b64 s[20:21], vcc
	s_cbranch_execz .LBB0_910
	v_mov_b32_e32 v61, v133
	v_lshl_add_u64 v[20:21], v[104:105], 0, v[60:61]
	v_mov_b32_e32 v20, v176
	v_add_f32_e32 v20, v16, v20
	v_mul_f32_e32 v20, 0xbfb8aa3b, v20
	v_exp_f32_e32 v20, v20
	s_nop 0
	v_add_f32_e32 v20, 1.0, v20
	v_rcp_f32_e32 v20, v20

; __device__ __forceinline__ float sigmoidf_(float x) { return __builtin_amdgcn_rcpf(1.0f + __expf(-x)); }
; __device__ __forceinline__ void lora_phase(const Ctx& C, const PV& P, int layer, unsigned char* smem) {
;     ...
;                 for (int r = 0; r < 4; ++r) {
;                     float v = acc[i][jn][r];
;                     if (which < 2) {
;                         const float z = bias[n + r] + v;
;                         v = __expf(-0.6065306597126334f * sigmoidf_(z));
;                     } else if (which < 4) { v = sigmoidf_(bias[n + r] + v); }
;                     h[r] = (f16)v;
;                 }
;                 *(f16x4*)(dst + (size_t)lt * 512 + n) = h;
.LBB0_912:
	v_mov_b32_e32 v61, v133
	v_lshl_add_u64 v[20:21], v[104:105], 0, v[60:61]
	v_mov_b32_e32 v20, v176
	v_add_f32_e32 v16, v16, v20
	v_mul_f32_e32 v16, 0xbfb8aa3b, v16
	v_exp_f32_e32 v16, v16
	s_nop 0
	v_add_f32_e32 v16, 1.0, v16
	v_rcp_f32_e32 v16, v16
	s_nop 0
	v_mul_f32_e32 v16, 0xbf1b4598, v16
	v_mul_f32_e32 v16, 0x3fb8aa3b, v16
	v_exp_f32_e32 v20, v16
.LBB0_913:
	s_or_b64 exec, exec, s[2:3]
	s_and_saveexec_b64 s[2:3], s[40:41]
	s_xor_b64 s[2:3], exec, s[2:3]
	s_cbranch_execz .LBB0_917
	v_mov_b32_e32 v16, v17
	s_and_saveexec_b64 s[20:21], vcc
	s_cbranch_execz .LBB0_916
	v_mov_b32_e32 v61, v133
	v_lshl_add_u64 v[22:23], v[104:105], 0, v[60:61]
	v_mov_b32_e32 v16, v177
	v_add_f32_e32 v16, v17, v16
	v_mul_f32_e32 v16, 0xbfb8aa3b, v16
	v_exp_f32_e32 v16, v16
	s_nop 0
	v_add_f32_e32 v16, 1.0, v16
	v_rcp_f32_e32 v16, v16

; __device__ __forceinline__ float sigmoidf_(float x) { return __builtin_amdgcn_rcpf(1.0f + __expf(-x)); }
; __device__ __forceinline__ void lora_phase(const Ctx& C, const PV& P, int layer, unsigned char* smem) {
;     ...
;                 for (int r = 0; r < 4; ++r) {
;                     float v = acc[i][jn][r];
;                     if (which < 2) {
;                         const float z = bias[n + r] + v;
;                         v = __expf(-0.6065306597126334f * sigmoidf_(z));
;                     } else if (which < 4) { v = sigmoidf_(bias[n + r] + v); }
;                     h[r] = (f16)v;
;                 }
;                 *(f16x4*)(dst + (size_t)lt * 512 + n) = h;
.LBB0_918:
	v_mov_b32_e32 v61, v133
	v_lshl_add_u64 v[22:23], v[104:105], 0, v[60:61]
	v_mov_b32_e32 v16, v177
	v_add_f32_e32 v16, v17, v16
	v_mul_f32_e32 v16, 0xbfb8aa3b, v16
	v_exp_f32_e32 v16, v16
	s_nop 0
	v_add_f32_e32 v16, 1.0, v16
	v_rcp_f32_e32 v16, v16
	s_nop 0
	v_mul_f32_e32 v16, 0xbf1b4598, v16
	v_mul_f32_e32 v16, 0x3fb8aa3b, v16
	v_exp_f32_e32 v16, v16
.LBB0_919:
	s_or_b64 exec, exec, s[2:3]
	s_and_saveexec_b64 s[2:3], s[40:41]
	s_xor_b64 s[2:3], exec, s[2:3]
	s_cbranch_execz .LBB0_923
	v_mov_b32_e32 v17, v18
	s_and_saveexec_b64 s[20:21], vcc
	s_cbranch_execz .LBB0_922
	v_mov_b32_e32 v61, v133
	v_lshl_add_u64 v[22:23], v[104:105], 0, v[60:61]
	v_mov_b32_e32 v17, v178
	v_add_f32_e32 v17, v18, v17
	v_mul_f32_e32 v17, 0xbfb8aa3b, v17
	v_exp_f32_e32 v17, v17
	s_nop 0
	v_add_f32_e32 v17, 1.0, v17
	v_rcp_f32_e32 v17, v17

; __device__ __forceinline__ float sigmoidf_(float x) { return __builtin_amdgcn_rcpf(1.0f + __expf(-x)); }
; __device__ __forceinline__ void lora_phase(const Ctx& C, const PV& P, int layer, unsigned char* smem) {
;     ...
;                 for (int r = 0; r < 4; ++r) {
;                     float v = acc[i][jn][r];
;                     if (which < 2) {
;                         const float z = bias[n + r] + v;
;                         v = __expf(-0.6065306597126334f * sigmoidf_(z));
;                     } else if (which < 4) { v = sigmoidf_(bias[n + r] + v); }
;                     h[r] = (f16)v;
;                 }
;                 *(f16x4*)(dst + (size_t)lt * 512 + n) = h;
.LBB0_924:
	v_mov_b32_e32 v61, v133
	v_lshl_add_u64 v[22:23], v[104:105], 0, v[60:61]
	v_mov_b32_e32 v17, v178
	v_add_f32_e32 v17, v18, v17
	v_mul_f32_e32 v17, 0xbfb8aa3b, v17
	v_exp_f32_e32 v17, v17
	s_nop 0
	v_add_f32_e32 v17, 1.0, v17
	v_rcp_f32_e32 v17, v17
	s_nop 0
	v_mul_f32_e32 v17, 0xbf1b4598, v17
	v_mul_f32_e32 v17, 0x3fb8aa3b, v17
	v_exp_f32_e32 v17, v17
.LBB0_925:
	s_or_b64 exec, exec, s[2:3]
	s_and_saveexec_b64 s[2:3], s[40:41]
	s_xor_b64 s[2:3], exec, s[2:3]
	s_cbranch_execz .LBB0_929
	v_mov_b32_e32 v18, v19
	s_and_saveexec_b64 s[20:21], vcc
	s_cbranch_execz .LBB0_928
	v_mov_b32_e32 v61, v133
	v_lshl_add_u64 v[22:23], v[104:105], 0, v[60:61]
	v_mov_b32_e32 v18, v179
	v_add_f32_e32 v18, v19, v18
	v_mul_f32_e32 v18, 0xbfb8aa3b, v18
	v_exp_f32_e32 v18, v18
	s_nop 0
	v_add_f32_e32 v18, 1.0, v18
	v_rcp_f32_e32 v18, v18

; __device__ __forceinline__ float sigmoidf_(float x) { return __builtin_amdgcn_rcpf(1.0f + __expf(-x)); }
; __device__ __forceinline__ void lora_phase(const Ctx& C, const PV& P, int layer, unsigned char* smem) {
;     ...
;                 for (int r = 0; r < 4; ++r) {
;                     float v = acc[i][jn][r];
;                     if (which < 2) {
;                         const float z = bias[n + r] + v;
;                         v = __expf(-0.6065306597126334f * sigmoidf_(z));
;                     } else if (which < 4) { v = sigmoidf_(bias[n + r] + v); }
;                     h[r] = (f16)v;
;                 }
;                 *(f16x4*)(dst + (size_t)lt * 512 + n) = h;
.LBB0_930:
	v_mov_b32_e32 v61, v133
	v_lshl_add_u64 v[22:23], v[104:105], 0, v[60:61]
	v_mov_b32_e32 v18, v179
	v_add_f32_e32 v18, v19, v18
	v_mul_f32_e32 v18, 0xbfb8aa3b, v18
	v_exp_f32_e32 v18, v18
	s_nop 0
	v_add_f32_e32 v18, 1.0, v18
	v_rcp_f32_e32 v18, v18
	s_nop 0
	v_mul_f32_e32 v18, 0xbf1b4598, v18
	v_mul_f32_e32 v18, 0x3fb8aa3b, v18
	v_exp_f32_e32 v18, v18
.LBB0_931:
	s_or_b64 exec, exec, s[2:3]
	v_cvt_pk_f16_f32 v17, v17, v18
	v_cvt_pk_f16_f32 v16, v20, v16
	global_store_dwordx2 v[28:29], v[16:17], off offset:96
	s_and_saveexec_b64 s[2:3], s[40:41]
	s_xor_b64 s[2:3], exec, s[2:3]
	s_cbranch_execz .LBB0_935
	v_mov_b32_e32 v16, v12
	s_and_saveexec_b64 s[20:21], vcc
	s_cbranch_execz .LBB0_934
	v_mov_b32_e32 v61, v133
	v_lshl_add_u64 v[16:17], v[104:105], 0, v[60:61]
	v_mov_b32_e32 v16, v164
	v_add_f32_e32 v16, v12, v16
	v_mul_f32_e32 v16, 0xbfb8aa3b, v16
	v_exp_f32_e32 v16, v16
	s_nop 0
	v_add_f32_e32 v16, 1.0, v16
	v_rcp_f32_e32 v16, v16

; __device__ __forceinline__ float sigmoidf_(float x) { return __builtin_amdgcn_rcpf(1.0f + __expf(-x)); }
; __device__ __forceinline__ void lora_phase(const Ctx& C, const PV& P, int layer, unsigned char* smem) {
;     ...
;                 for (int r = 0; r < 4; ++r) {
;                     float v = acc[i][jn][r];
;                     if (which < 2) {
;                         const float z = bias[n + r] + v;
;                         v = __expf(-0.6065306597126334f * sigmoidf_(z));
;                     } else if (which < 4) { v = sigmoidf_(bias[n + r] + v); }
;                     h[r] = (f16)v;
;                 }
;                 *(f16x4*)(dst + (size_t)lt * 512 + n) = h;
.LBB0_936:
	v_mov_b32_e32 v61, v133
	v_lshl_add_u64 v[16:17], v[104:105], 0, v[60:61]
	v_mov_b32_e32 v16, v164
	v_add_f32_e32 v12, v12, v16
	v_mul_f32_e32 v12, 0xbfb8aa3b, v12
	v_exp_f32_e32 v12, v12
	s_nop 0
	v_add_f32_e32 v12, 1.0, v12
	v_rcp_f32_e32 v12, v12
	s_nop 0
	v_mul_f32_e32 v12, 0xbf1b4598, v12
	v_mul_f32_e32 v12, 0x3fb8aa3b, v12
	v_exp_f32_e32 v16, v12
.LBB0_937:
	s_or_b64 exec, exec, s[2:3]
	s_and_saveexec_b64 s[2:3], s[40:41]
	s_xor_b64 s[2:3], exec, s[2:3]
	s_cbranch_execz .LBB0_941
	v_mov_b32_e32 v12, v13
	s_and_saveexec_b64 s[20:21], vcc
	s_cbranch_execz .LBB0_940
	v_mov_b32_e32 v61, v133
	v_lshl_add_u64 v[18:19], v[104:105], 0, v[60:61]
	v_mov_b32_e32 v12, v165
	v_add_f32_e32 v12, v13, v12
	v_mul_f32_e32 v12, 0xbfb8aa3b, v12
	v_exp_f32_e32 v12, v12
	s_nop 0
	v_add_f32_e32 v12, 1.0, v12
	v_rcp_f32_e32 v12, v12

; __device__ __forceinline__ float sigmoidf_(float x) { return __builtin_amdgcn_rcpf(1.0f + __expf(-x)); }
; __device__ __forceinline__ void lora_phase(const Ctx& C, const PV& P, int layer, unsigned char* smem) {
;     ...
;                 for (int r = 0; r < 4; ++r) {
;                     float v = acc[i][jn][r];
;                     if (which < 2) {
;                         const float z = bias[n + r] + v;
;                         v = __expf(-0.6065306597126334f * sigmoidf_(z));
;                     } else if (which < 4) { v = sigmoidf_(bias[n + r] + v); }
;                     h[r] = (f16)v;
;                 }
;                 *(f16x4*)(dst + (size_t)lt * 512 + n) = h;
.LBB0_942:
	v_mov_b32_e32 v61, v133
	v_lshl_add_u64 v[18:19], v[104:105], 0, v[60:61]
	v_mov_b32_e32 v12, v165
	v_add_f32_e32 v12, v13, v12
	v_mul_f32_e32 v12, 0xbfb8aa3b, v12
	v_exp_f32_e32 v12, v12
	s_nop 0
	v_add_f32_e32 v12, 1.0, v12
	v_rcp_f32_e32 v12, v12
	s_nop 0
	v_mul_f32_e32 v12, 0xbf1b4598, v12
	v_mul_f32_e32 v12, 0x3fb8aa3b, v12
	v_exp_f32_e32 v12, v12
.LBB0_943:
	s_or_b64 exec, exec, s[2:3]
	s_and_saveexec_b64 s[2:3], s[40:41]
	s_xor_b64 s[2:3], exec, s[2:3]
	s_cbranch_execz .LBB0_947
	v_mov_b32_e32 v13, v14
	s_and_saveexec_b64 s[20:21], vcc
	s_cbranch_execz .LBB0_946
	v_mov_b32_e32 v61, v133
	v_lshl_add_u64 v[18:19], v[104:105], 0, v[60:61]
	v_mov_b32_e32 v13, v166
	v_add_f32_e32 v13, v14, v13
	v_mul_f32_e32 v13, 0xbfb8aa3b, v13
	v_exp_f32_e32 v13, v13
	s_nop 0
	v_add_f32_e32 v13, 1.0, v13
	v_rcp_f32_e32 v13, v13

; __device__ __forceinline__ float sigmoidf_(float x) { return __builtin_amdgcn_rcpf(1.0f + __expf(-x)); }
; __device__ __forceinline__ void lora_phase(const Ctx& C, const PV& P, int layer, unsigned char* smem) {
;     ...
;                 for (int r = 0; r < 4; ++r) {
;                     float v = acc[i][jn][r];
;                     if (which < 2) {
;                         const float z = bias[n + r] + v;
;                         v = __expf(-0.6065306597126334f * sigmoidf_(z));
;                     } else if (which < 4) { v = sigmoidf_(bias[n + r] + v); }
;                     h[r] = (f16)v;
;                 }
;                 *(f16x4*)(dst + (size_t)lt * 512 + n) = h;
.LBB0_948:
	v_mov_b32_e32 v61, v133
	v_lshl_add_u64 v[18:19], v[104:105], 0, v[60:61]
	v_mov_b32_e32 v13, v166
	v_add_f32_e32 v13, v14, v13
	v_mul_f32_e32 v13, 0xbfb8aa3b, v13
	v_exp_f32_e32 v13, v13
	s_nop 0
	v_add_f32_e32 v13, 1.0, v13
	v_rcp_f32_e32 v13, v13
	s_nop 0
	v_mul_f32_e32 v13, 0xbf1b4598, v13
	v_mul_f32_e32 v13, 0x3fb8aa3b, v13
	v_exp_f32_e32 v13, v13
.LBB0_949:
	s_or_b64 exec, exec, s[2:3]
	s_and_saveexec_b64 s[2:3], s[40:41]
	s_xor_b64 s[2:3], exec, s[2:3]
	s_cbranch_execz .LBB0_953
	v_mov_b32_e32 v14, v15
	s_and_saveexec_b64 s[20:21], vcc
	s_cbranch_execz .LBB0_952
	v_mov_b32_e32 v61, v133
	v_lshl_add_u64 v[18:19], v[104:105], 0, v[60:61]
	v_mov_b32_e32 v14, v167
	v_add_f32_e32 v14, v15, v14
	v_mul_f32_e32 v14, 0xbfb8aa3b, v14
	v_exp_f32_e32 v14, v14
	s_nop 0
	v_add_f32_e32 v14, 1.0, v14
	v_rcp_f32_e32 v14, v14

; __device__ __forceinline__ float sigmoidf_(float x) { return __builtin_amdgcn_rcpf(1.0f + __expf(-x)); }
; __device__ __forceinline__ void lora_phase(const Ctx& C, const PV& P, int layer, unsigned char* smem) {
;     ...
;                 for (int r = 0; r < 4; ++r) {
;                     float v = acc[i][jn][r];
;                     if (which < 2) {
;                         const float z = bias[n + r] + v;
;                         v = __expf(-0.6065306597126334f * sigmoidf_(z));
;                     } else if (which < 4) { v = sigmoidf_(bias[n + r] + v); }
;                     h[r] = (f16)v;
;                 }
;                 *(f16x4*)(dst + (size_t)lt * 512 + n) = h;
.LBB0_954:
	v_mov_b32_e32 v61, v133
	v_lshl_add_u64 v[18:19], v[104:105], 0, v[60:61]
	v_mov_b32_e32 v14, v167
	v_add_f32_e32 v14, v15, v14
	v_mul_f32_e32 v14, 0xbfb8aa3b, v14
	v_exp_f32_e32 v14, v14
	s_nop 0
	v_add_f32_e32 v14, 1.0, v14
	v_rcp_f32_e32 v14, v14
	s_nop 0
	v_mul_f32_e32 v14, 0xbf1b4598, v14
	v_mul_f32_e32 v14, 0x3fb8aa3b, v14
	v_exp_f32_e32 v14, v14
.LBB0_955:
	s_or_b64 exec, exec, s[2:3]
	v_or_b32_e32 v18, 48, v62
	v_ashrrev_i32_e32 v19, 31, v18
	v_lshlrev_b64 v[18:19], 10, v[18:19]
	v_lshl_add_u64 v[18:19], v[106:107], 0, v[18:19]
	v_cvt_pk_f16_f32 v15, v13, v14
	v_cvt_pk_f16_f32 v14, v16, v12
	v_lshl_add_u64 v[12:13], v[18:19], 0, v[132:133]
	global_store_dwordx2 v[12:13], v[14:15], off
	s_and_saveexec_b64 s[2:3], s[40:41]
	s_xor_b64 s[2:3], exec, s[2:3]
	s_cbranch_execz .LBB0_959
	v_mov_b32_e32 v14, v8
	s_and_saveexec_b64 s[20:21], vcc
	s_cbranch_execz .LBB0_958
	v_mov_b32_e32 v61, v133
	v_lshl_add_u64 v[14:15], v[104:105], 0, v[60:61]
	v_mov_b32_e32 v14, v168
	v_add_f32_e32 v14, v8, v14
	v_mul_f32_e32 v14, 0xbfb8aa3b, v14
	v_exp_f32_e32 v14, v14
	s_nop 0
	v_add_f32_e32 v14, 1.0, v14
	v_rcp_f32_e32 v14, v14

; __device__ __forceinline__ float sigmoidf_(float x) { return __builtin_amdgcn_rcpf(1.0f + __expf(-x)); }
; __device__ __forceinline__ void lora_phase(const Ctx& C, const PV& P, int layer, unsigned char* smem) {
;     ...
;                 for (int r = 0; r < 4; ++r) {
;                     float v = acc[i][jn][r];
;                     if (which < 2) {
;                         const float z = bias[n + r] + v;
;                         v = __expf(-0.6065306597126334f * sigmoidf_(z));
;                     } else if (which < 4) { v = sigmoidf_(bias[n + r] + v); }
;                     h[r] = (f16)v;
;                 }
;                 *(f16x4*)(dst + (size_t)lt * 512 + n) = h;
.LBB0_960:
	v_mov_b32_e32 v61, v133
	v_lshl_add_u64 v[14:15], v[104:105], 0, v[60:61]
	v_mov_b32_e32 v14, v168
	v_add_f32_e32 v8, v8, v14
	v_mul_f32_e32 v8, 0xbfb8aa3b, v8
	v_exp_f32_e32 v8, v8
	s_nop 0
	v_add_f32_e32 v8, 1.0, v8
	v_rcp_f32_e32 v8, v8
	s_nop 0
	v_mul_f32_e32 v8, 0xbf1b4598, v8
	v_mul_f32_e32 v8, 0x3fb8aa3b, v8
	v_exp_f32_e32 v14, v8
.LBB0_961:
	s_or_b64 exec, exec, s[2:3]
	s_and_saveexec_b64 s[2:3], s[40:41]
	s_xor_b64 s[2:3], exec, s[2:3]
	s_cbranch_execz .LBB0_965
	v_mov_b32_e32 v8, v9
	s_and_saveexec_b64 s[20:21], vcc
	s_cbranch_execz .LBB0_964
	v_mov_b32_e32 v61, v133
	v_lshl_add_u64 v[16:17], v[104:105], 0, v[60:61]
	v_mov_b32_e32 v8, v169
	v_add_f32_e32 v8, v9, v8
	v_mul_f32_e32 v8, 0xbfb8aa3b, v8
	v_exp_f32_e32 v8, v8
	s_nop 0
	v_add_f32_e32 v8, 1.0, v8
	v_rcp_f32_e32 v8, v8

; __device__ __forceinline__ float sigmoidf_(float x) { return __builtin_amdgcn_rcpf(1.0f + __expf(-x)); }
; __device__ __forceinline__ void lora_phase(const Ctx& C, const PV& P, int layer, unsigned char* smem) {
;     ...
;                 for (int r = 0; r < 4; ++r) {
;                     float v = acc[i][jn][r];
;                     if (which < 2) {
;                         const float z = bias[n + r] + v;
;                         v = __expf(-0.6065306597126334f * sigmoidf_(z));
;                     } else if (which < 4) { v = sigmoidf_(bias[n + r] + v); }
;                     h[r] = (f16)v;
;                 }
;                 *(f16x4*)(dst + (size_t)lt * 512 + n) = h;
.LBB0_966:
	v_mov_b32_e32 v61, v133
	v_lshl_add_u64 v[16:17], v[104:105], 0, v[60:61]
	v_mov_b32_e32 v8, v169
	v_add_f32_e32 v8, v9, v8
	v_mul_f32_e32 v8, 0xbfb8aa3b, v8
	v_exp_f32_e32 v8, v8
	s_nop 0
	v_add_f32_e32 v8, 1.0, v8
	v_rcp_f32_e32 v8, v8
	s_nop 0
	v_mul_f32_e32 v8, 0xbf1b4598, v8
	v_mul_f32_e32 v8, 0x3fb8aa3b, v8
	v_exp_f32_e32 v8, v8
.LBB0_967:
	s_or_b64 exec, exec, s[2:3]
	s_and_saveexec_b64 s[2:3], s[40:41]
	s_xor_b64 s[2:3], exec, s[2:3]
	s_cbranch_execz .LBB0_971
	v_mov_b32_e32 v9, v10
	s_and_saveexec_b64 s[20:21], vcc
	s_cbranch_execz .LBB0_970
	v_mov_b32_e32 v61, v133
	v_lshl_add_u64 v[16:17], v[104:105], 0, v[60:61]
	v_mov_b32_e32 v9, v170
	v_add_f32_e32 v9, v10, v9
	v_mul_f32_e32 v9, 0xbfb8aa3b, v9
	v_exp_f32_e32 v9, v9
	s_nop 0
	v_add_f32_e32 v9, 1.0, v9
	v_rcp_f32_e32 v9, v9

; __device__ __forceinline__ float sigmoidf_(float x) { return __builtin_amdgcn_rcpf(1.0f + __expf(-x)); }
; __device__ __forceinline__ void lora_phase(const Ctx& C, const PV& P, int layer, unsigned char* smem) {
;     ...
;                 for (int r = 0; r < 4; ++r) {
;                     float v = acc[i][jn][r];
;                     if (which < 2) {
;                         const float z = bias[n + r] + v;
;                         v = __expf(-0.6065306597126334f * sigmoidf_(z));
;                     } else if (which < 4) { v = sigmoidf_(bias[n + r] + v); }
;                     h[r] = (f16)v;
;                 }
;                 *(f16x4*)(dst + (size_t)lt * 512 + n) = h;
.LBB0_972:
	v_mov_b32_e32 v61, v133
	v_lshl_add_u64 v[16:17], v[104:105], 0, v[60:61]
	v_mov_b32_e32 v9, v170
	v_add_f32_e32 v9, v10, v9
	v_mul_f32_e32 v9, 0xbfb8aa3b, v9
	v_exp_f32_e32 v9, v9
	s_nop 0
	v_add_f32_e32 v9, 1.0, v9
	v_rcp_f32_e32 v9, v9
	s_nop 0
	v_mul_f32_e32 v9, 0xbf1b4598, v9
	v_mul_f32_e32 v9, 0x3fb8aa3b, v9
	v_exp_f32_e32 v9, v9
.LBB0_973:
	s_or_b64 exec, exec, s[2:3]
	s_and_saveexec_b64 s[2:3], s[40:41]
	s_xor_b64 s[2:3], exec, s[2:3]
	s_cbranch_execz .LBB0_977
	v_mov_b32_e32 v10, v11
	s_and_saveexec_b64 s[20:21], vcc
	s_cbranch_execz .LBB0_976
	v_mov_b32_e32 v61, v133
	v_lshl_add_u64 v[16:17], v[104:105], 0, v[60:61]
	v_mov_b32_e32 v10, v171
	v_add_f32_e32 v10, v11, v10
	v_mul_f32_e32 v10, 0xbfb8aa3b, v10
	v_exp_f32_e32 v10, v10
	s_nop 0
	v_add_f32_e32 v10, 1.0, v10
	v_rcp_f32_e32 v10, v10

; __device__ __forceinline__ float sigmoidf_(float x) { return __builtin_amdgcn_rcpf(1.0f + __expf(-x)); }
; __device__ __forceinline__ void lora_phase(const Ctx& C, const PV& P, int layer, unsigned char* smem) {
;     ...
;                 for (int r = 0; r < 4; ++r) {
;                     float v = acc[i][jn][r];
;                     if (which < 2) {
;                         const float z = bias[n + r] + v;
;                         v = __expf(-0.6065306597126334f * sigmoidf_(z));
;                     } else if (which < 4) { v = sigmoidf_(bias[n + r] + v); }
;                     h[r] = (f16)v;
;                 }
;                 *(f16x4*)(dst + (size_t)lt * 512 + n) = h;
.LBB0_978:
	v_mov_b32_e32 v61, v133
	v_lshl_add_u64 v[16:17], v[104:105], 0, v[60:61]
	v_mov_b32_e32 v10, v171
	v_add_f32_e32 v10, v11, v10
	v_mul_f32_e32 v10, 0xbfb8aa3b, v10
	v_exp_f32_e32 v10, v10
	s_nop 0
	v_add_f32_e32 v10, 1.0, v10
	v_rcp_f32_e32 v10, v10
	s_nop 0
	v_mul_f32_e32 v10, 0xbf1b4598, v10
	v_mul_f32_e32 v10, 0x3fb8aa3b, v10
	v_exp_f32_e32 v10, v10
.LBB0_979:
	s_or_b64 exec, exec, s[2:3]
	v_cvt_pk_f16_f32 v9, v9, v10
	v_cvt_pk_f16_f32 v8, v14, v8
	global_store_dwordx2 v[12:13], v[8:9], off offset:32
	s_and_saveexec_b64 s[2:3], s[40:41]
	s_xor_b64 s[2:3], exec, s[2:3]
	s_cbranch_execz .LBB0_983
	v_mov_b32_e32 v8, v4
	s_and_saveexec_b64 s[20:21], vcc
	s_cbranch_execz .LBB0_982
	v_mov_b32_e32 v61, v133
	v_lshl_add_u64 v[8:9], v[104:105], 0, v[60:61]
	v_mov_b32_e32 v8, v172
	v_add_f32_e32 v8, v4, v8
	v_mul_f32_e32 v8, 0xbfb8aa3b, v8
	v_exp_f32_e32 v8, v8
	s_nop 0
	v_add_f32_e32 v8, 1.0, v8
	v_rcp_f32_e32 v8, v8

; __device__ __forceinline__ float sigmoidf_(float x) { return __builtin_amdgcn_rcpf(1.0f + __expf(-x)); }
; __device__ __forceinline__ void lora_phase(const Ctx& C, const PV& P, int layer, unsigned char* smem) {
;     ...
;                 for (int r = 0; r < 4; ++r) {
;                     float v = acc[i][jn][r];
;                     if (which < 2) {
;                         const float z = bias[n + r] + v;
;                         v = __expf(-0.6065306597126334f * sigmoidf_(z));
;                     } else if (which < 4) { v = sigmoidf_(bias[n + r] + v); }
;                     h[r] = (f16)v;
;                 }
;                 *(f16x4*)(dst + (size_t)lt * 512 + n) = h;
.LBB0_984:
	v_mov_b32_e32 v61, v133
	v_lshl_add_u64 v[8:9], v[104:105], 0, v[60:61]
	v_mov_b32_e32 v8, v172
	v_add_f32_e32 v4, v4, v8
	v_mul_f32_e32 v4, 0xbfb8aa3b, v4
	v_exp_f32_e32 v4, v4
	s_nop 0
	v_add_f32_e32 v4, 1.0, v4
	v_rcp_f32_e32 v4, v4
	s_nop 0
	v_mul_f32_e32 v4, 0xbf1b4598, v4
	v_mul_f32_e32 v4, 0x3fb8aa3b, v4
	v_exp_f32_e32 v8, v4
.LBB0_985:
	s_or_b64 exec, exec, s[2:3]
	s_and_saveexec_b64 s[2:3], s[40:41]
	s_xor_b64 s[2:3], exec, s[2:3]
	s_cbranch_execz .LBB0_989
	v_mov_b32_e32 v4, v5
	s_and_saveexec_b64 s[20:21], vcc
	s_cbranch_execz .LBB0_988
	v_mov_b32_e32 v61, v133
	v_lshl_add_u64 v[10:11], v[104:105], 0, v[60:61]
	v_mov_b32_e32 v4, v173
	v_add_f32_e32 v4, v5, v4
	v_mul_f32_e32 v4, 0xbfb8aa3b, v4
	v_exp_f32_e32 v4, v4
	s_nop 0
	v_add_f32_e32 v4, 1.0, v4
	v_rcp_f32_e32 v4, v4

; __device__ __forceinline__ float sigmoidf_(float x) { return __builtin_amdgcn_rcpf(1.0f + __expf(-x)); }
; __device__ __forceinline__ void lora_phase(const Ctx& C, const PV& P, int layer, unsigned char* smem) {
;     ...
;                 for (int r = 0; r < 4; ++r) {
;                     float v = acc[i][jn][r];
;                     if (which < 2) {
;                         const float z = bias[n + r] + v;
;                         v = __expf(-0.6065306597126334f * sigmoidf_(z));
;                     } else if (which < 4) { v = sigmoidf_(bias[n + r] + v); }
;                     h[r] = (f16)v;
;                 }
;                 *(f16x4*)(dst + (size_t)lt * 512 + n) = h;
.LBB0_990:
	v_mov_b32_e32 v61, v133
	v_lshl_add_u64 v[10:11], v[104:105], 0, v[60:61]
	v_mov_b32_e32 v4, v173
	v_add_f32_e32 v4, v5, v4
	v_mul_f32_e32 v4, 0xbfb8aa3b, v4
	v_exp_f32_e32 v4, v4
	s_nop 0
	v_add_f32_e32 v4, 1.0, v4
	v_rcp_f32_e32 v4, v4
	s_nop 0
	v_mul_f32_e32 v4, 0xbf1b4598, v4
	v_mul_f32_e32 v4, 0x3fb8aa3b, v4
	v_exp_f32_e32 v4, v4
.LBB0_991:
	s_or_b64 exec, exec, s[2:3]
	s_and_saveexec_b64 s[2:3], s[40:41]
	s_xor_b64 s[2:3], exec, s[2:3]
	s_cbranch_execz .LBB0_995
	v_mov_b32_e32 v5, v6
	s_and_saveexec_b64 s[20:21], vcc
	s_cbranch_execz .LBB0_994
	v_mov_b32_e32 v61, v133
	v_lshl_add_u64 v[10:11], v[104:105], 0, v[60:61]
	v_mov_b32_e32 v5, v174
	v_add_f32_e32 v5, v6, v5
	v_mul_f32_e32 v5, 0xbfb8aa3b, v5
	v_exp_f32_e32 v5, v5
	s_nop 0
	v_add_f32_e32 v5, 1.0, v5
	v_rcp_f32_e32 v5, v5

; __device__ __forceinline__ float sigmoidf_(float x) { return __builtin_amdgcn_rcpf(1.0f + __expf(-x)); }
; __device__ __forceinline__ void lora_phase(const Ctx& C, const PV& P, int layer, unsigned char* smem) {
;     ...
;                 for (int r = 0; r < 4; ++r) {
;                     float v = acc[i][jn][r];
;                     if (which < 2) {
;                         const float z = bias[n + r] + v;
;                         v = __expf(-0.6065306597126334f * sigmoidf_(z));
;                     } else if (which < 4) { v = sigmoidf_(bias[n + r] + v); }
;                     h[r] = (f16)v;
;                 }
;                 *(f16x4*)(dst + (size_t)lt * 512 + n) = h;
.LBB0_996:
	v_mov_b32_e32 v61, v133
	v_lshl_add_u64 v[10:11], v[104:105], 0, v[60:61]
	v_mov_b32_e32 v5, v174
	v_add_f32_e32 v5, v6, v5
	v_mul_f32_e32 v5, 0xbfb8aa3b, v5
	v_exp_f32_e32 v5, v5
	s_nop 0
	v_add_f32_e32 v5, 1.0, v5
	v_rcp_f32_e32 v5, v5
	s_nop 0
	v_mul_f32_e32 v5, 0xbf1b4598, v5
	v_mul_f32_e32 v5, 0x3fb8aa3b, v5
	v_exp_f32_e32 v5, v5
.LBB0_997:
	s_or_b64 exec, exec, s[2:3]
	s_and_saveexec_b64 s[2:3], s[40:41]
	s_xor_b64 s[2:3], exec, s[2:3]
	s_cbranch_execz .LBB0_1001
	v_mov_b32_e32 v6, v7
	s_and_saveexec_b64 s[20:21], vcc
	s_cbranch_execz .LBB0_1000
	v_mov_b32_e32 v61, v133
	v_lshl_add_u64 v[10:11], v[104:105], 0, v[60:61]
	v_mov_b32_e32 v6, v175
	v_add_f32_e32 v6, v7, v6
	v_mul_f32_e32 v6, 0xbfb8aa3b, v6
	v_exp_f32_e32 v6, v6
	s_nop 0
	v_add_f32_e32 v6, 1.0, v6
	v_rcp_f32_e32 v6, v6

; __device__ __forceinline__ float sigmoidf_(float x) { return __builtin_amdgcn_rcpf(1.0f + __expf(-x)); }
; __device__ __forceinline__ void lora_phase(const Ctx& C, const PV& P, int layer, unsigned char* smem) {
;     ...
;                 for (int r = 0; r < 4; ++r) {
;                     float v = acc[i][jn][r];
;                     if (which < 2) {
;                         const float z = bias[n + r] + v;
;                         v = __expf(-0.6065306597126334f * sigmoidf_(z));
;                     } else if (which < 4) { v = sigmoidf_(bias[n + r] + v); }
;                     h[r] = (f16)v;
;                 }
;                 *(f16x4*)(dst + (size_t)lt * 512 + n) = h;
.LBB0_1002:
	v_mov_b32_e32 v61, v133
	v_lshl_add_u64 v[10:11], v[104:105], 0, v[60:61]
	v_mov_b32_e32 v6, v175
	v_add_f32_e32 v6, v7, v6
	v_mul_f32_e32 v6, 0xbfb8aa3b, v6
	v_exp_f32_e32 v6, v6
	s_nop 0
	v_add_f32_e32 v6, 1.0, v6
	v_rcp_f32_e32 v6, v6
	s_nop 0
	v_mul_f32_e32 v6, 0xbf1b4598, v6
	v_mul_f32_e32 v6, 0x3fb8aa3b, v6
	v_exp_f32_e32 v6, v6
.LBB0_1003:
	s_or_b64 exec, exec, s[2:3]
	v_cvt_pk_f16_f32 v5, v5, v6
	v_cvt_pk_f16_f32 v4, v8, v4
	global_store_dwordx2 v[12:13], v[4:5], off offset:64
	s_and_saveexec_b64 s[2:3], s[40:41]
	s_xor_b64 s[2:3], exec, s[2:3]
	s_cbranch_execz .LBB0_1007
	v_mov_b32_e32 v4, v0
	s_and_saveexec_b64 s[20:21], vcc
	s_cbranch_execz .LBB0_1006
	v_mov_b32_e32 v61, v133
	v_lshl_add_u64 v[4:5], v[104:105], 0, v[60:61]
	v_mov_b32_e32 v4, v176
	v_add_f32_e32 v4, v0, v4
	v_mul_f32_e32 v4, 0xbfb8aa3b, v4
	v_exp_f32_e32 v4, v4
	s_nop 0
	v_add_f32_e32 v4, 1.0, v4
	v_rcp_f32_e32 v4, v4

; __device__ __forceinline__ float sigmoidf_(float x) { return __builtin_amdgcn_rcpf(1.0f + __expf(-x)); }
; __device__ __forceinline__ void lora_phase(const Ctx& C, const PV& P, int layer, unsigned char* smem) {
;     ...
;                 for (int r = 0; r < 4; ++r) {
;                     float v = acc[i][jn][r];
;                     if (which < 2) {
;                         const float z = bias[n + r] + v;
;                         v = __expf(-0.6065306597126334f * sigmoidf_(z));
;                     } else if (which < 4) { v = sigmoidf_(bias[n + r] + v); }
;                     h[r] = (f16)v;
;                 }
;                 *(f16x4*)(dst + (size_t)lt * 512 + n) = h;
.LBB0_1008:
	v_mov_b32_e32 v61, v133
	v_lshl_add_u64 v[4:5], v[104:105], 0, v[60:61]
	v_mov_b32_e32 v4, v176
	v_add_f32_e32 v0, v0, v4
	v_mul_f32_e32 v0, 0xbfb8aa3b, v0
	v_exp_f32_e32 v0, v0
	s_nop 0
	v_add_f32_e32 v0, 1.0, v0
	v_rcp_f32_e32 v0, v0
	s_nop 0
	v_mul_f32_e32 v0, 0xbf1b4598, v0
	v_mul_f32_e32 v0, 0x3fb8aa3b, v0
	v_exp_f32_e32 v4, v0
.LBB0_1009:
	s_or_b64 exec, exec, s[2:3]
	s_and_saveexec_b64 s[2:3], s[40:41]
	s_xor_b64 s[2:3], exec, s[2:3]
	s_cbranch_execz .LBB0_1013
	v_mov_b32_e32 v0, v1
	s_and_saveexec_b64 s[20:21], vcc
	s_cbranch_execz .LBB0_1012
	v_mov_b32_e32 v61, v133
	v_lshl_add_u64 v[6:7], v[104:105], 0, v[60:61]
	v_mov_b32_e32 v0, v177
	v_add_f32_e32 v0, v1, v0
	v_mul_f32_e32 v0, 0xbfb8aa3b, v0
	v_exp_f32_e32 v0, v0
	s_nop 0
	v_add_f32_e32 v0, 1.0, v0
	v_rcp_f32_e32 v0, v0

; __device__ __forceinline__ float sigmoidf_(float x) { return __builtin_amdgcn_rcpf(1.0f + __expf(-x)); }
; __device__ __forceinline__ void lora_phase(const Ctx& C, const PV& P, int layer, unsigned char* smem) {
;     ...
;                 for (int r = 0; r < 4; ++r) {
;                     float v = acc[i][jn][r];
;                     if (which < 2) {
;                         const float z = bias[n + r] + v;
;                         v = __expf(-0.6065306597126334f * sigmoidf_(z));
;                     } else if (which < 4) { v = sigmoidf_(bias[n + r] + v); }
;                     h[r] = (f16)v;
;                 }
;                 *(f16x4*)(dst + (size_t)lt * 512 + n) = h;
.LBB0_1014:
	v_mov_b32_e32 v61, v133
	v_lshl_add_u64 v[6:7], v[104:105], 0, v[60:61]
	v_mov_b32_e32 v0, v177
	v_add_f32_e32 v0, v1, v0
	v_mul_f32_e32 v0, 0xbfb8aa3b, v0
	v_exp_f32_e32 v0, v0
	s_nop 0
	v_add_f32_e32 v0, 1.0, v0
	v_rcp_f32_e32 v0, v0
	s_nop 0
	v_mul_f32_e32 v0, 0xbf1b4598, v0
	v_mul_f32_e32 v0, 0x3fb8aa3b, v0
	v_exp_f32_e32 v0, v0
.LBB0_1015:
	s_or_b64 exec, exec, s[2:3]
	s_and_saveexec_b64 s[2:3], s[40:41]
	s_xor_b64 s[2:3], exec, s[2:3]
	s_cbranch_execz .LBB0_1019
	v_mov_b32_e32 v1, v2
	s_and_saveexec_b64 s[20:21], vcc
	s_cbranch_execz .LBB0_1018
	v_mov_b32_e32 v61, v133
	v_lshl_add_u64 v[6:7], v[104:105], 0, v[60:61]
	v_mov_b32_e32 v1, v178
	v_add_f32_e32 v1, v2, v1
	v_mul_f32_e32 v1, 0xbfb8aa3b, v1
	v_exp_f32_e32 v1, v1
	s_nop 0
	v_add_f32_e32 v1, 1.0, v1
	v_rcp_f32_e32 v1, v1

; __device__ __forceinline__ float sigmoidf_(float x) { return __builtin_amdgcn_rcpf(1.0f + __expf(-x)); }
; __device__ __forceinline__ void lora_phase(const Ctx& C, const PV& P, int layer, unsigned char* smem) {
;     ...
;                 for (int r = 0; r < 4; ++r) {
;                     float v = acc[i][jn][r];
;                     if (which < 2) {
;                         const float z = bias[n + r] + v;
;                         v = __expf(-0.6065306597126334f * sigmoidf_(z));
;                     } else if (which < 4) { v = sigmoidf_(bias[n + r] + v); }
;                     h[r] = (f16)v;
;                 }
;                 *(f16x4*)(dst + (size_t)lt * 512 + n) = h;
.LBB0_1020:
	v_mov_b32_e32 v61, v133
	v_lshl_add_u64 v[6:7], v[104:105], 0, v[60:61]
	v_mov_b32_e32 v1, v178
	v_add_f32_e32 v1, v2, v1
	v_mul_f32_e32 v1, 0xbfb8aa3b, v1
	v_exp_f32_e32 v1, v1
	s_nop 0
	v_add_f32_e32 v1, 1.0, v1
	v_rcp_f32_e32 v1, v1
	s_nop 0
	v_mul_f32_e32 v1, 0xbf1b4598, v1
	v_mul_f32_e32 v1, 0x3fb8aa3b, v1
	v_exp_f32_e32 v1, v1
.LBB0_1021:
	s_or_b64 exec, exec, s[2:3]
	s_and_saveexec_b64 s[2:3], s[40:41]
	s_xor_b64 s[2:3], exec, s[2:3]
	s_cbranch_execz .LBB0_1025
	v_mov_b32_e32 v2, v3
	s_and_saveexec_b64 s[20:21], vcc
	s_cbranch_execz .LBB0_1024
	v_mov_b32_e32 v61, v133
	v_lshl_add_u64 v[6:7], v[104:105], 0, v[60:61]
	v_mov_b32_e32 v2, v179
	v_add_f32_e32 v2, v3, v2
	v_mul_f32_e32 v2, 0xbfb8aa3b, v2
	v_exp_f32_e32 v2, v2
	s_nop 0
	v_add_f32_e32 v2, 1.0, v2
	v_rcp_f32_e32 v2, v2

; __device__ __forceinline__ float sigmoidf_(float x) { return __builtin_amdgcn_rcpf(1.0f + __expf(-x)); }
; __device__ __forceinline__ void lora_phase(const Ctx& C, const PV& P, int layer, unsigned char* smem) {
;     ...
;                 for (int r = 0; r < 4; ++r) {
;                     float v = acc[i][jn][r];
;                     if (which < 2) {
;                         const float z = bias[n + r] + v;
;                         v = __expf(-0.6065306597126334f * sigmoidf_(z));
;                     } else if (which < 4) { v = sigmoidf_(bias[n + r] + v); }
;                     h[r] = (f16)v;
;                 }
;                 *(f16x4*)(dst + (size_t)lt * 512 + n) = h;
.LBB0_1026:
	v_mov_b32_e32 v61, v133
	v_lshl_add_u64 v[6:7], v[104:105], 0, v[60:61]
	v_mov_b32_e32 v2, v179
	v_add_f32_e32 v2, v3, v2
	v_mul_f32_e32 v2, 0xbfb8aa3b, v2
	v_exp_f32_e32 v2, v2
	s_nop 0
	v_add_f32_e32 v2, 1.0, v2
	v_rcp_f32_e32 v2, v2
	s_nop 0
	v_mul_f32_e32 v2, 0xbf1b4598, v2
	v_mul_f32_e32 v2, 0x3fb8aa3b, v2
	v_exp_f32_e32 v2, v2
	s_branch .LBB0_632

; __device__ __forceinline__ void lin_pool_phase(const Ctx& C, const PV& P, int layer) {
;     ...
;         for (int lt = C.bid * NWV + wave; lt < TP; lt += C.nblk * NWV) {
;             const int pos = pos_of(lt), S = lt < 8192 ? 8192 : 4096;
;             float ss[8];
; #pragma unroll
;             for (int h = 0; h < 8; ++h) {
;                 const int c = h * 64 + lane;
;                 const float k = shiftv(raw, lt, pos, S, 512 + c, mu[512 + c]) * k_k[c];
;                 ss[h] = k * k;
;             }
; #pragma unroll
;             for (int h = 0; h < 8; ++h) ss[h] = wsum(ss[h]);
.LBB0_1166:
	s_waitcnt lgkmcnt(0)
	v_and_b32_e32 v10, 0xfff, v1
	v_cmp_gt_i32_e64 s[56:57], s29, v1
	v_add_u32_e32 v13, -1, v1
	v_cndmask_b32_e64 v12, v10, v1, s[56:57]
	v_mov_b64_e32 v[10:11], s[14:15]
	v_cmp_lt_i32_e32 vcc, 0, v12
	v_mad_i64_i32 v[10:11], s[4:5], v13, s77, v[10:11]
	v_lshlrev_b32_e32 v132, 1, v0
	v_cndmask_b32_e64 v13, v185, v184, s[56:57]
	v_cmp_lt_i32_e64 s[56:57], v12, v13
	v_add_u32_e32 v24, 1, v1
	v_mov_b64_e32 v[12:13], s[14:15]
	v_mad_i64_i32 v[12:13], s[4:5], v24, s77, v[12:13]
	v_lshl_add_u64 v[60:61], v[10:11], 0, v[132:133]
	v_lshl_add_u64 v[62:63], v[12:13], 0, v[132:133]
	global_load_ushort v64, v[60:61], off offset:1024
	global_load_ushort v72, v[62:63], off offset:1024
	global_load_ushort v21, v[8:9], off offset:-512
	global_load_dword v20, v[2:3], off offset:2048
	global_load_dword v25, v[4:5], off
	global_load_ushort v65, v[60:61], off offset:1152
	global_load_ushort v73, v[62:63], off offset:1152
	global_load_ushort v28, v[8:9], off offset:-384
	global_load_dword v26, v[2:3], off offset:2304
	global_load_dword v31, v[4:5], off offset:256
	global_load_ushort v66, v[60:61], off offset:1280
	global_load_ushort v74, v[62:63], off offset:1280
	global_load_ushort v33, v[8:9], off offset:-256
	global_load_dword v32, v[2:3], off offset:2560
	global_load_dword v36, v[4:5], off offset:512
	global_load_ushort v67, v[60:61], off offset:1408
	global_load_ushort v75, v[62:63], off offset:1408
	global_load_ushort v38, v[8:9], off offset:-128
	global_load_dword v37, v[2:3], off offset:2816
	global_load_dword v41, v[4:5], off offset:768
	global_load_ushort v68, v[60:61], off offset:1536
	global_load_ushort v76, v[62:63], off offset:1536
	global_load_ushort v27, v[8:9], off
	global_load_dword v24, v[2:3], off offset:3072
	global_load_dword v44, v[4:5], off offset:1024
	global_load_ushort v69, v[60:61], off offset:1664
	global_load_ushort v77, v[62:63], off offset:1664
	global_load_ushort v46, v[8:9], off offset:128
	global_load_dword v45, v[2:3], off offset:3328
	global_load_dword v49, v[4:5], off offset:1280
	global_load_ushort v70, v[60:61], off offset:1792
	global_load_ushort v78, v[62:63], off offset:1792
	global_load_ushort v52, v[8:9], off offset:256
	global_load_dword v50, v[2:3], off offset:3584
	global_load_dword v58, v[4:5], off offset:1536
	global_load_ushort v71, v[60:61], off offset:1920
	global_load_ushort v79, v[62:63], off offset:1920
	global_load_ushort v53, v[8:9], off offset:384
	global_load_dword v51, v[2:3], off offset:3840
	s_waitcnt vmcnt(0)
	v_cvt_f32_f16_e32 v23, v64
	v_cvt_f32_f16_e32 v22, v72
	v_cvt_f32_f16_e32 v30, v65
	v_cvt_f32_f16_e32 v29, v73
	v_cvt_f32_f16_e32 v35, v66
	v_cvt_f32_f16_e32 v34, v74
	v_cvt_f32_f16_e32 v40, v67
	v_cvt_f32_f16_e32 v39, v75
	v_cvt_f32_f16_e32 v43, v68
	v_cvt_f32_f16_e32 v42, v76
	v_cvt_f32_f16_e32 v48, v69
	v_cvt_f32_f16_e32 v47, v77
	v_cvt_f32_f16_e32 v56, v70
	v_cvt_f32_f16_e32 v54, v78
	v_cvt_f32_f16_e32 v57, v71
	v_cvt_f32_f16_e32 v55, v79
	v_cndmask_b32_e32 v23, 0, v23, vcc
	v_cndmask_b32_e64 v22, 0, v22, s[56:57]
	v_cndmask_b32_e32 v30, 0, v30, vcc
	v_cndmask_b32_e64 v29, 0, v29, s[56:57]
	v_cndmask_b32_e32 v35, 0, v35, vcc
	v_cndmask_b32_e64 v34, 0, v34, s[56:57]
	v_cndmask_b32_e32 v40, 0, v40, vcc
	v_cndmask_b32_e64 v39, 0, v39, s[56:57]
	v_cndmask_b32_e32 v43, 0, v43, vcc
	v_cndmask_b32_e64 v42, 0, v42, s[56:57]
	v_cndmask_b32_e32 v48, 0, v48, vcc
	v_cndmask_b32_e64 v47, 0, v47, s[56:57]
	v_cndmask_b32_e32 v56, 0, v56, vcc
	v_cndmask_b32_e64 v54, 0, v54, s[56:57]
	v_cndmask_b32_e32 v57, 0, v57, vcc
	v_cndmask_b32_e64 v55, 0, v55, s[56:57]
	s_mov_b32 s4, 0.5
	v_add_f32_e32 v22, v23, v22
	s_waitcnt vmcnt(0)
	v_fma_mix_f32 v22, v22, s4, -v21 op_sel_hi:[0,0,1]
	v_fma_mix_f32 v20, v20, v22, v21 op_sel_hi:[0,0,1]
	global_load_dword v21, v[4:5], off offset:1792
	v_add_f32_e32 v10, v56, v54
	v_add_f32_e32 v12, v48, v47
	v_add_f32_e32 v42, v43, v42
	v_add_f32_e32 v39, v40, v39
	v_add_f32_e32 v34, v35, v34
	v_add_f32_e32 v29, v30, v29
	v_mul_f32_e32 v22, v25, v20
	v_add_f32_e32 v20, v57, v55
	v_fma_mix_f32 v10, v10, s4, -v52 op_sel_hi:[0,0,1]
	v_fma_mix_f32 v12, v12, s4, -v46 op_sel_hi:[0,0,1]
	v_fma_mix_f32 v42, v42, s4, -v27 op_sel_hi:[0,0,1]
	v_fma_mix_f32 v39, v39, s4, -v38 op_sel_hi:[0,0,1]
	v_fma_mix_f32 v34, v34, s4, -v33 op_sel_hi:[0,0,1]
	v_fma_mix_f32 v29, v29, s4, -v28 op_sel_hi:[0,0,1]
	v_fma_mix_f32 v20, v20, s4, -v53 op_sel_hi:[0,0,1]
	v_fma_mix_f32 v10, v50, v10, v52 op_sel_hi:[0,0,1]
	v_fma_mix_f32 v12, v45, v12, v46 op_sel_hi:[0,0,1]
	v_fma_mix_f32 v24, v24, v42, v27 op_sel_hi:[0,0,1]
	v_fma_mix_f32 v37, v37, v39, v38 op_sel_hi:[0,0,1]
	v_fma_mix_f32 v32, v32, v34, v33 op_sel_hi:[0,0,1]
	v_fma_mix_f32 v26, v26, v29, v28 op_sel_hi:[0,0,1]
	v_fma_mix_f32 v20, v51, v20, v53 op_sel_hi:[0,0,1]
	v_mul_f32_e32 v10, v58, v10
	v_mul_f32_e32 v12, v49, v12
	v_mul_f32_e32 v24, v44, v24
	v_mul_f32_e32 v37, v41, v37
	v_mul_f32_e32 v32, v36, v32
	v_mul_f32_e32 v26, v31, v26
	v_mul_f32_e32 v11, v10, v10
	v_mul_f32_e32 v13, v12, v12
	v_mul_f32_e32 v27, v24, v24
	v_mul_f32_e32 v38, v37, v37
	v_mul_f32_e32 v33, v32, v32
	v_mul_f32_e32 v28, v26, v26
	v_mul_f32_e32 v23, v22, v22
	ds_bpermute_b32 v23, v14, v23
	ds_bpermute_b32 v25, v14, v28
	ds_bpermute_b32 v28, v14, v33
	ds_bpermute_b32 v30, v14, v38
	ds_bpermute_b32 v27, v14, v27
	ds_bpermute_b32 v13, v14, v13
	ds_bpermute_b32 v11, v14, v11
	s_waitcnt lgkmcnt(6)
; __device__ __forceinline__ void lin_pool_phase(const Ctx& C, const PV& P, int layer) {
;     ...
; #pragma unroll
;             for (int h = 0; h < 8; ++h) ss[h] = wsum(ss[h]);
;             if (lane < 8) {
;                 float sel = ss[0];
; #pragma unroll
;                 for (int h = 1; h < 8; ++h) sel = lane == h ? ss[h] : sel;
;                 invn[(size_t)lt * 8 + lane] = 1.0f / fmaxf(sqrtf(sel), 1e-12f);
;             }
	v_fmac_f32_e32 v23, v22, v22
	s_waitcnt lgkmcnt(5)
	v_fmac_f32_e32 v25, v26, v26
	s_waitcnt lgkmcnt(4)
	v_fmac_f32_e32 v28, v32, v32
	s_waitcnt lgkmcnt(3)
	v_fmac_f32_e32 v30, v37, v37
	s_waitcnt lgkmcnt(2)
	v_fmac_f32_e32 v27, v24, v24
	s_waitcnt lgkmcnt(1)
	v_fmac_f32_e32 v13, v12, v12
	s_waitcnt lgkmcnt(0)
	v_fmac_f32_e32 v11, v10, v10
	ds_bpermute_b32 v22, v15, v23
	ds_bpermute_b32 v26, v15, v25
	ds_bpermute_b32 v29, v15, v28
	ds_bpermute_b32 v31, v15, v30
	ds_bpermute_b32 v24, v15, v27
	ds_bpermute_b32 v12, v15, v13
	ds_bpermute_b32 v10, v15, v11
	s_waitcnt lgkmcnt(6)
	v_add_f32_e32 v22, v23, v22
	s_waitcnt lgkmcnt(5)
	v_add_f32_e32 v25, v25, v26
	s_waitcnt lgkmcnt(4)
	v_add_f32_e32 v28, v28, v29
	s_waitcnt lgkmcnt(3)
	v_add_f32_e32 v30, v30, v31
	s_waitcnt lgkmcnt(2)
	v_add_f32_e32 v24, v27, v24
	s_waitcnt lgkmcnt(1)
	v_add_f32_e32 v12, v13, v12
	s_waitcnt lgkmcnt(0)
	v_add_f32_e32 v10, v11, v10
	ds_bpermute_b32 v23, v16, v22
	ds_bpermute_b32 v26, v16, v25
	ds_bpermute_b32 v29, v16, v28
	ds_bpermute_b32 v31, v16, v30
	ds_bpermute_b32 v27, v16, v24
	ds_bpermute_b32 v13, v16, v12
	ds_bpermute_b32 v11, v16, v10
	s_waitcnt lgkmcnt(6)
	v_add_f32_e32 v22, v22, v23
	s_waitcnt lgkmcnt(5)
	v_add_f32_e32 v25, v25, v26
	s_waitcnt lgkmcnt(4)
	v_add_f32_e32 v28, v28, v29
	s_waitcnt lgkmcnt(3)
	v_add_f32_e32 v30, v30, v31
	s_waitcnt lgkmcnt(2)
	v_add_f32_e32 v24, v24, v27
	s_waitcnt lgkmcnt(1)
	v_add_f32_e32 v12, v12, v13
	s_waitcnt lgkmcnt(0)
	v_add_f32_e32 v10, v10, v11
	ds_bpermute_b32 v23, v17, v22
	ds_bpermute_b32 v26, v17, v25
	s_waitcnt vmcnt(0)
	v_mul_f32_e32 v20, v21, v20
	v_mul_f32_e32 v21, v20, v20
	ds_bpermute_b32 v21, v14, v21
	ds_bpermute_b32 v29, v17, v28
	ds_bpermute_b32 v31, v17, v30
	ds_bpermute_b32 v27, v17, v24
	ds_bpermute_b32 v13, v17, v12
	s_waitcnt lgkmcnt(4)
	v_fmac_f32_e32 v21, v20, v20
	ds_bpermute_b32 v20, v15, v21
	ds_bpermute_b32 v11, v17, v10
	v_add_f32_e32 v22, v22, v23
	v_add_f32_e32 v25, v25, v26
	s_waitcnt lgkmcnt(5)
	v_add_f32_e32 v28, v28, v29
	s_waitcnt lgkmcnt(1)
	v_add_f32_e32 v20, v21, v20
	ds_bpermute_b32 v21, v16, v20
	v_add_f32_e32 v30, v30, v31
	v_add_f32_e32 v24, v24, v27
	v_add_f32_e32 v12, v12, v13
	s_waitcnt lgkmcnt(1)
	v_add_f32_e32 v10, v10, v11
	s_waitcnt lgkmcnt(0)
	v_add_f32_e32 v20, v20, v21
	ds_bpermute_b32 v21, v17, v20
	ds_bpermute_b32 v23, v18, v22
	ds_bpermute_b32 v26, v18, v25
	ds_bpermute_b32 v29, v18, v28
	ds_bpermute_b32 v31, v18, v30
	s_waitcnt lgkmcnt(4)
	v_add_f32_e32 v20, v20, v21
	ds_bpermute_b32 v27, v18, v24
	ds_bpermute_b32 v13, v18, v12
	ds_bpermute_b32 v11, v18, v10
	ds_bpermute_b32 v21, v18, v20
	s_waitcnt lgkmcnt(7)
	v_add_f32_e32 v22, v22, v23
	s_waitcnt lgkmcnt(6)
	v_add_f32_e32 v25, v25, v26
	s_waitcnt lgkmcnt(5)
	v_add_f32_e32 v28, v28, v29
	s_waitcnt lgkmcnt(4)
	v_add_f32_e32 v30, v30, v31
	s_waitcnt lgkmcnt(3)
	v_add_f32_e32 v24, v24, v27
	s_waitcnt lgkmcnt(2)
	v_add_f32_e32 v12, v12, v13
	s_waitcnt lgkmcnt(1)
	v_add_f32_e32 v10, v10, v11
	s_waitcnt lgkmcnt(0)
	v_add_f32_e32 v20, v20, v21
	ds_bpermute_b32 v23, v19, v22
	ds_bpermute_b32 v26, v19, v25
	ds_bpermute_b32 v29, v19, v28
	ds_bpermute_b32 v31, v19, v30
	ds_bpermute_b32 v27, v19, v24
	ds_bpermute_b32 v13, v19, v12
	ds_bpermute_b32 v11, v19, v10
	ds_bpermute_b32 v21, v19, v20
	s_and_saveexec_b64 s[62:63], s[40:41]
	s_cbranch_execz .LBB0_1165
	s_waitcnt lgkmcnt(1)
	v_add_f32_e32 v10, v10, v11
	v_add_f32_e32 v11, v12, v13
	v_add_f32_e32 v12, v24, v27
	v_add_f32_e32 v24, v25, v26
	v_add_f32_e32 v22, v22, v23
	s_waitcnt lgkmcnt(0)
	v_add_f32_e32 v20, v20, v21
	v_add_f32_e32 v21, v28, v29
	v_cndmask_b32_e64 v22, v22, v24, s[42:43]
	v_add_f32_e32 v13, v30, v31
	v_cndmask_b32_e64 v21, v22, v21, s[44:45]
	v_cndmask_b32_e64 v13, v21, v13, s[46:47]
	v_cndmask_b32_e64 v12, v13, v12, s[48:49]
	v_cndmask_b32_e64 v11, v12, v11, s[50:51]
	v_cndmask_b32_e64 v10, v11, v10, s[52:53]
	v_cndmask_b32_e64 v10, v10, v20, s[54:55]
	s_mov_b32 s4, 0xf800000
	v_mul_f32_e32 v11, 0x4f800000, v10
	v_cmp_gt_f32_e32 vcc, s4, v10
	s_nop 1
	v_cndmask_b32_e32 v10, v10, v11, vcc
	v_sqrt_f32_e32 v11, v10
	s_nop 0
	v_add_u32_e32 v12, -1, v11
	v_fma_f32 v13, -v12, v11, v10
	v_cmp_ge_f32_e64 s[56:57], 0, v13
	v_add_u32_e32 v13, 1, v11
	s_nop 0
	v_cndmask_b32_e64 v12, v11, v12, s[56:57]
	v_fma_f32 v11, -v13, v11, v10
	v_cmp_lt_f32_e64 s[56:57], 0, v11
	s_nop 1
	v_cndmask_b32_e64 v11, v12, v13, s[56:57]
	v_mul_f32_e32 v12, 0x37800000, v11
	v_cndmask_b32_e32 v11, v11, v12, vcc
	v_mov_b32_e32 v12, 0x260
	v_cmp_class_f32_e32 vcc, v10, v12
	s_nop 1
	v_cndmask_b32_e32 v10, v11, v10, vcc
	v_max_f32_e32 v10, 0x2b8cbccc, v10
	v_div_scale_f32 v11, s[4:5], v10, v10, 1.0
	v_rcp_f32_e32 v12, v11
	s_nop 0
	v_fma_f32 v13, -v11, v12, 1.0
	v_fmac_f32_e32 v12, v13, v12
	v_div_scale_f32 v13, vcc, 1.0, v10, 1.0
	v_mul_f32_e32 v20, v13, v12
	v_fma_f32 v21, -v11, v20, v13
	v_fmac_f32_e32 v20, v21, v12
	v_fma_f32 v11, -v11, v20, v13
	v_div_fmas_f32 v11, v11, v12, v20
	v_div_fixup_f32 v10, v11, v10, 1.0
	global_store_dword v[6:7], v10, off
	s_branch .LBB0_1165

; __device__ __forceinline__ void prep_phase(const Ctx& C, const PV& P, unsigned char* smem) {
;     ...
;                 for (int kk = ks * 64; kk < ks * 64 + 64; ++kk) {
;                     const float w = aw[(size_t)(half * 512 + kk) * 9216 + n0 + nl];
; #pragma unroll
;                     for (int b = 0; b < 18; ++b) acc[b] += sc[b * 512 + kk] * w;
;                 }
.LBB0_2114:
	v_mov_b32_e32 v66, v26
	v_mov_b32_e32 v67, v27
	s_mov_b64 s[8:9], 0x9000
	global_load_dword v58, v[66:67], off
	v_lshl_add_u64 v[66:67], v[66:67], 0, s[8:9]
	global_load_dword v59, v[66:67], off
	v_lshl_add_u64 v[66:67], v[66:67], 0, s[8:9]
	global_load_dword v60, v[66:67], off
	v_lshl_add_u64 v[66:67], v[66:67], 0, s[8:9]
	global_load_dword v61, v[66:67], off
	v_lshl_add_u64 v[66:67], v[66:67], 0, s[8:9]
	global_load_dword v62, v[66:67], off
	v_lshl_add_u64 v[66:67], v[66:67], 0, s[8:9]
	global_load_dword v63, v[66:67], off
	v_lshl_add_u64 v[66:67], v[66:67], 0, s[8:9]
	global_load_dword v64, v[66:67], off
	v_lshl_add_u64 v[66:67], v[66:67], 0, s[8:9]
	global_load_dword v65, v[66:67], off
	v_lshl_add_u64 v[66:67], v[66:67], 0, s[8:9]
	s_mov_b32 s14, 7
.Lprep_a_loop:
	ds_read2st64_b32 v[40:41], v1 offset1:8
	ds_read2st64_b32 v[42:43], v1 offset0:16 offset1:24
	ds_read2st64_b32 v[44:45], v1 offset0:32 offset1:40
	ds_read2st64_b32 v[46:47], v1 offset0:48 offset1:56
	ds_read2st64_b32 v[48:49], v1 offset0:64 offset1:72
	ds_read2st64_b32 v[50:51], v1 offset0:80 offset1:88
	ds_read2st64_b32 v[52:53], v1 offset0:96 offset1:104
	ds_read2st64_b32 v[54:55], v1 offset0:112 offset1:120
	ds_read2st64_b32 v[56:57], v1 offset0:128 offset1:136
	v_add_u32_e32 v1, 4, v1
	s_waitcnt vmcnt(7)
	v_mov_b32_e32 v38, v58
	global_load_dword v58, v[66:67], off
	v_lshl_add_u64 v[66:67], v[66:67], 0, s[8:9]
	s_waitcnt lgkmcnt(8)
	v_pk_fma_f32 v[10:11], v[38:39], v[40:41], v[10:11] op_sel_hi:[0,1,1]
	s_waitcnt lgkmcnt(7)
	v_pk_fma_f32 v[12:13], v[38:39], v[42:43], v[12:13] op_sel_hi:[0,1,1]
	s_waitcnt lgkmcnt(6)
	v_pk_fma_f32 v[14:15], v[38:39], v[44:45], v[14:15] op_sel_hi:[0,1,1]
	s_waitcnt lgkmcnt(5)
	v_pk_fma_f32 v[16:17], v[38:39], v[46:47], v[16:17] op_sel_hi:[0,1,1]
	s_waitcnt lgkmcnt(4)
	v_pk_fma_f32 v[18:19], v[38:39], v[48:49], v[18:19] op_sel_hi:[0,1,1]
	s_waitcnt lgkmcnt(3)
	v_pk_fma_f32 v[20:21], v[38:39], v[50:51], v[20:21] op_sel_hi:[0,1,1]
	s_waitcnt lgkmcnt(2)
	v_pk_fma_f32 v[22:23], v[38:39], v[52:53], v[22:23] op_sel_hi:[0,1,1]
	s_waitcnt lgkmcnt(1)
	v_pk_fma_f32 v[24:25], v[38:39], v[54:55], v[24:25] op_sel_hi:[0,1,1]
	s_waitcnt lgkmcnt(0)
	v_pk_fma_f32 v[8:9], v[38:39], v[56:57], v[8:9] op_sel_hi:[0,1,1]
	ds_read2st64_b32 v[40:41], v1 offset1:8
	ds_read2st64_b32 v[42:43], v1 offset0:16 offset1:24
	ds_read2st64_b32 v[44:45], v1 offset0:32 offset1:40
	ds_read2st64_b32 v[46:47], v1 offset0:48 offset1:56
	ds_read2st64_b32 v[48:49], v1 offset0:64 offset1:72
	ds_read2st64_b32 v[50:51], v1 offset0:80 offset1:88
	ds_read2st64_b32 v[52:53], v1 offset0:96 offset1:104
	ds_read2st64_b32 v[54:55], v1 offset0:112 offset1:120
	ds_read2st64_b32 v[56:57], v1 offset0:128 offset1:136
	v_add_u32_e32 v1, 4, v1
	s_waitcnt vmcnt(7)
	v_mov_b32_e32 v38, v59
	global_load_dword v59, v[66:67], off
	v_lshl_add_u64 v[66:67], v[66:67], 0, s[8:9]
	s_waitcnt lgkmcnt(8)
	v_pk_fma_f32 v[10:11], v[38:39], v[40:41], v[10:11] op_sel_hi:[0,1,1]
	s_waitcnt lgkmcnt(7)
	v_pk_fma_f32 v[12:13], v[38:39], v[42:43], v[12:13] op_sel_hi:[0,1,1]
	s_waitcnt lgkmcnt(6)
	v_pk_fma_f32 v[14:15], v[38:39], v[44:45], v[14:15] op_sel_hi:[0,1,1]
	s_waitcnt lgkmcnt(5)
	v_pk_fma_f32 v[16:17], v[38:39], v[46:47], v[16:17] op_sel_hi:[0,1,1]
	s_waitcnt lgkmcnt(4)
	v_pk_fma_f32 v[18:19], v[38:39], v[48:49], v[18:19] op_sel_hi:[0,1,1]
	s_waitcnt lgkmcnt(3)
	v_pk_fma_f32 v[20:21], v[38:39], v[50:51], v[20:21] op_sel_hi:[0,1,1]
	s_waitcnt lgkmcnt(2)
	v_pk_fma_f32 v[22:23], v[38:39], v[52:53], v[22:23] op_sel_hi:[0,1,1]
	s_waitcnt lgkmcnt(1)
	v_pk_fma_f32 v[24:25], v[38:39], v[54:55], v[24:25] op_sel_hi:[0,1,1]
	s_waitcnt lgkmcnt(0)
	v_pk_fma_f32 v[8:9], v[38:39], v[56:57], v[8:9] op_sel_hi:[0,1,1]
	ds_read2st64_b32 v[40:41], v1 offset1:8
	ds_read2st64_b32 v[42:43], v1 offset0:16 offset1:24
	ds_read2st64_b32 v[44:45], v1 offset0:32 offset1:40
	ds_read2st64_b32 v[46:47], v1 offset0:48 offset1:56
	ds_read2st64_b32 v[48:49], v1 offset0:64 offset1:72
	ds_read2st64_b32 v[50:51], v1 offset0:80 offset1:88
	ds_read2st64_b32 v[52:53], v1 offset0:96 offset1:104
	ds_read2st64_b32 v[54:55], v1 offset0:112 offset1:120
	ds_read2st64_b32 v[56:57], v1 offset0:128 offset1:136
	v_add_u32_e32 v1, 4, v1
	s_waitcnt vmcnt(7)
	v_mov_b32_e32 v38, v60
	global_load_dword v60, v[66:67], off
	v_lshl_add_u64 v[66:67], v[66:67], 0, s[8:9]
	s_waitcnt lgkmcnt(8)
	v_pk_fma_f32 v[10:11], v[38:39], v[40:41], v[10:11] op_sel_hi:[0,1,1]
	s_waitcnt lgkmcnt(7)
	v_pk_fma_f32 v[12:13], v[38:39], v[42:43], v[12:13] op_sel_hi:[0,1,1]
	s_waitcnt lgkmcnt(6)
	v_pk_fma_f32 v[14:15], v[38:39], v[44:45], v[14:15] op_sel_hi:[0,1,1]
	s_waitcnt lgkmcnt(5)
	v_pk_fma_f32 v[16:17], v[38:39], v[46:47], v[16:17] op_sel_hi:[0,1,1]
	s_waitcnt lgkmcnt(4)
	v_pk_fma_f32 v[18:19], v[38:39], v[48:49], v[18:19] op_sel_hi:[0,1,1]
	s_waitcnt lgkmcnt(3)
	v_pk_fma_f32 v[20:21], v[38:39], v[50:51], v[20:21] op_sel_hi:[0,1,1]
	s_waitcnt lgkmcnt(2)
	v_pk_fma_f32 v[22:23], v[38:39], v[52:53], v[22:23] op_sel_hi:[0,1,1]
	s_waitcnt lgkmcnt(1)
	v_pk_fma_f32 v[24:25], v[38:39], v[54:55], v[24:25] op_sel_hi:[0,1,1]
	s_waitcnt lgkmcnt(0)
	v_pk_fma_f32 v[8:9], v[38:39], v[56:57], v[8:9] op_sel_hi:[0,1,1]
	ds_read2st64_b32 v[40:41], v1 offset1:8
	ds_read2st64_b32 v[42:43], v1 offset0:16 offset1:24
	ds_read2st64_b32 v[44:45], v1 offset0:32 offset1:40
	ds_read2st64_b32 v[46:47], v1 offset0:48 offset1:56
	ds_read2st64_b32 v[48:49], v1 offset0:64 offset1:72
	ds_read2st64_b32 v[50:51], v1 offset0:80 offset1:88
	ds_read2st64_b32 v[52:53], v1 offset0:96 offset1:104
	ds_read2st64_b32 v[54:55], v1 offset0:112 offset1:120
	ds_read2st64_b32 v[56:57], v1 offset0:128 offset1:136
	v_add_u32_e32 v1, 4, v1
	s_waitcnt vmcnt(7)
; __device__ __forceinline__ void prep_phase(const Ctx& C, const PV& P, unsigned char* smem) {
;     ...
;                 for (int kk = ks * 64; kk < ks * 64 + 64; ++kk) {
;                     const float w = aw[(size_t)(half * 512 + kk) * 9216 + n0 + nl];
; #pragma unroll
;                     for (int b = 0; b < 18; ++b) acc[b] += sc[b * 512 + kk] * w;
;                 }
	v_mov_b32_e32 v38, v61
	global_load_dword v61, v[66:67], off
	v_lshl_add_u64 v[66:67], v[66:67], 0, s[8:9]
	s_waitcnt lgkmcnt(8)
	v_pk_fma_f32 v[10:11], v[38:39], v[40:41], v[10:11] op_sel_hi:[0,1,1]
	s_waitcnt lgkmcnt(7)
	v_pk_fma_f32 v[12:13], v[38:39], v[42:43], v[12:13] op_sel_hi:[0,1,1]
	s_waitcnt lgkmcnt(6)
	v_pk_fma_f32 v[14:15], v[38:39], v[44:45], v[14:15] op_sel_hi:[0,1,1]
	s_waitcnt lgkmcnt(5)
	v_pk_fma_f32 v[16:17], v[38:39], v[46:47], v[16:17] op_sel_hi:[0,1,1]
	s_waitcnt lgkmcnt(4)
	v_pk_fma_f32 v[18:19], v[38:39], v[48:49], v[18:19] op_sel_hi:[0,1,1]
	s_waitcnt lgkmcnt(3)
	v_pk_fma_f32 v[20:21], v[38:39], v[50:51], v[20:21] op_sel_hi:[0,1,1]
	s_waitcnt lgkmcnt(2)
	v_pk_fma_f32 v[22:23], v[38:39], v[52:53], v[22:23] op_sel_hi:[0,1,1]
	s_waitcnt lgkmcnt(1)
	v_pk_fma_f32 v[24:25], v[38:39], v[54:55], v[24:25] op_sel_hi:[0,1,1]
	s_waitcnt lgkmcnt(0)
	v_pk_fma_f32 v[8:9], v[38:39], v[56:57], v[8:9] op_sel_hi:[0,1,1]
	ds_read2st64_b32 v[40:41], v1 offset1:8
	ds_read2st64_b32 v[42:43], v1 offset0:16 offset1:24
	ds_read2st64_b32 v[44:45], v1 offset0:32 offset1:40
	ds_read2st64_b32 v[46:47], v1 offset0:48 offset1:56
	ds_read2st64_b32 v[48:49], v1 offset0:64 offset1:72
	ds_read2st64_b32 v[50:51], v1 offset0:80 offset1:88
	ds_read2st64_b32 v[52:53], v1 offset0:96 offset1:104
	ds_read2st64_b32 v[54:55], v1 offset0:112 offset1:120
	ds_read2st64_b32 v[56:57], v1 offset0:128 offset1:136
	v_add_u32_e32 v1, 4, v1
	s_waitcnt vmcnt(7)
	v_mov_b32_e32 v38, v62
	global_load_dword v62, v[66:67], off
	v_lshl_add_u64 v[66:67], v[66:67], 0, s[8:9]
	s_waitcnt lgkmcnt(8)
	v_pk_fma_f32 v[10:11], v[38:39], v[40:41], v[10:11] op_sel_hi:[0,1,1]
	s_waitcnt lgkmcnt(7)
	v_pk_fma_f32 v[12:13], v[38:39], v[42:43], v[12:13] op_sel_hi:[0,1,1]
	s_waitcnt lgkmcnt(6)
	v_pk_fma_f32 v[14:15], v[38:39], v[44:45], v[14:15] op_sel_hi:[0,1,1]
	s_waitcnt lgkmcnt(5)
	v_pk_fma_f32 v[16:17], v[38:39], v[46:47], v[16:17] op_sel_hi:[0,1,1]
	s_waitcnt lgkmcnt(4)
	v_pk_fma_f32 v[18:19], v[38:39], v[48:49], v[18:19] op_sel_hi:[0,1,1]
	s_waitcnt lgkmcnt(3)
	v_pk_fma_f32 v[20:21], v[38:39], v[50:51], v[20:21] op_sel_hi:[0,1,1]
	s_waitcnt lgkmcnt(2)
	v_pk_fma_f32 v[22:23], v[38:39], v[52:53], v[22:23] op_sel_hi:[0,1,1]
	s_waitcnt lgkmcnt(1)
	v_pk_fma_f32 v[24:25], v[38:39], v[54:55], v[24:25] op_sel_hi:[0,1,1]
	s_waitcnt lgkmcnt(0)
	v_pk_fma_f32 v[8:9], v[38:39], v[56:57], v[8:9] op_sel_hi:[0,1,1]
	ds_read2st64_b32 v[40:41], v1 offset1:8
	ds_read2st64_b32 v[42:43], v1 offset0:16 offset1:24
	ds_read2st64_b32 v[44:45], v1 offset0:32 offset1:40
	ds_read2st64_b32 v[46:47], v1 offset0:48 offset1:56
	ds_read2st64_b32 v[48:49], v1 offset0:64 offset1:72
	ds_read2st64_b32 v[50:51], v1 offset0:80 offset1:88
	ds_read2st64_b32 v[52:53], v1 offset0:96 offset1:104
	ds_read2st64_b32 v[54:55], v1 offset0:112 offset1:120
	ds_read2st64_b32 v[56:57], v1 offset0:128 offset1:136
	v_add_u32_e32 v1, 4, v1
	s_waitcnt vmcnt(7)
	v_mov_b32_e32 v38, v63
	global_load_dword v63, v[66:67], off
	v_lshl_add_u64 v[66:67], v[66:67], 0, s[8:9]
	s_waitcnt lgkmcnt(8)
	v_pk_fma_f32 v[10:11], v[38:39], v[40:41], v[10:11] op_sel_hi:[0,1,1]
	s_waitcnt lgkmcnt(7)
	v_pk_fma_f32 v[12:13], v[38:39], v[42:43], v[12:13] op_sel_hi:[0,1,1]
	s_waitcnt lgkmcnt(6)
	v_pk_fma_f32 v[14:15], v[38:39], v[44:45], v[14:15] op_sel_hi:[0,1,1]
	s_waitcnt lgkmcnt(5)
	v_pk_fma_f32 v[16:17], v[38:39], v[46:47], v[16:17] op_sel_hi:[0,1,1]
	s_waitcnt lgkmcnt(4)
	v_pk_fma_f32 v[18:19], v[38:39], v[48:49], v[18:19] op_sel_hi:[0,1,1]
	s_waitcnt lgkmcnt(3)
	v_pk_fma_f32 v[20:21], v[38:39], v[50:51], v[20:21] op_sel_hi:[0,1,1]
	s_waitcnt lgkmcnt(2)
	v_pk_fma_f32 v[22:23], v[38:39], v[52:53], v[22:23] op_sel_hi:[0,1,1]
	s_waitcnt lgkmcnt(1)
	v_pk_fma_f32 v[24:25], v[38:39], v[54:55], v[24:25] op_sel_hi:[0,1,1]
	s_waitcnt lgkmcnt(0)
	v_pk_fma_f32 v[8:9], v[38:39], v[56:57], v[8:9] op_sel_hi:[0,1,1]
	ds_read2st64_b32 v[40:41], v1 offset1:8
	ds_read2st64_b32 v[42:43], v1 offset0:16 offset1:24
	ds_read2st64_b32 v[44:45], v1 offset0:32 offset1:40
	ds_read2st64_b32 v[46:47], v1 offset0:48 offset1:56
	ds_read2st64_b32 v[48:49], v1 offset0:64 offset1:72
	ds_read2st64_b32 v[50:51], v1 offset0:80 offset1:88
	ds_read2st64_b32 v[52:53], v1 offset0:96 offset1:104
	ds_read2st64_b32 v[54:55], v1 offset0:112 offset1:120
	ds_read2st64_b32 v[56:57], v1 offset0:128 offset1:136
	v_add_u32_e32 v1, 4, v1
	s_waitcnt vmcnt(7)
	v_mov_b32_e32 v38, v64
	global_load_dword v64, v[66:67], off
	v_lshl_add_u64 v[66:67], v[66:67], 0, s[8:9]
	s_waitcnt lgkmcnt(8)
	v_pk_fma_f32 v[10:11], v[38:39], v[40:41], v[10:11] op_sel_hi:[0,1,1]
	s_waitcnt lgkmcnt(7)
	v_pk_fma_f32 v[12:13], v[38:39], v[42:43], v[12:13] op_sel_hi:[0,1,1]
	s_waitcnt lgkmcnt(6)
	v_pk_fma_f32 v[14:15], v[38:39], v[44:45], v[14:15] op_sel_hi:[0,1,1]
	s_waitcnt lgkmcnt(5)
	v_pk_fma_f32 v[16:17], v[38:39], v[46:47], v[16:17] op_sel_hi:[0,1,1]
	s_waitcnt lgkmcnt(4)
	v_pk_fma_f32 v[18:19], v[38:39], v[48:49], v[18:19] op_sel_hi:[0,1,1]
	s_waitcnt lgkmcnt(3)
	v_pk_fma_f32 v[20:21], v[38:39], v[50:51], v[20:21] op_sel_hi:[0,1,1]
	s_waitcnt lgkmcnt(2)
	v_pk_fma_f32 v[22:23], v[38:39], v[52:53], v[22:23] op_sel_hi:[0,1,1]
	s_waitcnt lgkmcnt(1)
	v_pk_fma_f32 v[24:25], v[38:39], v[54:55], v[24:25] op_sel_hi:[0,1,1]
	s_waitcnt lgkmcnt(0)
	v_pk_fma_f32 v[8:9], v[38:39], v[56:57], v[8:9] op_sel_hi:[0,1,1]
	ds_read2st64_b32 v[40:41], v1 offset1:8
	ds_read2st64_b32 v[42:43], v1 offset0:16 offset1:24
	ds_read2st64_b32 v[44:45], v1 offset0:32 offset1:40
	ds_read2st64_b32 v[46:47], v1 offset0:48 offset1:56
	ds_read2st64_b32 v[48:49], v1 offset0:64 offset1:72
	ds_read2st64_b32 v[50:51], v1 offset0:80 offset1:88
	ds_read2st64_b32 v[52:53], v1 offset0:96 offset1:104
	ds_read2st64_b32 v[54:55], v1 offset0:112 offset1:120
	ds_read2st64_b32 v[56:57], v1 offset0:128 offset1:136
	v_add_u32_e32 v1, 4, v1
	s_waitcnt vmcnt(7)
	v_mov_b32_e32 v38, v65
	global_load_dword v65, v[66:67], off
	v_lshl_add_u64 v[66:67], v[66:67], 0, s[8:9]
	s_waitcnt lgkmcnt(8)
	v_pk_fma_f32 v[10:11], v[38:39], v[40:41], v[10:11] op_sel_hi:[0,1,1]
	s_waitcnt lgkmcnt(7)
	v_pk_fma_f32 v[12:13], v[38:39], v[42:43], v[12:13] op_sel_hi:[0,1,1]
	s_waitcnt lgkmcnt(6)
	v_pk_fma_f32 v[14:15], v[38:39], v[44:45], v[14:15] op_sel_hi:[0,1,1]
	s_waitcnt lgkmcnt(5)
	v_pk_fma_f32 v[16:17], v[38:39], v[46:47], v[16:17] op_sel_hi:[0,1,1]
	s_waitcnt lgkmcnt(4)
	v_pk_fma_f32 v[18:19], v[38:39], v[48:49], v[18:19] op_sel_hi:[0,1,1]
	s_waitcnt lgkmcnt(3)
	v_pk_fma_f32 v[20:21], v[38:39], v[50:51], v[20:21] op_sel_hi:[0,1,1]
	s_waitcnt lgkmcnt(2)
	v_pk_fma_f32 v[22:23], v[38:39], v[52:53], v[22:23] op_sel_hi:[0,1,1]
	s_waitcnt lgkmcnt(1)
	v_pk_fma_f32 v[24:25], v[38:39], v[54:55], v[24:25] op_sel_hi:[0,1,1]
	s_waitcnt lgkmcnt(0)
	v_pk_fma_f32 v[8:9], v[38:39], v[56:57], v[8:9] op_sel_hi:[0,1,1]
	s_sub_i32 s14, s14, 1
	s_cmp_lg_u32 s14, 0
	s_cbranch_scc1 .Lprep_a_loop
; __device__ __forceinline__ void prep_phase(const Ctx& C, const PV& P, unsigned char* smem) {
;     ...
;                 for (int kk = ks * 64; kk < ks * 64 + 64; ++kk) {
;                     const float w = aw[(size_t)(half * 512 + kk) * 9216 + n0 + nl];
; #pragma unroll
;                     for (int b = 0; b < 18; ++b) acc[b] += sc[b * 512 + kk] * w;
;                 }
	ds_read2st64_b32 v[40:41], v1 offset1:8
	ds_read2st64_b32 v[42:43], v1 offset0:16 offset1:24
	ds_read2st64_b32 v[44:45], v1 offset0:32 offset1:40
	ds_read2st64_b32 v[46:47], v1 offset0:48 offset1:56
	ds_read2st64_b32 v[48:49], v1 offset0:64 offset1:72
	ds_read2st64_b32 v[50:51], v1 offset0:80 offset1:88
	ds_read2st64_b32 v[52:53], v1 offset0:96 offset1:104
	ds_read2st64_b32 v[54:55], v1 offset0:112 offset1:120
	ds_read2st64_b32 v[56:57], v1 offset0:128 offset1:136
	v_add_u32_e32 v1, 4, v1
	s_waitcnt vmcnt(7)
	v_mov_b32_e32 v38, v58
	s_waitcnt lgkmcnt(8)
	v_pk_fma_f32 v[10:11], v[38:39], v[40:41], v[10:11] op_sel_hi:[0,1,1]
	s_waitcnt lgkmcnt(7)
	v_pk_fma_f32 v[12:13], v[38:39], v[42:43], v[12:13] op_sel_hi:[0,1,1]
	s_waitcnt lgkmcnt(6)
	v_pk_fma_f32 v[14:15], v[38:39], v[44:45], v[14:15] op_sel_hi:[0,1,1]
	s_waitcnt lgkmcnt(5)
	v_pk_fma_f32 v[16:17], v[38:39], v[46:47], v[16:17] op_sel_hi:[0,1,1]
	s_waitcnt lgkmcnt(4)
	v_pk_fma_f32 v[18:19], v[38:39], v[48:49], v[18:19] op_sel_hi:[0,1,1]
	s_waitcnt lgkmcnt(3)
	v_pk_fma_f32 v[20:21], v[38:39], v[50:51], v[20:21] op_sel_hi:[0,1,1]
	s_waitcnt lgkmcnt(2)
	v_pk_fma_f32 v[22:23], v[38:39], v[52:53], v[22:23] op_sel_hi:[0,1,1]
	s_waitcnt lgkmcnt(1)
	v_pk_fma_f32 v[24:25], v[38:39], v[54:55], v[24:25] op_sel_hi:[0,1,1]
	s_waitcnt lgkmcnt(0)
	v_pk_fma_f32 v[8:9], v[38:39], v[56:57], v[8:9] op_sel_hi:[0,1,1]
	ds_read2st64_b32 v[40:41], v1 offset1:8
	ds_read2st64_b32 v[42:43], v1 offset0:16 offset1:24
	ds_read2st64_b32 v[44:45], v1 offset0:32 offset1:40
	ds_read2st64_b32 v[46:47], v1 offset0:48 offset1:56
	ds_read2st64_b32 v[48:49], v1 offset0:64 offset1:72
	ds_read2st64_b32 v[50:51], v1 offset0:80 offset1:88
	ds_read2st64_b32 v[52:53], v1 offset0:96 offset1:104
	ds_read2st64_b32 v[54:55], v1 offset0:112 offset1:120
	ds_read2st64_b32 v[56:57], v1 offset0:128 offset1:136
	v_add_u32_e32 v1, 4, v1
	s_waitcnt vmcnt(6)
	v_mov_b32_e32 v38, v59
	s_waitcnt lgkmcnt(8)
	v_pk_fma_f32 v[10:11], v[38:39], v[40:41], v[10:11] op_sel_hi:[0,1,1]
	s_waitcnt lgkmcnt(7)
	v_pk_fma_f32 v[12:13], v[38:39], v[42:43], v[12:13] op_sel_hi:[0,1,1]
	s_waitcnt lgkmcnt(6)
	v_pk_fma_f32 v[14:15], v[38:39], v[44:45], v[14:15] op_sel_hi:[0,1,1]
	s_waitcnt lgkmcnt(5)
	v_pk_fma_f32 v[16:17], v[38:39], v[46:47], v[16:17] op_sel_hi:[0,1,1]
	s_waitcnt lgkmcnt(4)
	v_pk_fma_f32 v[18:19], v[38:39], v[48:49], v[18:19] op_sel_hi:[0,1,1]
	s_waitcnt lgkmcnt(3)
	v_pk_fma_f32 v[20:21], v[38:39], v[50:51], v[20:21] op_sel_hi:[0,1,1]
	s_waitcnt lgkmcnt(2)
	v_pk_fma_f32 v[22:23], v[38:39], v[52:53], v[22:23] op_sel_hi:[0,1,1]
	s_waitcnt lgkmcnt(1)
	v_pk_fma_f32 v[24:25], v[38:39], v[54:55], v[24:25] op_sel_hi:[0,1,1]
	s_waitcnt lgkmcnt(0)
	v_pk_fma_f32 v[8:9], v[38:39], v[56:57], v[8:9] op_sel_hi:[0,1,1]
	ds_read2st64_b32 v[40:41], v1 offset1:8
	ds_read2st64_b32 v[42:43], v1 offset0:16 offset1:24
	ds_read2st64_b32 v[44:45], v1 offset0:32 offset1:40
	ds_read2st64_b32 v[46:47], v1 offset0:48 offset1:56
	ds_read2st64_b32 v[48:49], v1 offset0:64 offset1:72
	ds_read2st64_b32 v[50:51], v1 offset0:80 offset1:88
	ds_read2st64_b32 v[52:53], v1 offset0:96 offset1:104
	ds_read2st64_b32 v[54:55], v1 offset0:112 offset1:120
	ds_read2st64_b32 v[56:57], v1 offset0:128 offset1:136
	v_add_u32_e32 v1, 4, v1
	s_waitcnt vmcnt(5)
	v_mov_b32_e32 v38, v60
	s_waitcnt lgkmcnt(8)
	v_pk_fma_f32 v[10:11], v[38:39], v[40:41], v[10:11] op_sel_hi:[0,1,1]
	s_waitcnt lgkmcnt(7)
	v_pk_fma_f32 v[12:13], v[38:39], v[42:43], v[12:13] op_sel_hi:[0,1,1]
	s_waitcnt lgkmcnt(6)
	v_pk_fma_f32 v[14:15], v[38:39], v[44:45], v[14:15] op_sel_hi:[0,1,1]
	s_waitcnt lgkmcnt(5)
	v_pk_fma_f32 v[16:17], v[38:39], v[46:47], v[16:17] op_sel_hi:[0,1,1]
	s_waitcnt lgkmcnt(4)
	v_pk_fma_f32 v[18:19], v[38:39], v[48:49], v[18:19] op_sel_hi:[0,1,1]
	s_waitcnt lgkmcnt(3)
	v_pk_fma_f32 v[20:21], v[38:39], v[50:51], v[20:21] op_sel_hi:[0,1,1]
	s_waitcnt lgkmcnt(2)
	v_pk_fma_f32 v[22:23], v[38:39], v[52:53], v[22:23] op_sel_hi:[0,1,1]
	s_waitcnt lgkmcnt(1)
	v_pk_fma_f32 v[24:25], v[38:39], v[54:55], v[24:25] op_sel_hi:[0,1,1]
	s_waitcnt lgkmcnt(0)
	v_pk_fma_f32 v[8:9], v[38:39], v[56:57], v[8:9] op_sel_hi:[0,1,1]
	ds_read2st64_b32 v[40:41], v1 offset1:8
	ds_read2st64_b32 v[42:43], v1 offset0:16 offset1:24
	ds_read2st64_b32 v[44:45], v1 offset0:32 offset1:40
	ds_read2st64_b32 v[46:47], v1 offset0:48 offset1:56
	ds_read2st64_b32 v[48:49], v1 offset0:64 offset1:72
	ds_read2st64_b32 v[50:51], v1 offset0:80 offset1:88
	ds_read2st64_b32 v[52:53], v1 offset0:96 offset1:104
	ds_read2st64_b32 v[54:55], v1 offset0:112 offset1:120
	ds_read2st64_b32 v[56:57], v1 offset0:128 offset1:136
	v_add_u32_e32 v1, 4, v1
	s_waitcnt vmcnt(4)
	v_mov_b32_e32 v38, v61
	s_waitcnt lgkmcnt(8)
	v_pk_fma_f32 v[10:11], v[38:39], v[40:41], v[10:11] op_sel_hi:[0,1,1]
	s_waitcnt lgkmcnt(7)
	v_pk_fma_f32 v[12:13], v[38:39], v[42:43], v[12:13] op_sel_hi:[0,1,1]
	s_waitcnt lgkmcnt(6)
	v_pk_fma_f32 v[14:15], v[38:39], v[44:45], v[14:15] op_sel_hi:[0,1,1]
	s_waitcnt lgkmcnt(5)
	v_pk_fma_f32 v[16:17], v[38:39], v[46:47], v[16:17] op_sel_hi:[0,1,1]
	s_waitcnt lgkmcnt(4)
	v_pk_fma_f32 v[18:19], v[38:39], v[48:49], v[18:19] op_sel_hi:[0,1,1]
	s_waitcnt lgkmcnt(3)
	v_pk_fma_f32 v[20:21], v[38:39], v[50:51], v[20:21] op_sel_hi:[0,1,1]
	s_waitcnt lgkmcnt(2)
	v_pk_fma_f32 v[22:23], v[38:39], v[52:53], v[22:23] op_sel_hi:[0,1,1]
	s_waitcnt lgkmcnt(1)
	v_pk_fma_f32 v[24:25], v[38:39], v[54:55], v[24:25] op_sel_hi:[0,1,1]
	s_waitcnt lgkmcnt(0)
; __device__ __forceinline__ void prep_phase(const Ctx& C, const PV& P, unsigned char* smem) {
;     ...
;                 for (int kk = ks * 64; kk < ks * 64 + 64; ++kk) {
;                     const float w = aw[(size_t)(half * 512 + kk) * 9216 + n0 + nl];
; #pragma unroll
;                     for (int b = 0; b < 18; ++b) acc[b] += sc[b * 512 + kk] * w;
;                 }
	v_pk_fma_f32 v[8:9], v[38:39], v[56:57], v[8:9] op_sel_hi:[0,1,1]
	ds_read2st64_b32 v[40:41], v1 offset1:8
	ds_read2st64_b32 v[42:43], v1 offset0:16 offset1:24
	ds_read2st64_b32 v[44:45], v1 offset0:32 offset1:40
	ds_read2st64_b32 v[46:47], v1 offset0:48 offset1:56
	ds_read2st64_b32 v[48:49], v1 offset0:64 offset1:72
	ds_read2st64_b32 v[50:51], v1 offset0:80 offset1:88
	ds_read2st64_b32 v[52:53], v1 offset0:96 offset1:104
	ds_read2st64_b32 v[54:55], v1 offset0:112 offset1:120
	ds_read2st64_b32 v[56:57], v1 offset0:128 offset1:136
	v_add_u32_e32 v1, 4, v1
	s_waitcnt vmcnt(3)
	v_mov_b32_e32 v38, v62
	s_waitcnt lgkmcnt(8)
	v_pk_fma_f32 v[10:11], v[38:39], v[40:41], v[10:11] op_sel_hi:[0,1,1]
	s_waitcnt lgkmcnt(7)
	v_pk_fma_f32 v[12:13], v[38:39], v[42:43], v[12:13] op_sel_hi:[0,1,1]
	s_waitcnt lgkmcnt(6)
	v_pk_fma_f32 v[14:15], v[38:39], v[44:45], v[14:15] op_sel_hi:[0,1,1]
	s_waitcnt lgkmcnt(5)
	v_pk_fma_f32 v[16:17], v[38:39], v[46:47], v[16:17] op_sel_hi:[0,1,1]
	s_waitcnt lgkmcnt(4)
	v_pk_fma_f32 v[18:19], v[38:39], v[48:49], v[18:19] op_sel_hi:[0,1,1]
	s_waitcnt lgkmcnt(3)
	v_pk_fma_f32 v[20:21], v[38:39], v[50:51], v[20:21] op_sel_hi:[0,1,1]
	s_waitcnt lgkmcnt(2)
	v_pk_fma_f32 v[22:23], v[38:39], v[52:53], v[22:23] op_sel_hi:[0,1,1]
	s_waitcnt lgkmcnt(1)
	v_pk_fma_f32 v[24:25], v[38:39], v[54:55], v[24:25] op_sel_hi:[0,1,1]
	s_waitcnt lgkmcnt(0)
	v_pk_fma_f32 v[8:9], v[38:39], v[56:57], v[8:9] op_sel_hi:[0,1,1]
	ds_read2st64_b32 v[40:41], v1 offset1:8
	ds_read2st64_b32 v[42:43], v1 offset0:16 offset1:24
	ds_read2st64_b32 v[44:45], v1 offset0:32 offset1:40
	ds_read2st64_b32 v[46:47], v1 offset0:48 offset1:56
	ds_read2st64_b32 v[48:49], v1 offset0:64 offset1:72
	ds_read2st64_b32 v[50:51], v1 offset0:80 offset1:88
	ds_read2st64_b32 v[52:53], v1 offset0:96 offset1:104
	ds_read2st64_b32 v[54:55], v1 offset0:112 offset1:120
	ds_read2st64_b32 v[56:57], v1 offset0:128 offset1:136
	v_add_u32_e32 v1, 4, v1
	s_waitcnt vmcnt(2)
	v_mov_b32_e32 v38, v63
	s_waitcnt lgkmcnt(8)
	v_pk_fma_f32 v[10:11], v[38:39], v[40:41], v[10:11] op_sel_hi:[0,1,1]
	s_waitcnt lgkmcnt(7)
	v_pk_fma_f32 v[12:13], v[38:39], v[42:43], v[12:13] op_sel_hi:[0,1,1]
	s_waitcnt lgkmcnt(6)
	v_pk_fma_f32 v[14:15], v[38:39], v[44:45], v[14:15] op_sel_hi:[0,1,1]
	s_waitcnt lgkmcnt(5)
	v_pk_fma_f32 v[16:17], v[38:39], v[46:47], v[16:17] op_sel_hi:[0,1,1]
	s_waitcnt lgkmcnt(4)
	v_pk_fma_f32 v[18:19], v[38:39], v[48:49], v[18:19] op_sel_hi:[0,1,1]
	s_waitcnt lgkmcnt(3)
	v_pk_fma_f32 v[20:21], v[38:39], v[50:51], v[20:21] op_sel_hi:[0,1,1]
	s_waitcnt lgkmcnt(2)
	v_pk_fma_f32 v[22:23], v[38:39], v[52:53], v[22:23] op_sel_hi:[0,1,1]
	s_waitcnt lgkmcnt(1)
	v_pk_fma_f32 v[24:25], v[38:39], v[54:55], v[24:25] op_sel_hi:[0,1,1]
	s_waitcnt lgkmcnt(0)
	v_pk_fma_f32 v[8:9], v[38:39], v[56:57], v[8:9] op_sel_hi:[0,1,1]
	ds_read2st64_b32 v[40:41], v1 offset1:8
	ds_read2st64_b32 v[42:43], v1 offset0:16 offset1:24
	ds_read2st64_b32 v[44:45], v1 offset0:32 offset1:40
	ds_read2st64_b32 v[46:47], v1 offset0:48 offset1:56
	ds_read2st64_b32 v[48:49], v1 offset0:64 offset1:72
	ds_read2st64_b32 v[50:51], v1 offset0:80 offset1:88
	ds_read2st64_b32 v[52:53], v1 offset0:96 offset1:104
	ds_read2st64_b32 v[54:55], v1 offset0:112 offset1:120
	ds_read2st64_b32 v[56:57], v1 offset0:128 offset1:136
	v_add_u32_e32 v1, 4, v1
	s_waitcnt vmcnt(1)
	v_mov_b32_e32 v38, v64
	s_waitcnt lgkmcnt(8)
	v_pk_fma_f32 v[10:11], v[38:39], v[40:41], v[10:11] op_sel_hi:[0,1,1]
	s_waitcnt lgkmcnt(7)
	v_pk_fma_f32 v[12:13], v[38:39], v[42:43], v[12:13] op_sel_hi:[0,1,1]
	s_waitcnt lgkmcnt(6)
	v_pk_fma_f32 v[14:15], v[38:39], v[44:45], v[14:15] op_sel_hi:[0,1,1]
	s_waitcnt lgkmcnt(5)
	v_pk_fma_f32 v[16:17], v[38:39], v[46:47], v[16:17] op_sel_hi:[0,1,1]
	s_waitcnt lgkmcnt(4)
	v_pk_fma_f32 v[18:19], v[38:39], v[48:49], v[18:19] op_sel_hi:[0,1,1]
	s_waitcnt lgkmcnt(3)
	v_pk_fma_f32 v[20:21], v[38:39], v[50:51], v[20:21] op_sel_hi:[0,1,1]
	s_waitcnt lgkmcnt(2)
	v_pk_fma_f32 v[22:23], v[38:39], v[52:53], v[22:23] op_sel_hi:[0,1,1]
	s_waitcnt lgkmcnt(1)
	v_pk_fma_f32 v[24:25], v[38:39], v[54:55], v[24:25] op_sel_hi:[0,1,1]
	s_waitcnt lgkmcnt(0)
	v_pk_fma_f32 v[8:9], v[38:39], v[56:57], v[8:9] op_sel_hi:[0,1,1]
	ds_read2st64_b32 v[40:41], v1 offset1:8
	ds_read2st64_b32 v[42:43], v1 offset0:16 offset1:24
	ds_read2st64_b32 v[44:45], v1 offset0:32 offset1:40
	ds_read2st64_b32 v[46:47], v1 offset0:48 offset1:56
	ds_read2st64_b32 v[48:49], v1 offset0:64 offset1:72
	ds_read2st64_b32 v[50:51], v1 offset0:80 offset1:88
	ds_read2st64_b32 v[52:53], v1 offset0:96 offset1:104
	ds_read2st64_b32 v[54:55], v1 offset0:112 offset1:120
	ds_read2st64_b32 v[56:57], v1 offset0:128 offset1:136
	v_add_u32_e32 v1, 4, v1
	s_waitcnt vmcnt(0)
	v_mov_b32_e32 v38, v65
	s_waitcnt lgkmcnt(8)
	v_pk_fma_f32 v[10:11], v[38:39], v[40:41], v[10:11] op_sel_hi:[0,1,1]
	s_waitcnt lgkmcnt(7)
	v_pk_fma_f32 v[12:13], v[38:39], v[42:43], v[12:13] op_sel_hi:[0,1,1]
	s_waitcnt lgkmcnt(6)
	v_pk_fma_f32 v[14:15], v[38:39], v[44:45], v[14:15] op_sel_hi:[0,1,1]
	s_waitcnt lgkmcnt(5)
	v_pk_fma_f32 v[16:17], v[38:39], v[46:47], v[16:17] op_sel_hi:[0,1,1]
	s_waitcnt lgkmcnt(4)
	v_pk_fma_f32 v[18:19], v[38:39], v[48:49], v[18:19] op_sel_hi:[0,1,1]
	s_waitcnt lgkmcnt(3)
	v_pk_fma_f32 v[20:21], v[38:39], v[50:51], v[20:21] op_sel_hi:[0,1,1]
	s_waitcnt lgkmcnt(2)
	v_pk_fma_f32 v[22:23], v[38:39], v[52:53], v[22:23] op_sel_hi:[0,1,1]
	s_waitcnt lgkmcnt(1)
	v_pk_fma_f32 v[24:25], v[38:39], v[54:55], v[24:25] op_sel_hi:[0,1,1]
	s_waitcnt lgkmcnt(0)
	v_pk_fma_f32 v[8:9], v[38:39], v[56:57], v[8:9] op_sel_hi:[0,1,1]
	s_or_b64 exec, exec, s[12:13]
	s_barrier
	s_and_saveexec_b64 s[12:13], s[40:41]
	s_cbranch_execz .LBB0_2122
	s_mov_b64 s[14:15], 0
	v_mov_b32_e32 v1, v34
	v_mov_b32_e32 v38, v144
	s_branch .LBB0_2118

; __device__ __forceinline__ void prep_phase(const Ctx& C, const PV& P, unsigned char* smem) {
;     ...
;                 for (int kk = ks * 64; kk < ks * 64 + 64; ++kk) {
;                     const float w = aw[(size_t)(half * 512 + kk) * 9216 + n0 + nl];
; #pragma unroll
;                     for (int b = 0; b < 18; ++b) acc[b] += sc[b * 512 + kk] * w;
;                 }
.LBB0_2123:
	v_add_u32_e32 v29, 0x201, v28
	v_mad_i64_i32 v[66:67], s[6:7], v29, s72, v[26:27]
	s_mov_b64 s[8:9], 0x9000
	global_load_dword v58, v[66:67], off
	v_lshl_add_u64 v[66:67], v[66:67], 0, s[8:9]
	global_load_dword v59, v[66:67], off
	v_lshl_add_u64 v[66:67], v[66:67], 0, s[8:9]
	global_load_dword v60, v[66:67], off
	v_lshl_add_u64 v[66:67], v[66:67], 0, s[8:9]
	global_load_dword v61, v[66:67], off
	v_lshl_add_u64 v[66:67], v[66:67], 0, s[8:9]
	global_load_dword v62, v[66:67], off
	v_lshl_add_u64 v[66:67], v[66:67], 0, s[8:9]
	global_load_dword v63, v[66:67], off
	v_lshl_add_u64 v[66:67], v[66:67], 0, s[8:9]
	global_load_dword v64, v[66:67], off
	v_lshl_add_u64 v[66:67], v[66:67], 0, s[8:9]
	global_load_dword v65, v[66:67], off
	v_lshl_add_u64 v[66:67], v[66:67], 0, s[8:9]
	s_mov_b32 s14, 7
.Lprep_b_loop:
	ds_read2st64_b32 v[40:41], v1 offset1:8
	ds_read2st64_b32 v[42:43], v1 offset0:16 offset1:24
	ds_read2st64_b32 v[44:45], v1 offset0:32 offset1:40
	ds_read2st64_b32 v[46:47], v1 offset0:48 offset1:56
	ds_read2st64_b32 v[48:49], v1 offset0:64 offset1:72
	ds_read2st64_b32 v[50:51], v1 offset0:80 offset1:88
	ds_read2st64_b32 v[52:53], v1 offset0:96 offset1:104
	ds_read2st64_b32 v[54:55], v1 offset0:112 offset1:120
	ds_read2st64_b32 v[56:57], v1 offset0:128 offset1:136
	v_add_u32_e32 v1, 4, v1
	s_waitcnt vmcnt(7)
	v_mov_b32_e32 v38, v58
	global_load_dword v58, v[66:67], off
	v_lshl_add_u64 v[66:67], v[66:67], 0, s[8:9]
	s_waitcnt lgkmcnt(8)
	v_pk_fma_f32 v[10:11], v[38:39], v[40:41], v[10:11] op_sel_hi:[0,1,1]
	s_waitcnt lgkmcnt(7)
	v_pk_fma_f32 v[12:13], v[38:39], v[42:43], v[12:13] op_sel_hi:[0,1,1]
	s_waitcnt lgkmcnt(6)
	v_pk_fma_f32 v[14:15], v[38:39], v[44:45], v[14:15] op_sel_hi:[0,1,1]
	s_waitcnt lgkmcnt(5)
	v_pk_fma_f32 v[16:17], v[38:39], v[46:47], v[16:17] op_sel_hi:[0,1,1]
	s_waitcnt lgkmcnt(4)
	v_pk_fma_f32 v[18:19], v[38:39], v[48:49], v[18:19] op_sel_hi:[0,1,1]
	s_waitcnt lgkmcnt(3)
	v_pk_fma_f32 v[20:21], v[38:39], v[50:51], v[20:21] op_sel_hi:[0,1,1]
	s_waitcnt lgkmcnt(2)
	v_pk_fma_f32 v[22:23], v[38:39], v[52:53], v[22:23] op_sel_hi:[0,1,1]
	s_waitcnt lgkmcnt(1)
	v_pk_fma_f32 v[24:25], v[38:39], v[54:55], v[24:25] op_sel_hi:[0,1,1]
	s_waitcnt lgkmcnt(0)
	v_pk_fma_f32 v[8:9], v[38:39], v[56:57], v[8:9] op_sel_hi:[0,1,1]
	ds_read2st64_b32 v[40:41], v1 offset1:8
	ds_read2st64_b32 v[42:43], v1 offset0:16 offset1:24
	ds_read2st64_b32 v[44:45], v1 offset0:32 offset1:40
	ds_read2st64_b32 v[46:47], v1 offset0:48 offset1:56
	ds_read2st64_b32 v[48:49], v1 offset0:64 offset1:72
	ds_read2st64_b32 v[50:51], v1 offset0:80 offset1:88
	ds_read2st64_b32 v[52:53], v1 offset0:96 offset1:104
	ds_read2st64_b32 v[54:55], v1 offset0:112 offset1:120
	ds_read2st64_b32 v[56:57], v1 offset0:128 offset1:136
	v_add_u32_e32 v1, 4, v1
	s_waitcnt vmcnt(7)
	v_mov_b32_e32 v38, v59
	global_load_dword v59, v[66:67], off
	v_lshl_add_u64 v[66:67], v[66:67], 0, s[8:9]
	s_waitcnt lgkmcnt(8)
	v_pk_fma_f32 v[10:11], v[38:39], v[40:41], v[10:11] op_sel_hi:[0,1,1]
	s_waitcnt lgkmcnt(7)
	v_pk_fma_f32 v[12:13], v[38:39], v[42:43], v[12:13] op_sel_hi:[0,1,1]
	s_waitcnt lgkmcnt(6)
	v_pk_fma_f32 v[14:15], v[38:39], v[44:45], v[14:15] op_sel_hi:[0,1,1]
	s_waitcnt lgkmcnt(5)
	v_pk_fma_f32 v[16:17], v[38:39], v[46:47], v[16:17] op_sel_hi:[0,1,1]
	s_waitcnt lgkmcnt(4)
	v_pk_fma_f32 v[18:19], v[38:39], v[48:49], v[18:19] op_sel_hi:[0,1,1]
	s_waitcnt lgkmcnt(3)
	v_pk_fma_f32 v[20:21], v[38:39], v[50:51], v[20:21] op_sel_hi:[0,1,1]
	s_waitcnt lgkmcnt(2)
	v_pk_fma_f32 v[22:23], v[38:39], v[52:53], v[22:23] op_sel_hi:[0,1,1]
	s_waitcnt lgkmcnt(1)
	v_pk_fma_f32 v[24:25], v[38:39], v[54:55], v[24:25] op_sel_hi:[0,1,1]
	s_waitcnt lgkmcnt(0)
	v_pk_fma_f32 v[8:9], v[38:39], v[56:57], v[8:9] op_sel_hi:[0,1,1]
	ds_read2st64_b32 v[40:41], v1 offset1:8
	ds_read2st64_b32 v[42:43], v1 offset0:16 offset1:24
	ds_read2st64_b32 v[44:45], v1 offset0:32 offset1:40
	ds_read2st64_b32 v[46:47], v1 offset0:48 offset1:56
	ds_read2st64_b32 v[48:49], v1 offset0:64 offset1:72
	ds_read2st64_b32 v[50:51], v1 offset0:80 offset1:88
	ds_read2st64_b32 v[52:53], v1 offset0:96 offset1:104
	ds_read2st64_b32 v[54:55], v1 offset0:112 offset1:120
	ds_read2st64_b32 v[56:57], v1 offset0:128 offset1:136
	v_add_u32_e32 v1, 4, v1
	s_waitcnt vmcnt(7)
	v_mov_b32_e32 v38, v60
	global_load_dword v60, v[66:67], off
	v_lshl_add_u64 v[66:67], v[66:67], 0, s[8:9]
	s_waitcnt lgkmcnt(8)
	v_pk_fma_f32 v[10:11], v[38:39], v[40:41], v[10:11] op_sel_hi:[0,1,1]
	s_waitcnt lgkmcnt(7)
	v_pk_fma_f32 v[12:13], v[38:39], v[42:43], v[12:13] op_sel_hi:[0,1,1]
	s_waitcnt lgkmcnt(6)
	v_pk_fma_f32 v[14:15], v[38:39], v[44:45], v[14:15] op_sel_hi:[0,1,1]
	s_waitcnt lgkmcnt(5)
	v_pk_fma_f32 v[16:17], v[38:39], v[46:47], v[16:17] op_sel_hi:[0,1,1]
	s_waitcnt lgkmcnt(4)
	v_pk_fma_f32 v[18:19], v[38:39], v[48:49], v[18:19] op_sel_hi:[0,1,1]
	s_waitcnt lgkmcnt(3)
	v_pk_fma_f32 v[20:21], v[38:39], v[50:51], v[20:21] op_sel_hi:[0,1,1]
	s_waitcnt lgkmcnt(2)
	v_pk_fma_f32 v[22:23], v[38:39], v[52:53], v[22:23] op_sel_hi:[0,1,1]
	s_waitcnt lgkmcnt(1)
	v_pk_fma_f32 v[24:25], v[38:39], v[54:55], v[24:25] op_sel_hi:[0,1,1]
	s_waitcnt lgkmcnt(0)
	v_pk_fma_f32 v[8:9], v[38:39], v[56:57], v[8:9] op_sel_hi:[0,1,1]
	ds_read2st64_b32 v[40:41], v1 offset1:8
	ds_read2st64_b32 v[42:43], v1 offset0:16 offset1:24
	ds_read2st64_b32 v[44:45], v1 offset0:32 offset1:40
	ds_read2st64_b32 v[46:47], v1 offset0:48 offset1:56
	ds_read2st64_b32 v[48:49], v1 offset0:64 offset1:72
	ds_read2st64_b32 v[50:51], v1 offset0:80 offset1:88
	ds_read2st64_b32 v[52:53], v1 offset0:96 offset1:104
	ds_read2st64_b32 v[54:55], v1 offset0:112 offset1:120
	ds_read2st64_b32 v[56:57], v1 offset0:128 offset1:136
	v_add_u32_e32 v1, 4, v1
	s_waitcnt vmcnt(7)
; __device__ __forceinline__ void prep_phase(const Ctx& C, const PV& P, unsigned char* smem) {
;     ...
;                 for (int kk = ks * 64; kk < ks * 64 + 64; ++kk) {
;                     const float w = aw[(size_t)(half * 512 + kk) * 9216 + n0 + nl];
; #pragma unroll
;                     for (int b = 0; b < 18; ++b) acc[b] += sc[b * 512 + kk] * w;
;                 }
	v_mov_b32_e32 v38, v61
	global_load_dword v61, v[66:67], off
	v_lshl_add_u64 v[66:67], v[66:67], 0, s[8:9]
	s_waitcnt lgkmcnt(8)
	v_pk_fma_f32 v[10:11], v[38:39], v[40:41], v[10:11] op_sel_hi:[0,1,1]
	s_waitcnt lgkmcnt(7)
	v_pk_fma_f32 v[12:13], v[38:39], v[42:43], v[12:13] op_sel_hi:[0,1,1]
	s_waitcnt lgkmcnt(6)
	v_pk_fma_f32 v[14:15], v[38:39], v[44:45], v[14:15] op_sel_hi:[0,1,1]
	s_waitcnt lgkmcnt(5)
	v_pk_fma_f32 v[16:17], v[38:39], v[46:47], v[16:17] op_sel_hi:[0,1,1]
	s_waitcnt lgkmcnt(4)
	v_pk_fma_f32 v[18:19], v[38:39], v[48:49], v[18:19] op_sel_hi:[0,1,1]
	s_waitcnt lgkmcnt(3)
	v_pk_fma_f32 v[20:21], v[38:39], v[50:51], v[20:21] op_sel_hi:[0,1,1]
	s_waitcnt lgkmcnt(2)
	v_pk_fma_f32 v[22:23], v[38:39], v[52:53], v[22:23] op_sel_hi:[0,1,1]
	s_waitcnt lgkmcnt(1)
	v_pk_fma_f32 v[24:25], v[38:39], v[54:55], v[24:25] op_sel_hi:[0,1,1]
	s_waitcnt lgkmcnt(0)
	v_pk_fma_f32 v[8:9], v[38:39], v[56:57], v[8:9] op_sel_hi:[0,1,1]
	ds_read2st64_b32 v[40:41], v1 offset1:8
	ds_read2st64_b32 v[42:43], v1 offset0:16 offset1:24
	ds_read2st64_b32 v[44:45], v1 offset0:32 offset1:40
	ds_read2st64_b32 v[46:47], v1 offset0:48 offset1:56
	ds_read2st64_b32 v[48:49], v1 offset0:64 offset1:72
	ds_read2st64_b32 v[50:51], v1 offset0:80 offset1:88
	ds_read2st64_b32 v[52:53], v1 offset0:96 offset1:104
	ds_read2st64_b32 v[54:55], v1 offset0:112 offset1:120
	ds_read2st64_b32 v[56:57], v1 offset0:128 offset1:136
	v_add_u32_e32 v1, 4, v1
	s_waitcnt vmcnt(7)
	v_mov_b32_e32 v38, v62
	global_load_dword v62, v[66:67], off
	v_lshl_add_u64 v[66:67], v[66:67], 0, s[8:9]
	s_waitcnt lgkmcnt(8)
	v_pk_fma_f32 v[10:11], v[38:39], v[40:41], v[10:11] op_sel_hi:[0,1,1]
	s_waitcnt lgkmcnt(7)
	v_pk_fma_f32 v[12:13], v[38:39], v[42:43], v[12:13] op_sel_hi:[0,1,1]
	s_waitcnt lgkmcnt(6)
	v_pk_fma_f32 v[14:15], v[38:39], v[44:45], v[14:15] op_sel_hi:[0,1,1]
	s_waitcnt lgkmcnt(5)
	v_pk_fma_f32 v[16:17], v[38:39], v[46:47], v[16:17] op_sel_hi:[0,1,1]
	s_waitcnt lgkmcnt(4)
	v_pk_fma_f32 v[18:19], v[38:39], v[48:49], v[18:19] op_sel_hi:[0,1,1]
	s_waitcnt lgkmcnt(3)
	v_pk_fma_f32 v[20:21], v[38:39], v[50:51], v[20:21] op_sel_hi:[0,1,1]
	s_waitcnt lgkmcnt(2)
	v_pk_fma_f32 v[22:23], v[38:39], v[52:53], v[22:23] op_sel_hi:[0,1,1]
	s_waitcnt lgkmcnt(1)
	v_pk_fma_f32 v[24:25], v[38:39], v[54:55], v[24:25] op_sel_hi:[0,1,1]
	s_waitcnt lgkmcnt(0)
	v_pk_fma_f32 v[8:9], v[38:39], v[56:57], v[8:9] op_sel_hi:[0,1,1]
	ds_read2st64_b32 v[40:41], v1 offset1:8
	ds_read2st64_b32 v[42:43], v1 offset0:16 offset1:24
	ds_read2st64_b32 v[44:45], v1 offset0:32 offset1:40
	ds_read2st64_b32 v[46:47], v1 offset0:48 offset1:56
	ds_read2st64_b32 v[48:49], v1 offset0:64 offset1:72
	ds_read2st64_b32 v[50:51], v1 offset0:80 offset1:88
	ds_read2st64_b32 v[52:53], v1 offset0:96 offset1:104
	ds_read2st64_b32 v[54:55], v1 offset0:112 offset1:120
	ds_read2st64_b32 v[56:57], v1 offset0:128 offset1:136
	v_add_u32_e32 v1, 4, v1
	s_waitcnt vmcnt(7)
	v_mov_b32_e32 v38, v63
	global_load_dword v63, v[66:67], off
	v_lshl_add_u64 v[66:67], v[66:67], 0, s[8:9]
	s_waitcnt lgkmcnt(8)
	v_pk_fma_f32 v[10:11], v[38:39], v[40:41], v[10:11] op_sel_hi:[0,1,1]
	s_waitcnt lgkmcnt(7)
	v_pk_fma_f32 v[12:13], v[38:39], v[42:43], v[12:13] op_sel_hi:[0,1,1]
	s_waitcnt lgkmcnt(6)
	v_pk_fma_f32 v[14:15], v[38:39], v[44:45], v[14:15] op_sel_hi:[0,1,1]
	s_waitcnt lgkmcnt(5)
	v_pk_fma_f32 v[16:17], v[38:39], v[46:47], v[16:17] op_sel_hi:[0,1,1]
	s_waitcnt lgkmcnt(4)
	v_pk_fma_f32 v[18:19], v[38:39], v[48:49], v[18:19] op_sel_hi:[0,1,1]
	s_waitcnt lgkmcnt(3)
	v_pk_fma_f32 v[20:21], v[38:39], v[50:51], v[20:21] op_sel_hi:[0,1,1]
	s_waitcnt lgkmcnt(2)
	v_pk_fma_f32 v[22:23], v[38:39], v[52:53], v[22:23] op_sel_hi:[0,1,1]
	s_waitcnt lgkmcnt(1)
	v_pk_fma_f32 v[24:25], v[38:39], v[54:55], v[24:25] op_sel_hi:[0,1,1]
	s_waitcnt lgkmcnt(0)
	v_pk_fma_f32 v[8:9], v[38:39], v[56:57], v[8:9] op_sel_hi:[0,1,1]
	ds_read2st64_b32 v[40:41], v1 offset1:8
	ds_read2st64_b32 v[42:43], v1 offset0:16 offset1:24
	ds_read2st64_b32 v[44:45], v1 offset0:32 offset1:40
	ds_read2st64_b32 v[46:47], v1 offset0:48 offset1:56
	ds_read2st64_b32 v[48:49], v1 offset0:64 offset1:72
	ds_read2st64_b32 v[50:51], v1 offset0:80 offset1:88
	ds_read2st64_b32 v[52:53], v1 offset0:96 offset1:104
	ds_read2st64_b32 v[54:55], v1 offset0:112 offset1:120
	ds_read2st64_b32 v[56:57], v1 offset0:128 offset1:136
	v_add_u32_e32 v1, 4, v1
	s_waitcnt vmcnt(7)
	v_mov_b32_e32 v38, v64
	global_load_dword v64, v[66:67], off
	v_lshl_add_u64 v[66:67], v[66:67], 0, s[8:9]
	s_waitcnt lgkmcnt(8)
	v_pk_fma_f32 v[10:11], v[38:39], v[40:41], v[10:11] op_sel_hi:[0,1,1]
	s_waitcnt lgkmcnt(7)
	v_pk_fma_f32 v[12:13], v[38:39], v[42:43], v[12:13] op_sel_hi:[0,1,1]
	s_waitcnt lgkmcnt(6)
	v_pk_fma_f32 v[14:15], v[38:39], v[44:45], v[14:15] op_sel_hi:[0,1,1]
	s_waitcnt lgkmcnt(5)
	v_pk_fma_f32 v[16:17], v[38:39], v[46:47], v[16:17] op_sel_hi:[0,1,1]
	s_waitcnt lgkmcnt(4)
	v_pk_fma_f32 v[18:19], v[38:39], v[48:49], v[18:19] op_sel_hi:[0,1,1]
	s_waitcnt lgkmcnt(3)
	v_pk_fma_f32 v[20:21], v[38:39], v[50:51], v[20:21] op_sel_hi:[0,1,1]
	s_waitcnt lgkmcnt(2)
	v_pk_fma_f32 v[22:23], v[38:39], v[52:53], v[22:23] op_sel_hi:[0,1,1]
	s_waitcnt lgkmcnt(1)
	v_pk_fma_f32 v[24:25], v[38:39], v[54:55], v[24:25] op_sel_hi:[0,1,1]
	s_waitcnt lgkmcnt(0)
	v_pk_fma_f32 v[8:9], v[38:39], v[56:57], v[8:9] op_sel_hi:[0,1,1]
	ds_read2st64_b32 v[40:41], v1 offset1:8
	ds_read2st64_b32 v[42:43], v1 offset0:16 offset1:24
	ds_read2st64_b32 v[44:45], v1 offset0:32 offset1:40
	ds_read2st64_b32 v[46:47], v1 offset0:48 offset1:56
	ds_read2st64_b32 v[48:49], v1 offset0:64 offset1:72
	ds_read2st64_b32 v[50:51], v1 offset0:80 offset1:88
	ds_read2st64_b32 v[52:53], v1 offset0:96 offset1:104
	ds_read2st64_b32 v[54:55], v1 offset0:112 offset1:120
	ds_read2st64_b32 v[56:57], v1 offset0:128 offset1:136
	v_add_u32_e32 v1, 4, v1
	s_waitcnt vmcnt(7)
	v_mov_b32_e32 v38, v65
	global_load_dword v65, v[66:67], off
	v_lshl_add_u64 v[66:67], v[66:67], 0, s[8:9]
	s_waitcnt lgkmcnt(8)
	v_pk_fma_f32 v[10:11], v[38:39], v[40:41], v[10:11] op_sel_hi:[0,1,1]
	s_waitcnt lgkmcnt(7)
	v_pk_fma_f32 v[12:13], v[38:39], v[42:43], v[12:13] op_sel_hi:[0,1,1]
	s_waitcnt lgkmcnt(6)
	v_pk_fma_f32 v[14:15], v[38:39], v[44:45], v[14:15] op_sel_hi:[0,1,1]
	s_waitcnt lgkmcnt(5)
	v_pk_fma_f32 v[16:17], v[38:39], v[46:47], v[16:17] op_sel_hi:[0,1,1]
	s_waitcnt lgkmcnt(4)
	v_pk_fma_f32 v[18:19], v[38:39], v[48:49], v[18:19] op_sel_hi:[0,1,1]
	s_waitcnt lgkmcnt(3)
	v_pk_fma_f32 v[20:21], v[38:39], v[50:51], v[20:21] op_sel_hi:[0,1,1]
	s_waitcnt lgkmcnt(2)
	v_pk_fma_f32 v[22:23], v[38:39], v[52:53], v[22:23] op_sel_hi:[0,1,1]
	s_waitcnt lgkmcnt(1)
	v_pk_fma_f32 v[24:25], v[38:39], v[54:55], v[24:25] op_sel_hi:[0,1,1]
	s_waitcnt lgkmcnt(0)
	v_pk_fma_f32 v[8:9], v[38:39], v[56:57], v[8:9] op_sel_hi:[0,1,1]
	s_sub_i32 s14, s14, 1
	s_cmp_lg_u32 s14, 0
	s_cbranch_scc1 .Lprep_b_loop
; __device__ __forceinline__ void prep_phase(const Ctx& C, const PV& P, unsigned char* smem) {
;     ...
;                 for (int kk = ks * 64; kk < ks * 64 + 64; ++kk) {
;                     const float w = aw[(size_t)(half * 512 + kk) * 9216 + n0 + nl];
; #pragma unroll
;                     for (int b = 0; b < 18; ++b) acc[b] += sc[b * 512 + kk] * w;
;                 }
	ds_read2st64_b32 v[40:41], v1 offset1:8
	ds_read2st64_b32 v[42:43], v1 offset0:16 offset1:24
	ds_read2st64_b32 v[44:45], v1 offset0:32 offset1:40
	ds_read2st64_b32 v[46:47], v1 offset0:48 offset1:56
	ds_read2st64_b32 v[48:49], v1 offset0:64 offset1:72
	ds_read2st64_b32 v[50:51], v1 offset0:80 offset1:88
	ds_read2st64_b32 v[52:53], v1 offset0:96 offset1:104
	ds_read2st64_b32 v[54:55], v1 offset0:112 offset1:120
	ds_read2st64_b32 v[56:57], v1 offset0:128 offset1:136
	v_add_u32_e32 v1, 4, v1
	s_waitcnt vmcnt(7)
	v_mov_b32_e32 v38, v58
	s_waitcnt lgkmcnt(8)
	v_pk_fma_f32 v[10:11], v[38:39], v[40:41], v[10:11] op_sel_hi:[0,1,1]
	s_waitcnt lgkmcnt(7)
	v_pk_fma_f32 v[12:13], v[38:39], v[42:43], v[12:13] op_sel_hi:[0,1,1]
	s_waitcnt lgkmcnt(6)
	v_pk_fma_f32 v[14:15], v[38:39], v[44:45], v[14:15] op_sel_hi:[0,1,1]
	s_waitcnt lgkmcnt(5)
	v_pk_fma_f32 v[16:17], v[38:39], v[46:47], v[16:17] op_sel_hi:[0,1,1]
	s_waitcnt lgkmcnt(4)
	v_pk_fma_f32 v[18:19], v[38:39], v[48:49], v[18:19] op_sel_hi:[0,1,1]
	s_waitcnt lgkmcnt(3)
	v_pk_fma_f32 v[20:21], v[38:39], v[50:51], v[20:21] op_sel_hi:[0,1,1]
	s_waitcnt lgkmcnt(2)
	v_pk_fma_f32 v[22:23], v[38:39], v[52:53], v[22:23] op_sel_hi:[0,1,1]
	s_waitcnt lgkmcnt(1)
	v_pk_fma_f32 v[24:25], v[38:39], v[54:55], v[24:25] op_sel_hi:[0,1,1]
	s_waitcnt lgkmcnt(0)
	v_pk_fma_f32 v[8:9], v[38:39], v[56:57], v[8:9] op_sel_hi:[0,1,1]
	ds_read2st64_b32 v[40:41], v1 offset1:8
	ds_read2st64_b32 v[42:43], v1 offset0:16 offset1:24
	ds_read2st64_b32 v[44:45], v1 offset0:32 offset1:40
	ds_read2st64_b32 v[46:47], v1 offset0:48 offset1:56
	ds_read2st64_b32 v[48:49], v1 offset0:64 offset1:72
	ds_read2st64_b32 v[50:51], v1 offset0:80 offset1:88
	ds_read2st64_b32 v[52:53], v1 offset0:96 offset1:104
	ds_read2st64_b32 v[54:55], v1 offset0:112 offset1:120
	ds_read2st64_b32 v[56:57], v1 offset0:128 offset1:136
	v_add_u32_e32 v1, 4, v1
	s_waitcnt vmcnt(6)
	v_mov_b32_e32 v38, v59
	s_waitcnt lgkmcnt(8)
	v_pk_fma_f32 v[10:11], v[38:39], v[40:41], v[10:11] op_sel_hi:[0,1,1]
	s_waitcnt lgkmcnt(7)
	v_pk_fma_f32 v[12:13], v[38:39], v[42:43], v[12:13] op_sel_hi:[0,1,1]
	s_waitcnt lgkmcnt(6)
	v_pk_fma_f32 v[14:15], v[38:39], v[44:45], v[14:15] op_sel_hi:[0,1,1]
	s_waitcnt lgkmcnt(5)
	v_pk_fma_f32 v[16:17], v[38:39], v[46:47], v[16:17] op_sel_hi:[0,1,1]
	s_waitcnt lgkmcnt(4)
	v_pk_fma_f32 v[18:19], v[38:39], v[48:49], v[18:19] op_sel_hi:[0,1,1]
	s_waitcnt lgkmcnt(3)
	v_pk_fma_f32 v[20:21], v[38:39], v[50:51], v[20:21] op_sel_hi:[0,1,1]
	s_waitcnt lgkmcnt(2)
	v_pk_fma_f32 v[22:23], v[38:39], v[52:53], v[22:23] op_sel_hi:[0,1,1]
	s_waitcnt lgkmcnt(1)
	v_pk_fma_f32 v[24:25], v[38:39], v[54:55], v[24:25] op_sel_hi:[0,1,1]
	s_waitcnt lgkmcnt(0)
	v_pk_fma_f32 v[8:9], v[38:39], v[56:57], v[8:9] op_sel_hi:[0,1,1]
	ds_read2st64_b32 v[40:41], v1 offset1:8
	ds_read2st64_b32 v[42:43], v1 offset0:16 offset1:24
	ds_read2st64_b32 v[44:45], v1 offset0:32 offset1:40
	ds_read2st64_b32 v[46:47], v1 offset0:48 offset1:56
	ds_read2st64_b32 v[48:49], v1 offset0:64 offset1:72
	ds_read2st64_b32 v[50:51], v1 offset0:80 offset1:88
	ds_read2st64_b32 v[52:53], v1 offset0:96 offset1:104
	ds_read2st64_b32 v[54:55], v1 offset0:112 offset1:120
	ds_read2st64_b32 v[56:57], v1 offset0:128 offset1:136
	v_add_u32_e32 v1, 4, v1
	s_waitcnt vmcnt(5)
	v_mov_b32_e32 v38, v60
	s_waitcnt lgkmcnt(8)
	v_pk_fma_f32 v[10:11], v[38:39], v[40:41], v[10:11] op_sel_hi:[0,1,1]
	s_waitcnt lgkmcnt(7)
	v_pk_fma_f32 v[12:13], v[38:39], v[42:43], v[12:13] op_sel_hi:[0,1,1]
	s_waitcnt lgkmcnt(6)
	v_pk_fma_f32 v[14:15], v[38:39], v[44:45], v[14:15] op_sel_hi:[0,1,1]
	s_waitcnt lgkmcnt(5)
	v_pk_fma_f32 v[16:17], v[38:39], v[46:47], v[16:17] op_sel_hi:[0,1,1]
	s_waitcnt lgkmcnt(4)
	v_pk_fma_f32 v[18:19], v[38:39], v[48:49], v[18:19] op_sel_hi:[0,1,1]
	s_waitcnt lgkmcnt(3)
	v_pk_fma_f32 v[20:21], v[38:39], v[50:51], v[20:21] op_sel_hi:[0,1,1]
	s_waitcnt lgkmcnt(2)
	v_pk_fma_f32 v[22:23], v[38:39], v[52:53], v[22:23] op_sel_hi:[0,1,1]
	s_waitcnt lgkmcnt(1)
	v_pk_fma_f32 v[24:25], v[38:39], v[54:55], v[24:25] op_sel_hi:[0,1,1]
	s_waitcnt lgkmcnt(0)
	v_pk_fma_f32 v[8:9], v[38:39], v[56:57], v[8:9] op_sel_hi:[0,1,1]
	ds_read2st64_b32 v[40:41], v1 offset1:8
	ds_read2st64_b32 v[42:43], v1 offset0:16 offset1:24
	ds_read2st64_b32 v[44:45], v1 offset0:32 offset1:40
	ds_read2st64_b32 v[46:47], v1 offset0:48 offset1:56
	ds_read2st64_b32 v[48:49], v1 offset0:64 offset1:72
	ds_read2st64_b32 v[50:51], v1 offset0:80 offset1:88
	ds_read2st64_b32 v[52:53], v1 offset0:96 offset1:104
	ds_read2st64_b32 v[54:55], v1 offset0:112 offset1:120
	ds_read2st64_b32 v[56:57], v1 offset0:128 offset1:136
	v_add_u32_e32 v1, 4, v1
	s_waitcnt vmcnt(4)
	v_mov_b32_e32 v38, v61
	s_waitcnt lgkmcnt(8)
	v_pk_fma_f32 v[10:11], v[38:39], v[40:41], v[10:11] op_sel_hi:[0,1,1]
	s_waitcnt lgkmcnt(7)
	v_pk_fma_f32 v[12:13], v[38:39], v[42:43], v[12:13] op_sel_hi:[0,1,1]
	s_waitcnt lgkmcnt(6)
	v_pk_fma_f32 v[14:15], v[38:39], v[44:45], v[14:15] op_sel_hi:[0,1,1]
	s_waitcnt lgkmcnt(5)
	v_pk_fma_f32 v[16:17], v[38:39], v[46:47], v[16:17] op_sel_hi:[0,1,1]
	s_waitcnt lgkmcnt(4)
	v_pk_fma_f32 v[18:19], v[38:39], v[48:49], v[18:19] op_sel_hi:[0,1,1]
	s_waitcnt lgkmcnt(3)
	v_pk_fma_f32 v[20:21], v[38:39], v[50:51], v[20:21] op_sel_hi:[0,1,1]
	s_waitcnt lgkmcnt(2)
	v_pk_fma_f32 v[22:23], v[38:39], v[52:53], v[22:23] op_sel_hi:[0,1,1]
	s_waitcnt lgkmcnt(1)
	v_pk_fma_f32 v[24:25], v[38:39], v[54:55], v[24:25] op_sel_hi:[0,1,1]
	s_waitcnt lgkmcnt(0)
; __device__ __forceinline__ void prep_phase(const Ctx& C, const PV& P, unsigned char* smem) {
;     ...
;                 for (int kk = ks * 64; kk < ks * 64 + 64; ++kk) {
;                     const float w = aw[(size_t)(half * 512 + kk) * 9216 + n0 + nl];
; #pragma unroll
;                     for (int b = 0; b < 18; ++b) acc[b] += sc[b * 512 + kk] * w;
;                 }
;             }
;             __syncthreads();
; #pragma unroll
;             for (int b = 0; b < 18; ++b) red[(ks * 18 + b) * 64 + nl] = acc[b];
;             __syncthreads();
;             for (int e = tid; e < 18 * 64; e += NT) {
;                 const int b = e >> 6, n = e & 63;
;                 float s = 0.f;
; #pragma unroll
;                 for (int k8 = 0; k8 < 8; ++k8) s += red[(k8 * 18 + b) * 64 + n];
;                 mod[((size_t)l * 18 + b) * 9216 + n0 + n] = s + P.inp(5)[(size_t)l * 9216 + n0 + n];
	v_pk_fma_f32 v[8:9], v[38:39], v[56:57], v[8:9] op_sel_hi:[0,1,1]
	ds_read2st64_b32 v[40:41], v1 offset1:8
	ds_read2st64_b32 v[42:43], v1 offset0:16 offset1:24
	ds_read2st64_b32 v[44:45], v1 offset0:32 offset1:40
	ds_read2st64_b32 v[46:47], v1 offset0:48 offset1:56
	ds_read2st64_b32 v[48:49], v1 offset0:64 offset1:72
	ds_read2st64_b32 v[50:51], v1 offset0:80 offset1:88
	ds_read2st64_b32 v[52:53], v1 offset0:96 offset1:104
	ds_read2st64_b32 v[54:55], v1 offset0:112 offset1:120
	ds_read2st64_b32 v[56:57], v1 offset0:128 offset1:136
	v_add_u32_e32 v1, 4, v1
	s_waitcnt vmcnt(3)
	v_mov_b32_e32 v38, v62
	s_waitcnt lgkmcnt(8)
	v_pk_fma_f32 v[10:11], v[38:39], v[40:41], v[10:11] op_sel_hi:[0,1,1]
	s_waitcnt lgkmcnt(7)
	v_pk_fma_f32 v[12:13], v[38:39], v[42:43], v[12:13] op_sel_hi:[0,1,1]
	s_waitcnt lgkmcnt(6)
	v_pk_fma_f32 v[14:15], v[38:39], v[44:45], v[14:15] op_sel_hi:[0,1,1]
	s_waitcnt lgkmcnt(5)
	v_pk_fma_f32 v[16:17], v[38:39], v[46:47], v[16:17] op_sel_hi:[0,1,1]
	s_waitcnt lgkmcnt(4)
	v_pk_fma_f32 v[18:19], v[38:39], v[48:49], v[18:19] op_sel_hi:[0,1,1]
	s_waitcnt lgkmcnt(3)
	v_pk_fma_f32 v[20:21], v[38:39], v[50:51], v[20:21] op_sel_hi:[0,1,1]
	s_waitcnt lgkmcnt(2)
	v_pk_fma_f32 v[22:23], v[38:39], v[52:53], v[22:23] op_sel_hi:[0,1,1]
	s_waitcnt lgkmcnt(1)
	v_pk_fma_f32 v[24:25], v[38:39], v[54:55], v[24:25] op_sel_hi:[0,1,1]
	s_waitcnt lgkmcnt(0)
	v_pk_fma_f32 v[8:9], v[38:39], v[56:57], v[8:9] op_sel_hi:[0,1,1]
	ds_read2st64_b32 v[40:41], v1 offset1:8
	ds_read2st64_b32 v[42:43], v1 offset0:16 offset1:24
	ds_read2st64_b32 v[44:45], v1 offset0:32 offset1:40
	ds_read2st64_b32 v[46:47], v1 offset0:48 offset1:56
	ds_read2st64_b32 v[48:49], v1 offset0:64 offset1:72
	ds_read2st64_b32 v[50:51], v1 offset0:80 offset1:88
	ds_read2st64_b32 v[52:53], v1 offset0:96 offset1:104
	ds_read2st64_b32 v[54:55], v1 offset0:112 offset1:120
	ds_read2st64_b32 v[56:57], v1 offset0:128 offset1:136
	v_add_u32_e32 v1, 4, v1
	s_waitcnt vmcnt(2)
	v_mov_b32_e32 v38, v63
	s_waitcnt lgkmcnt(8)
	v_pk_fma_f32 v[10:11], v[38:39], v[40:41], v[10:11] op_sel_hi:[0,1,1]
	s_waitcnt lgkmcnt(7)
	v_pk_fma_f32 v[12:13], v[38:39], v[42:43], v[12:13] op_sel_hi:[0,1,1]
	s_waitcnt lgkmcnt(6)
	v_pk_fma_f32 v[14:15], v[38:39], v[44:45], v[14:15] op_sel_hi:[0,1,1]
	s_waitcnt lgkmcnt(5)
	v_pk_fma_f32 v[16:17], v[38:39], v[46:47], v[16:17] op_sel_hi:[0,1,1]
	s_waitcnt lgkmcnt(4)
	v_pk_fma_f32 v[18:19], v[38:39], v[48:49], v[18:19] op_sel_hi:[0,1,1]
	s_waitcnt lgkmcnt(3)
	v_pk_fma_f32 v[20:21], v[38:39], v[50:51], v[20:21] op_sel_hi:[0,1,1]
	s_waitcnt lgkmcnt(2)
	v_pk_fma_f32 v[22:23], v[38:39], v[52:53], v[22:23] op_sel_hi:[0,1,1]
	s_waitcnt lgkmcnt(1)
	v_pk_fma_f32 v[24:25], v[38:39], v[54:55], v[24:25] op_sel_hi:[0,1,1]
	s_waitcnt lgkmcnt(0)
	v_pk_fma_f32 v[8:9], v[38:39], v[56:57], v[8:9] op_sel_hi:[0,1,1]
	ds_read2st64_b32 v[40:41], v1 offset1:8
	ds_read2st64_b32 v[42:43], v1 offset0:16 offset1:24
	ds_read2st64_b32 v[44:45], v1 offset0:32 offset1:40
	ds_read2st64_b32 v[46:47], v1 offset0:48 offset1:56
	ds_read2st64_b32 v[48:49], v1 offset0:64 offset1:72
	ds_read2st64_b32 v[50:51], v1 offset0:80 offset1:88
	ds_read2st64_b32 v[52:53], v1 offset0:96 offset1:104
	ds_read2st64_b32 v[54:55], v1 offset0:112 offset1:120
	ds_read2st64_b32 v[56:57], v1 offset0:128 offset1:136
	v_add_u32_e32 v1, 4, v1
	s_waitcnt vmcnt(1)
	v_mov_b32_e32 v38, v64
	s_waitcnt lgkmcnt(8)
	v_pk_fma_f32 v[10:11], v[38:39], v[40:41], v[10:11] op_sel_hi:[0,1,1]
	s_waitcnt lgkmcnt(7)
	v_pk_fma_f32 v[12:13], v[38:39], v[42:43], v[12:13] op_sel_hi:[0,1,1]
	s_waitcnt lgkmcnt(6)
	v_pk_fma_f32 v[14:15], v[38:39], v[44:45], v[14:15] op_sel_hi:[0,1,1]
	s_waitcnt lgkmcnt(5)
	v_pk_fma_f32 v[16:17], v[38:39], v[46:47], v[16:17] op_sel_hi:[0,1,1]
	s_waitcnt lgkmcnt(4)
	v_pk_fma_f32 v[18:19], v[38:39], v[48:49], v[18:19] op_sel_hi:[0,1,1]
	s_waitcnt lgkmcnt(3)
	v_pk_fma_f32 v[20:21], v[38:39], v[50:51], v[20:21] op_sel_hi:[0,1,1]
	s_waitcnt lgkmcnt(2)
	v_pk_fma_f32 v[22:23], v[38:39], v[52:53], v[22:23] op_sel_hi:[0,1,1]
	s_waitcnt lgkmcnt(1)
	v_pk_fma_f32 v[24:25], v[38:39], v[54:55], v[24:25] op_sel_hi:[0,1,1]
	s_waitcnt lgkmcnt(0)
	v_pk_fma_f32 v[8:9], v[38:39], v[56:57], v[8:9] op_sel_hi:[0,1,1]
	ds_read2st64_b32 v[40:41], v1 offset1:8
	ds_read2st64_b32 v[42:43], v1 offset0:16 offset1:24
	ds_read2st64_b32 v[44:45], v1 offset0:32 offset1:40
	ds_read2st64_b32 v[46:47], v1 offset0:48 offset1:56
	ds_read2st64_b32 v[48:49], v1 offset0:64 offset1:72
	ds_read2st64_b32 v[50:51], v1 offset0:80 offset1:88
	ds_read2st64_b32 v[52:53], v1 offset0:96 offset1:104
	ds_read2st64_b32 v[54:55], v1 offset0:112 offset1:120
	ds_read2st64_b32 v[56:57], v1 offset0:128 offset1:136
	v_add_u32_e32 v1, 4, v1
	s_waitcnt vmcnt(0)
	v_mov_b32_e32 v38, v65
	s_waitcnt lgkmcnt(8)
	v_pk_fma_f32 v[10:11], v[38:39], v[40:41], v[10:11] op_sel_hi:[0,1,1]
	s_waitcnt lgkmcnt(7)
	v_pk_fma_f32 v[12:13], v[38:39], v[42:43], v[12:13] op_sel_hi:[0,1,1]
	s_waitcnt lgkmcnt(6)
	v_pk_fma_f32 v[14:15], v[38:39], v[44:45], v[14:15] op_sel_hi:[0,1,1]
	s_waitcnt lgkmcnt(5)
	v_pk_fma_f32 v[16:17], v[38:39], v[46:47], v[16:17] op_sel_hi:[0,1,1]
	s_waitcnt lgkmcnt(4)
	v_pk_fma_f32 v[18:19], v[38:39], v[48:49], v[18:19] op_sel_hi:[0,1,1]
	s_waitcnt lgkmcnt(3)
	v_pk_fma_f32 v[20:21], v[38:39], v[50:51], v[20:21] op_sel_hi:[0,1,1]
	s_waitcnt lgkmcnt(2)
	v_pk_fma_f32 v[22:23], v[38:39], v[52:53], v[22:23] op_sel_hi:[0,1,1]
	s_waitcnt lgkmcnt(1)
	v_pk_fma_f32 v[24:25], v[38:39], v[54:55], v[24:25] op_sel_hi:[0,1,1]
	s_waitcnt lgkmcnt(0)
	v_pk_fma_f32 v[8:9], v[38:39], v[56:57], v[8:9] op_sel_hi:[0,1,1]
	s_or_b64 exec, exec, s[12:13]
	s_barrier
	ds_write2st64_b32 v37, v10, v11 offset0:144 offset1:145
	ds_write2st64_b32 v37, v12, v13 offset0:146 offset1:147
	ds_write2st64_b32 v37, v14, v15 offset0:148 offset1:149
	ds_write2st64_b32 v37, v16, v17 offset0:150 offset1:151
	ds_write2st64_b32 v37, v18, v19 offset0:152 offset1:153
	ds_write2st64_b32 v37, v20, v21 offset0:154 offset1:155
	ds_write2st64_b32 v37, v22, v23 offset0:156 offset1:157
	ds_write2st64_b32 v37, v24, v25 offset0:158 offset1:159
	ds_write2st64_b32 v37, v8, v9 offset0:160 offset1:161
	s_waitcnt lgkmcnt(0)
	s_barrier
	s_and_saveexec_b64 s[12:13], s[42:43]
	s_cbranch_execz .LBB0_2105
	s_load_dwordx2 s[6:7], s[24:25], 0x28
	s_mul_i32 s8, s4, 0x9000
	s_mul_hi_i32 s5, s4, 0x9000
	s_mul_hi_i32 s15, s4, 18
	s_mul_i32 s14, s4, 18
	s_waitcnt lgkmcnt(0)
	s_add_u32 s4, s6, s8
	s_addc_u32 s5, s7, s5
	s_add_u32 s4, s4, s10
	s_addc_u32 s5, s5, s11
	v_mov_b32_e32 v1, v133
	v_lshl_add_u64 v[8:9], s[4:5], 0, v[0:1]
	v_lshl_add_u64 v[10:11], v[2:3], 0, s[10:11]
	s_mov_b64 s[10:11], 0
	v_mov_b32_e32 v1, v144

; __device__ __forceinline__ int tid_now(int wave_s, int z) { return wave_s * 64 + (int)__builtin_amdgcn_mbcnt_hi(~0u, __builtin_amdgcn_mbcnt_lo(~0u, (unsigned)z)); }
; __global__ void __launch_bounds__(512, 2) mk_forward(Params P0, int ph_lo, int ph_hi) {
;     ...
;     for (int it_ = 2 * ph_lo; it_ < 2 * ph_hi; ++it_) {
;         const int ph = it_ >> 1;
;         if (it_ & 1) {
;             if (PROBE_MASK == 0 || ph == 0) continue;
;             const int r_ = (ph - 1) % PH_PER_PASS;
;             if (r_ == PH_PER_PASS - 1 || !((PROBE_MASK >> (r_ % PH_PER_LAYER)) & 1)) continue;
;         }
;         if (it_ > 2 * ph_lo) { if (it_ == 2 * ph_lo + 2) cg::this_grid().sync(); else xcd_barrier(xb); }
;         int z = 0; asm volatile("" : "+s"(z));
;         Ctx C; C.tid = tid_now(wave_s, z); C.bid = (int)blockIdx.x + z; C.nblk = (int)gridDim.x + z; C.wave_s = wave_s;
;         ptrtab_t tab = (ptrtab_t)__builtin_amdgcn_kernarg_segment_ptr();
;         asm volatile("" : "+s"(tab));
;         const PV P{tab, (float*)tab[29], (unsigned char*)tab[30]};
;         if (ph == 0) { prep_phase(C, P, smem); continue; }
.Lpost_getpc2:
	s_add_u32 s98, s98, (.LBB0_7-.Lpost_getpc2)&4294967295
	s_addc_u32 s99, s99, (.LBB0_7-.Lpost_getpc2)>>32
	s_setpc_b64 s[98:99]
.LBB0_2131:
	s_endpgm
